# G3 epilogue: all 16 gate loads + 4 norm-weight loads issued up front into free VGPRs (was 32 just-in-time loads with a wait each), vmcnt waits re-derived; on top of conv DPP wave_sum
# baseline (speedup 1.0000x reference)
.LBB0_1010:
	s_and_b32 s0, s3, 3
	v_add_u32_e32 v3, s31, v2
	v_mad_i64_i32 v[52:53], s[4:5], v3, s27, v[138:139]
	s_lshl_b32 s18, s0, 7
	s_mov_b32 s19, s15
	v_lshl_add_u64 v[4:5], v[52:53], 0, s[18:19]
	global_load_dwordx4 v[20:23], v[4:5], off offset:512
	global_load_dwordx4 v[24:27], v[4:5], off offset:528
	global_load_dwordx4 v[28:31], v[4:5], off offset:544
	global_load_dwordx4 v[32:35], v[4:5], off offset:560
	global_load_dwordx4 v[36:39], v[4:5], off offset:576
	global_load_dwordx4 v[40:43], v[4:5], off offset:592
	global_load_dwordx4 v[44:47], v[4:5], off offset:608
	global_load_dwordx4 v[48:51], v[4:5], off offset:624
	s_lshl_b32 s14, s0, 6
	v_lshl_add_u32 v71, v2, 1, s17
	s_cmp_gt_i32 s33, 3
	v_ashrrev_i32_e32 v70, 4, v2
	s_cselect_b32 s1, 0x107, 3
	v_ashrrev_i32_e32 v3, 31, v2
	v_add_u32_e32 v54, 0x400, v2
	v_add_u32_e32 v56, 0x440, v2
	v_add_u32_e32 v58, 0x480, v2
	v_add_u32_e32 v60, 0x4c0, v2
	v_add_u32_e32 v62, 0x500, v2
	v_add_u32_e32 v64, 0x540, v2
	v_add_u32_e32 v66, 0x580, v2
	v_add_u32_e32 v68, 0x5c0, v2
	v_add_u32_e32 v18, 0x600, v2
	v_add_u32_e32 v14, 0x640, v2
	v_add_u32_e32 v16, 0x680, v2
	v_add_u32_e32 v12, 0x6c0, v2
	v_add_u32_e32 v10, 0x700, v2
	v_add_u32_e32 v8, 0x740, v2
	v_add_u32_e32 v4, 0x780, v2
	v_add_u32_e32 v6, 0x7c0, v2
	s_sub_i32 s35, s1, s33
	s_lshl_b32 s1, s2, 3
	v_lshlrev_b32_e32 v120, 2, v70
	v_and_b32_e32 v140, 15, v2
	v_ashrrev_i32_e32 v55, 31, v54
	v_ashrrev_i32_e32 v57, 31, v56
	v_ashrrev_i32_e32 v59, 31, v58
	v_ashrrev_i32_e32 v61, 31, v60
	v_ashrrev_i32_e32 v63, 31, v62
	v_ashrrev_i32_e32 v65, 31, v64
	v_ashrrev_i32_e32 v67, 31, v66
	v_ashrrev_i32_e32 v69, 31, v68
	v_ashrrev_i32_e32 v19, 31, v18
	v_ashrrev_i32_e32 v15, 31, v14
	v_ashrrev_i32_e32 v17, 31, v16
	v_ashrrev_i32_e32 v13, 31, v12
	v_ashrrev_i32_e32 v11, 31, v10
	v_ashrrev_i32_e32 v9, 31, v8
	v_ashrrev_i32_e32 v5, 31, v4
	v_ashrrev_i32_e32 v7, 31, v6
	s_or_b32 s36, s1, s0
	s_ashr_i32 s34, s33, 31
	v_lshlrev_b64 v[94:95], 7, v[2:3]
	v_lshl_add_u64 v[110:111], v[52:53], 0, s[14:15]
	v_lshl_add_u32 v142, v2, 6, s17
	v_ashrrev_i32_e32 v121, 31, v120
	s_waitcnt vmcnt(7)
	ds_write_b16 v71, v20 offset:8192
	ds_write_b16_d16_hi v71, v20 offset:8320
	ds_write_b16 v71, v21 offset:8448
	ds_write_b16_d16_hi v71, v21 offset:8576
	ds_write_b16 v71, v22 offset:8704
	ds_write_b16_d16_hi v71, v22 offset:8832
	ds_write_b16 v71, v23 offset:8960
	ds_write_b16_d16_hi v71, v23 offset:9088
	s_waitcnt vmcnt(6)
	ds_write_b16 v71, v24 offset:9216
	ds_write_b16_d16_hi v71, v24 offset:9344
	ds_write_b16 v71, v25 offset:9472
	ds_write_b16_d16_hi v71, v25 offset:9600
	ds_write_b16 v71, v26 offset:9728
	ds_write_b16_d16_hi v71, v26 offset:9856
	ds_write_b16 v71, v27 offset:9984
	ds_write_b16_d16_hi v71, v27 offset:10112
	s_waitcnt vmcnt(5)
	ds_write_b16 v71, v28 offset:10240
	ds_write_b16_d16_hi v71, v28 offset:10368
	ds_write_b16 v71, v29 offset:10496
	ds_write_b16_d16_hi v71, v29 offset:10624
	ds_write_b16 v71, v30 offset:10752
	ds_write_b16_d16_hi v71, v30 offset:10880
	ds_write_b16 v71, v31 offset:11008
	ds_write_b16_d16_hi v71, v31 offset:11136
	s_waitcnt vmcnt(4)
	ds_write_b16 v71, v32 offset:11264
	ds_write_b16_d16_hi v71, v32 offset:11392
	ds_write_b16 v71, v33 offset:11520
	ds_write_b16_d16_hi v71, v33 offset:11648
	ds_write_b16 v71, v34 offset:11776
	ds_write_b16_d16_hi v71, v34 offset:11904
	ds_write_b16 v71, v35 offset:12032
	ds_write_b16_d16_hi v71, v35 offset:12160
	s_waitcnt vmcnt(3)
	ds_write_b16 v71, v36 offset:12288
	ds_write_b16_d16_hi v71, v36 offset:12416
	ds_write_b16 v71, v37 offset:12544
	ds_write_b16_d16_hi v71, v37 offset:12672
	ds_write_b16 v71, v38 offset:12800
	ds_write_b16_d16_hi v71, v38 offset:12928
	ds_write_b16 v71, v39 offset:13056
	ds_write_b16_d16_hi v71, v39 offset:13184
	s_waitcnt vmcnt(2)
	ds_write_b16 v71, v40 offset:13312
	ds_write_b16_d16_hi v71, v40 offset:13440
	ds_write_b16 v71, v41 offset:13568
	ds_write_b16_d16_hi v71, v41 offset:13696
	ds_write_b16 v71, v42 offset:13824
	ds_write_b16_d16_hi v71, v42 offset:13952
	ds_write_b16 v71, v43 offset:14080
	ds_write_b16_d16_hi v71, v43 offset:14208
	s_waitcnt vmcnt(1)
	ds_write_b16 v71, v44 offset:14336
	ds_write_b16_d16_hi v71, v44 offset:14464
	ds_write_b16 v71, v45 offset:14592
	ds_write_b16_d16_hi v71, v45 offset:14720
	ds_write_b16 v71, v46 offset:14848
	ds_write_b16_d16_hi v71, v46 offset:14976
	ds_write_b16 v71, v47 offset:15104
	ds_write_b16_d16_hi v71, v47 offset:15232
	s_waitcnt vmcnt(0)
	ds_write_b16 v71, v48 offset:15360
	ds_write_b16_d16_hi v71, v48 offset:15488
	ds_write_b16 v71, v49 offset:15616
	ds_write_b16_d16_hi v71, v49 offset:15744
	ds_write_b16 v71, v50 offset:15872
	ds_write_b16_d16_hi v71, v50 offset:16000
	ds_write_b16 v71, v51 offset:16128
	ds_write_b16_d16_hi v71, v51 offset:16256
	v_and_b32_e32 v47, -16, v2
	v_lshlrev_b32_e32 v20, 3, v70
	v_add_u32_e32 v134, s17, v47
	v_sub_u32_e32 v46, v134, v20
	s_mul_i32 s0, s36, 0x104
	s_mul_hi_i32 s1, s36, 0x104
	s_add_u32 s0, s0, s33
	s_addc_u32 s1, s1, s34
	s_lshl_b64 s[0:1], s[0:1], 13
	s_add_u32 s4, s21, s0
	s_addc_u32 s5, s22, s1
	v_lshlrev_b64 v[96:97], 2, v[2:3]
	v_lshl_add_u64 v[2:3], s[4:5], 0, v[96:97]
	global_load_dword v26, v[2:3], off
	global_load_dword v27, v[2:3], off offset:256
	global_load_dword v28, v[2:3], off offset:512
	global_load_dword v29, v[2:3], off offset:768
	global_load_dword v30, v[2:3], off offset:1024
	global_load_dword v31, v[2:3], off offset:1280
	global_load_dword v32, v[2:3], off offset:1536
	global_load_dword v33, v[2:3], off offset:1792
	global_load_dword v38, v[2:3], off offset:2048
	global_load_dword v39, v[2:3], off offset:2304
	global_load_dword v40, v[2:3], off offset:2560
	global_load_dword v41, v[2:3], off offset:2816
	global_load_dword v44, v[2:3], off offset:3072
	global_load_dword v45, v[2:3], off offset:3328
	global_load_dword v48, v[2:3], off offset:3584
	v_lshlrev_b64 v[98:99], 2, v[54:55]
	global_load_dword v49, v[2:3], off offset:3840
	v_lshlrev_b64 v[100:101], 2, v[56:57]
	v_lshlrev_b64 v[130:131], 2, v[4:5]
	v_lshl_add_u64 v[4:5], s[4:5], 0, v[98:99]
	v_lshlrev_b64 v[128:129], 2, v[8:9]
	v_lshl_add_u64 v[8:9], s[4:5], 0, v[100:101]
	global_load_dword v50, v[4:5], off
	global_load_dword v51, v[8:9], off
	v_lshlrev_b64 v[102:103], 2, v[58:59]
	v_lshlrev_b64 v[104:105], 2, v[60:61]
	v_lshlrev_b64 v[126:127], 2, v[10:11]
	v_lshl_add_u64 v[10:11], s[4:5], 0, v[102:103]
	v_lshlrev_b64 v[124:125], 2, v[12:13]
	v_lshl_add_u64 v[12:13], s[4:5], 0, v[104:105]
	global_load_dword v52, v[10:11], off
	global_load_dword v53, v[12:13], off
	v_lshlrev_b64 v[106:107], 2, v[62:63]
	v_lshlrev_b64 v[112:113], 2, v[66:67]
	v_lshlrev_b64 v[108:109], 2, v[64:65]
	v_lshlrev_b64 v[114:115], 2, v[68:69]
	v_lshlrev_b64 v[116:117], 2, v[18:19]
	v_lshlrev_b64 v[118:119], 2, v[14:15]
	v_lshlrev_b64 v[122:123], 2, v[16:17]
	v_lshl_add_u64 v[14:15], s[4:5], 0, v[106:107]
	v_lshl_add_u64 v[16:17], s[4:5], 0, v[112:113]
	v_lshl_add_u64 v[2:3], s[4:5], 0, v[108:109]
	v_lshl_add_u64 v[4:5], s[4:5], 0, v[114:115]
	v_lshl_add_u64 v[18:19], s[4:5], 0, v[116:117]
	v_lshl_add_u64 v[20:21], s[4:5], 0, v[118:119]
	v_lshl_add_u64 v[8:9], s[4:5], 0, v[122:123]
	v_lshl_add_u64 v[22:23], s[4:5], 0, v[124:125]
	v_lshl_add_u64 v[10:11], s[4:5], 0, v[126:127]
	v_lshl_add_u64 v[24:25], s[4:5], 0, v[128:129]
	v_lshl_add_u64 v[12:13], s[4:5], 0, v[130:131]
	global_load_dword v14, v[14:15], off
	s_nop 0
	global_load_dword v15, v[2:3], off
	s_nop 0
	global_load_dword v16, v[16:17], off
	s_nop 0
	global_load_dword v17, v[4:5], off
	global_load_dword v54, v[18:19], off
	global_load_dword v55, v[20:21], off
	global_load_dword v56, v[8:9], off
	global_load_dword v57, v[22:23], off
	global_load_dword v58, v[10:11], off
	global_load_dword v59, v[24:25], off
	global_load_dword v60, v[12:13], off
	v_lshlrev_b64 v[132:133], 2, v[6:7]
	v_lshl_add_u64 v[6:7], s[4:5], 0, v[132:133]
	s_add_u32 s0, s23, s0
	s_addc_u32 s1, s24, s1
	v_lshl_add_u64 v[42:43], s[0:1], 0, v[94:95]
	v_add_u32_e32 v161, 16, v120
	v_cmp_gt_i32_e64 s[10:11], v120, v140
	v_cmp_le_i32_e32 vcc, v161, v140
	v_add_u32_e32 v162, 17, v120
	v_cmp_le_i32_e64 s[0:1], v162, v140
	v_or_b32_e32 v164, 2, v120
	v_add_u32_e32 v163, 18, v120
	v_or_b32_e32 v166, 3, v120
	v_add_u32_e32 v165, 19, v120
	v_or_b32_e32 v168, 16, v140
	v_cmp_lt_i32_e64 s[8:9], v120, v168
	v_or_b32_e32 v160, 32, v140
	v_cmp_lt_i32_e64 s[6:7], v120, v160
	v_lshl_add_u32 v173, v160, 6, v134
	v_add_u32_e32 v167, 48, v120
	v_or_b32_e32 v169, 1, v120
	s_waitcnt vmcnt(30)
	v_bfe_u32 v2, v26, 16, 1
	v_add3_u32 v2, v26, v2, s28
	global_load_dword v26, v[6:7], off
	global_load_dwordx4 v[22:25], v[42:43], off offset:16
	global_load_dwordx4 v[34:37], v[42:43], off
	global_load_dwordx4 v[18:21], v[110:111], off
	s_waitcnt vmcnt(32)
	v_bfe_u32 v4, v28, 16, 1
	s_waitcnt vmcnt(30)
	v_bfe_u32 v8, v30, 16, 1
	v_bfe_u32 v3, v27, 16, 1
	s_waitcnt vmcnt(26)
	v_bfe_u32 v6, v38, 16, 1
	v_add3_u32 v6, v38, v6, s28
	s_waitcnt vmcnt(25)
	v_bfe_u32 v7, v39, 16, 1
	v_bfe_u32 v5, v29, 16, 1
	v_bfe_u32 v9, v31, 16, 1
	v_add3_u32 v4, v28, v4, s28
	v_add3_u32 v8, v30, v8, s28
	v_lshrrev_b32_e32 v6, 16, v6
	v_add3_u32 v7, v39, v7, s28
	v_add3_u32 v3, v27, v3, s28
	v_add3_u32 v5, v29, v5, s28
	v_add3_u32 v9, v31, v9, s28
	v_lshrrev_b32_e32 v2, 16, v2
	v_lshrrev_b32_e32 v4, 16, v4
	v_lshrrev_b32_e32 v8, 16, v8
	v_and_or_b32 v6, v7, s29, v6
	s_waitcnt vmcnt(24)
	v_bfe_u32 v7, v40, 16, 1
	v_and_or_b32 v2, v3, s29, v2
	v_and_or_b32 v3, v5, s29, v4
	v_and_or_b32 v4, v9, s29, v8
	v_add3_u32 v7, v40, v7, s28
	s_waitcnt vmcnt(23)
	v_bfe_u32 v8, v41, 16, 1
	v_lshrrev_b32_e32 v7, 16, v7
	v_add3_u32 v8, v41, v8, s28
	v_and_or_b32 v7, v8, s29, v7
	s_waitcnt vmcnt(22)
	v_bfe_u32 v8, v44, 16, 1
	v_bfe_u32 v10, v32, 16, 1
	v_add3_u32 v8, v44, v8, s28
	s_waitcnt vmcnt(21)
	v_bfe_u32 v9, v45, 16, 1
	v_add3_u32 v10, v32, v10, s28
	v_bfe_u32 v5, v33, 16, 1
	v_lshrrev_b32_e32 v8, 16, v8
	v_add3_u32 v9, v45, v9, s28
	v_lshrrev_b32_e32 v10, 16, v10
	v_add3_u32 v5, v33, v5, s28
	v_and_or_b32 v8, v9, s29, v8
	s_waitcnt vmcnt(20)
	v_bfe_u32 v9, v48, 16, 1
	v_and_or_b32 v5, v5, s29, v10
	v_add3_u32 v9, v48, v9, s28
	s_waitcnt vmcnt(19)
	v_bfe_u32 v10, v49, 16, 1
	v_lshrrev_b32_e32 v9, 16, v9
	v_add3_u32 v10, v49, v10, s28
	v_and_or_b32 v9, v10, s29, v9
	s_waitcnt vmcnt(18)
	v_bfe_u32 v10, v50, 16, 1
	v_add3_u32 v10, v50, v10, s28
	s_waitcnt vmcnt(17)
	v_bfe_u32 v11, v51, 16, 1
	v_lshrrev_b32_e32 v10, 16, v10
	v_add3_u32 v11, v51, v11, s28
	v_and_or_b32 v10, v11, s29, v10
	s_waitcnt vmcnt(16)
	v_bfe_u32 v11, v52, 16, 1
	v_add3_u32 v11, v52, v11, s28
	s_waitcnt vmcnt(15)
	v_bfe_u32 v12, v53, 16, 1
	v_lshrrev_b32_e32 v11, 16, v11
	v_add3_u32 v12, v53, v12, s28
	v_and_or_b32 v11, v12, s29, v11
	s_waitcnt vmcnt(14)
	v_bfe_u32 v12, v14, 16, 1
	v_add3_u32 v12, v14, v12, s28
	s_waitcnt vmcnt(13)
	v_bfe_u32 v13, v15, 16, 1
	v_lshrrev_b32_e32 v12, 16, v12
	v_add3_u32 v13, v15, v13, s28
	v_and_or_b32 v12, v13, s29, v12
	s_waitcnt vmcnt(12)
	v_bfe_u32 v13, v16, 16, 1
	v_add3_u32 v13, v16, v13, s28
	s_waitcnt vmcnt(11)
	v_bfe_u32 v14, v17, 16, 1
	v_lshrrev_b32_e32 v13, 16, v13
	v_add3_u32 v14, v17, v14, s28
	global_load_dwordx4 v[38:41], v[110:111], off offset:256
	v_and_or_b32 v13, v14, s29, v13
	s_waitcnt vmcnt(11)
	v_bfe_u32 v14, v54, 16, 1
	v_add3_u32 v14, v54, v14, s28
	s_waitcnt vmcnt(10)
	v_bfe_u32 v15, v55, 16, 1
	v_lshrrev_b32_e32 v14, 16, v14
	v_add3_u32 v15, v55, v15, s28
	v_and_or_b32 v14, v15, s29, v14
	s_waitcnt vmcnt(9)
	v_bfe_u32 v15, v56, 16, 1
	v_add3_u32 v15, v56, v15, s28
	s_waitcnt vmcnt(8)
	v_bfe_u32 v16, v57, 16, 1
	v_lshrrev_b32_e32 v15, 16, v15
	v_add3_u32 v16, v57, v16, s28
	v_and_or_b32 v15, v16, s29, v15
	s_waitcnt vmcnt(7)
	v_bfe_u32 v16, v58, 16, 1
	v_add3_u32 v16, v58, v16, s28
	s_waitcnt vmcnt(6)
	v_bfe_u32 v17, v59, 16, 1
	v_lshrrev_b32_e32 v16, 16, v16
	v_add3_u32 v17, v59, v17, s28
	v_and_or_b32 v16, v17, s29, v16
	s_waitcnt vmcnt(5)
	v_bfe_u32 v17, v60, 16, 1
	v_add3_u32 v17, v60, v17, s28
	s_waitcnt vmcnt(4)
	v_bfe_u32 v27, v26, 16, 1
	v_lshrrev_b32_e32 v17, 16, v17
	v_add3_u32 v26, v26, v27, s28
	v_and_or_b32 v17, v26, s29, v17
	global_load_dwordx4 v[26:29], v[42:43], off offset:48
	global_load_dwordx4 v[30:33], v[42:43], off offset:32
	s_waitcnt vmcnt(5)
	v_mul_f32_e32 v23, 0x3fb8aa3b, v23
	s_waitcnt vmcnt(4)
	v_mul_f32_e32 v34, 0x3fb8aa3b, v34
	v_exp_f32_e32 v52, v23
	v_mul_f32_e32 v23, 0x3fb8aa3b, v36
	v_exp_f32_e32 v44, v34
	v_mul_f32_e32 v34, 0x3fb8aa3b, v35
	v_exp_f32_e32 v45, v23
	v_mul_f32_e32 v23, 0x3fb8aa3b, v24
	v_mul_f32_e32 v24, 0x3fb8aa3b, v37
	v_exp_f32_e32 v48, v34
	v_exp_f32_e32 v49, v24
	global_load_dwordx4 v[34:37], v[110:111], off offset:16
	s_waitcnt vmcnt(4)
	v_lshlrev_b32_e32 v51, 16, v19
	v_lshlrev_b32_e32 v50, 16, v18
	v_and_b32_e32 v19, 0xffff0000, v19
	v_and_b32_e32 v18, 0xffff0000, v18
	v_pk_mul_f32 v[50:51], v[50:51], s[16:17] op_sel_hi:[1,0]
	v_pk_mul_f32 v[18:19], v[18:19], s[16:17] op_sel_hi:[1,0]
	v_rcp_f32_e32 v54, v48
	v_pk_mul_f32 v[56:57], v[50:51], v[44:45]
	v_pk_mul_f32 v[18:19], v[18:19], v[48:49]
	v_rcp_f32_e32 v55, v49
	global_load_dwordx4 v[48:51], v[110:111], off offset:272
	v_mul_f32_e32 v22, 0x3fb8aa3b, v22
	v_mul_f32_e32 v24, 0x3fb8aa3b, v25
	v_exp_f32_e32 v22, v22
	v_exp_f32_e32 v23, v23
	v_exp_f32_e32 v53, v24
	v_rcp_f32_e32 v24, v44
	v_rcp_f32_e32 v25, v45
	v_lshlrev_b32_e32 v59, 16, v21
	v_lshlrev_b32_e32 v58, 16, v20
	v_and_b32_e32 v21, 0xffff0000, v21
	v_and_b32_e32 v20, 0xffff0000, v20
	v_pk_mul_f32 v[58:59], v[58:59], s[16:17] op_sel_hi:[1,0]
	v_pk_mul_f32 v[20:21], v[20:21], s[16:17] op_sel_hi:[1,0]
	v_pk_mul_f32 v[58:59], v[58:59], v[22:23]
	v_pk_mul_f32 v[20:21], v[20:21], v[52:53]
	s_waitcnt vmcnt(4)
	v_lshlrev_b32_e32 v45, 16, v39
	v_lshlrev_b32_e32 v44, 16, v38
	v_pk_mul_f32 v[24:25], v[24:25], v[44:45]
	v_rcp_f32_e32 v44, v22
	v_rcp_f32_e32 v45, v23
	v_and_b32_e32 v39, 0xffff0000, v39
	v_and_b32_e32 v38, 0xffff0000, v38
	v_pk_mul_f32 v[38:39], v[54:55], v[38:39]
	v_rcp_f32_e32 v54, v52
	v_rcp_f32_e32 v55, v53
	v_lshlrev_b32_e32 v23, 16, v41
	v_lshlrev_b32_e32 v22, 16, v40
	v_bfe_u32 v52, v19, 16, 1
	v_pk_mul_f32 v[22:23], v[44:45], v[22:23]
	v_bfe_u32 v44, v21, 16, 1
	v_add3_u32 v19, v19, v52, s28
	v_bfe_u32 v52, v58, 16, 1
	v_bfe_u32 v45, v20, 16, 1
	v_bfe_u32 v53, v18, 16, 1
	v_add3_u32 v21, v21, v44, s28
	v_bfe_u32 v44, v56, 16, 1
	v_add3_u32 v52, v58, v52, s28
	v_and_b32_e32 v41, 0xffff0000, v41
	v_and_b32_e32 v40, 0xffff0000, v40
	v_add3_u32 v18, v18, v53, s28
	v_add3_u32 v20, v20, v45, s28
	v_bfe_u32 v45, v57, 16, 1
	v_bfe_u32 v53, v59, 16, 1
	v_add3_u32 v44, v56, v44, s28
	v_lshrrev_b32_e32 v52, 16, v52
	v_pk_mul_f32 v[40:41], v[54:55], v[40:41]
	v_add3_u32 v53, v59, v53, s28
	v_add3_u32 v45, v57, v45, s28
	v_lshrrev_b32_e32 v44, 16, v44
	v_and_or_b32 v20, v20, s29, v52
	v_bfe_u32 v52, v39, 16, 1
	v_lshrrev_b32_e32 v45, 16, v45
	v_lshrrev_b32_e32 v53, 16, v53
	v_and_or_b32 v18, v18, s29, v44
	v_bfe_u32 v44, v41, 16, 1
	v_add3_u32 v39, v39, v52, s28
	v_bfe_u32 v52, v22, 16, 1
	v_and_or_b32 v21, v21, s29, v53
	v_and_or_b32 v19, v19, s29, v45
	v_bfe_u32 v45, v40, 16, 1
	v_bfe_u32 v53, v38, 16, 1
	v_add3_u32 v41, v41, v44, s28
	v_bfe_u32 v44, v24, 16, 1
	v_add3_u32 v22, v22, v52, s28
	v_add3_u32 v38, v38, v53, s28
	v_add3_u32 v40, v40, v45, s28
	v_bfe_u32 v45, v25, 16, 1
	v_bfe_u32 v53, v23, 16, 1
	v_add3_u32 v24, v24, v44, s28
	v_lshrrev_b32_e32 v22, 16, v22
	s_waitcnt vmcnt(3)
	v_mul_f32_e32 v27, 0x3fb8aa3b, v27
	v_add3_u32 v23, v23, v53, s28
	v_add3_u32 v25, v25, v45, s28
	v_lshrrev_b32_e32 v44, 16, v24
	v_and_or_b32 v24, v40, s29, v22
	s_waitcnt vmcnt(2)
	v_mul_f32_e32 v30, 0x3fb8aa3b, v30
	v_mul_f32_e32 v31, 0x3fb8aa3b, v31
	v_exp_f32_e32 v40, v27
	v_mul_f32_e32 v27, 0x3fb8aa3b, v32
	v_lshrrev_b32_e32 v45, 16, v25
	v_lshrrev_b32_e32 v23, 16, v23
	v_and_or_b32 v22, v38, s29, v44
	v_exp_f32_e32 v30, v30
	v_exp_f32_e32 v38, v31
	v_exp_f32_e32 v31, v27
	v_mul_f32_e32 v27, 0x3fb8aa3b, v28
	v_mul_f32_e32 v28, 0x3fb8aa3b, v33
	v_and_or_b32 v25, v41, s29, v23
	v_and_or_b32 v23, v39, s29, v45
	v_exp_f32_e32 v39, v28
	v_mul_f32_e32 v26, 0x3fb8aa3b, v26
	global_load_dwordx4 v[52:55], v[42:43], off offset:80
	global_load_dwordx4 v[56:59], v[42:43], off offset:64
	v_exp_f32_e32 v26, v26
	v_exp_f32_e32 v27, v27
	v_mul_f32_e32 v28, 0x3fb8aa3b, v29
	s_waitcnt vmcnt(3)
	v_lshlrev_b32_e32 v45, 16, v35
	v_lshlrev_b32_e32 v44, 16, v34
	v_and_b32_e32 v35, 0xffff0000, v35
	v_and_b32_e32 v34, 0xffff0000, v34
	v_exp_f32_e32 v41, v28
	v_rcp_f32_e32 v28, v30
	v_pk_mul_f32 v[34:35], v[34:35], s[16:17] op_sel_hi:[1,0]
	v_rcp_f32_e32 v29, v31
	v_pk_mul_f32 v[60:61], v[34:35], v[38:39]
	v_lshlrev_b32_e32 v35, 16, v37
	v_lshlrev_b32_e32 v34, 16, v36
	v_pk_mul_f32 v[44:45], v[44:45], s[16:17] op_sel_hi:[1,0]
	v_pk_mul_f32 v[34:35], v[34:35], s[16:17] op_sel_hi:[1,0]
	v_pk_mul_f32 v[44:45], v[44:45], v[30:31]
	s_waitcnt vmcnt(2)
	v_lshlrev_b32_e32 v31, 16, v49
	v_lshlrev_b32_e32 v30, 16, v48
	v_pk_mul_f32 v[62:63], v[34:35], v[26:27]
	v_and_b32_e32 v35, 0xffff0000, v37
	v_and_b32_e32 v34, 0xffff0000, v36
	v_pk_mul_f32 v[30:31], v[28:29], v[30:31]
	v_and_b32_e32 v29, 0xffff0000, v49
	v_and_b32_e32 v28, 0xffff0000, v48
	v_pk_mul_f32 v[48:49], v[34:35], s[16:17] op_sel_hi:[1,0]
	global_load_dwordx4 v[34:37], v[110:111], off offset:32
	v_rcp_f32_e32 v32, v38
	v_rcp_f32_e32 v33, v39
	v_rcp_f32_e32 v38, v40
	v_pk_mul_f32 v[64:65], v[48:49], v[40:41]
	v_rcp_f32_e32 v39, v41
	v_pk_mul_f32 v[32:33], v[32:33], v[28:29]
	v_rcp_f32_e32 v28, v26
	v_rcp_f32_e32 v29, v27
	v_lshlrev_b32_e32 v27, 16, v51
	v_lshlrev_b32_e32 v26, 16, v50
	v_pk_mul_f32 v[40:41], v[28:29], v[26:27]
	v_and_b32_e32 v27, 0xffff0000, v51
	v_and_b32_e32 v26, 0xffff0000, v50
	global_load_dwordx4 v[48:51], v[110:111], off offset:288
	v_pk_mul_f32 v[38:39], v[38:39], v[26:27]
	v_bfe_u32 v26, v65, 16, 1
	v_bfe_u32 v27, v64, 16, 1
	v_bfe_u32 v28, v61, 16, 1
	v_bfe_u32 v29, v60, 16, 1
	v_add3_u32 v60, v60, v29, s28
	v_add3_u32 v61, v61, v28, s28
	v_add3_u32 v27, v64, v27, s28
	v_add3_u32 v26, v65, v26, s28
	v_bfe_u32 v28, v44, 16, 1
	v_bfe_u32 v29, v45, 16, 1
	v_bfe_u32 v64, v62, 16, 1
	v_bfe_u32 v65, v63, 16, 1
	v_add3_u32 v63, v63, v65, s28
	v_add3_u32 v62, v62, v64, s28
	v_add3_u32 v29, v45, v29, s28
	v_add3_u32 v28, v44, v28, s28
	v_lshrrev_b32_e32 v44, 16, v28
	v_lshrrev_b32_e32 v45, 16, v29
	v_lshrrev_b32_e32 v28, 16, v62
	v_lshrrev_b32_e32 v29, 16, v63
	v_and_or_b32 v29, v26, s29, v29
	v_and_or_b32 v28, v27, s29, v28
	v_and_or_b32 v27, v61, s29, v45
	v_and_or_b32 v26, v60, s29, v44
	v_bfe_u32 v44, v39, 16, 1
	v_bfe_u32 v45, v38, 16, 1
	v_bfe_u32 v60, v33, 16, 1
	v_bfe_u32 v61, v32, 16, 1
	v_add3_u32 v61, v32, v61, s28
	v_add3_u32 v60, v33, v60, s28
	v_add3_u32 v32, v38, v45, s28
	v_add3_u32 v33, v39, v44, s28
	v_bfe_u32 v39, v31, 16, 1
	v_bfe_u32 v44, v40, 16, 1
	v_bfe_u32 v45, v41, 16, 1
	v_bfe_u32 v38, v30, 16, 1
	v_add3_u32 v41, v41, v45, s28
	v_add3_u32 v40, v40, v44, s28
	v_add3_u32 v31, v31, v39, s28
	v_add3_u32 v30, v30, v38, s28
	v_lshrrev_b32_e32 v31, 16, v31
	v_lshrrev_b32_e32 v38, 16, v40
	v_lshrrev_b32_e32 v39, 16, v41
	s_waitcnt vmcnt(3)
	v_mul_f32_e32 v52, 0x3fb8aa3b, v52
	v_and_or_b32 v33, v33, s29, v39
	v_and_or_b32 v32, v32, s29, v38
	v_and_or_b32 v31, v60, s29, v31
	global_load_dwordx4 v[38:41], v[42:43], off offset:112
	s_nop 0
	global_load_dwordx4 v[42:45], v[42:43], off offset:96
	v_exp_f32_e32 v60, v52
	s_waitcnt vmcnt(4)
	v_mul_f32_e32 v52, 0x3fb8aa3b, v57
	v_exp_f32_e32 v62, v52
	v_mul_f32_e32 v52, 0x3fb8aa3b, v53
	v_exp_f32_e32 v64, v52
	v_mul_f32_e32 v52, 0x3fb8aa3b, v58
	v_lshrrev_b32_e32 v30, 16, v30
	v_mul_f32_e32 v56, 0x3fb8aa3b, v56
	v_exp_f32_e32 v57, v52
	v_mul_f32_e32 v52, 0x3fb8aa3b, v54
	v_and_or_b32 v30, v61, s29, v30
	v_exp_f32_e32 v56, v56
	v_exp_f32_e32 v61, v52
	v_mul_f32_e32 v52, 0x3fb8aa3b, v59
	v_exp_f32_e32 v63, v52
	v_mul_f32_e32 v52, 0x3fb8aa3b, v55
	v_exp_f32_e32 v65, v52
	global_load_dwordx4 v[52:55], v[110:111], off offset:48
	s_waitcnt vmcnt(4)
	v_lshlrev_b32_e32 v59, 16, v35
	v_lshlrev_b32_e32 v58, 16, v34
	v_pk_mul_f32 v[58:59], v[58:59], s[16:17] op_sel_hi:[1,0]
	v_rcp_f32_e32 v66, v56
	v_pk_mul_f32 v[70:71], v[58:59], v[56:57]
	v_rcp_f32_e32 v67, v57
	global_load_dwordx4 v[56:59], v[110:111], off offset:304
	v_and_b32_e32 v35, 0xffff0000, v35
	v_and_b32_e32 v34, 0xffff0000, v34
	v_rcp_f32_e32 v68, v62
	v_pk_mul_f32 v[34:35], v[34:35], s[16:17] op_sel_hi:[1,0]
	v_rcp_f32_e32 v69, v63
	v_pk_mul_f32 v[34:35], v[34:35], v[62:63]
	s_waitcnt vmcnt(4)
	v_lshlrev_b32_e32 v63, 16, v49
	v_lshlrev_b32_e32 v62, 16, v48
	v_pk_mul_f32 v[62:63], v[66:67], v[62:63]
	v_rcp_f32_e32 v66, v60
	v_lshlrev_b32_e32 v73, 16, v37
	v_lshlrev_b32_e32 v72, 16, v36
	v_and_b32_e32 v37, 0xffff0000, v37
	v_and_b32_e32 v36, 0xffff0000, v36
	v_rcp_f32_e32 v67, v61
	v_and_b32_e32 v49, 0xffff0000, v49
	v_and_b32_e32 v48, 0xffff0000, v48
	v_pk_mul_f32 v[36:37], v[36:37], s[16:17] op_sel_hi:[1,0]
	v_pk_mul_f32 v[48:49], v[68:69], v[48:49]
	v_rcp_f32_e32 v68, v64
	v_pk_mul_f32 v[72:73], v[72:73], s[16:17] op_sel_hi:[1,0]
	v_pk_mul_f32 v[36:37], v[36:37], v[64:65]
	v_rcp_f32_e32 v69, v65
	v_pk_mul_f32 v[72:73], v[72:73], v[60:61]
	v_lshlrev_b32_e32 v61, 16, v51
	v_lshlrev_b32_e32 v60, 16, v50
	v_bfe_u32 v64, v37, 16, 1
	v_pk_mul_f32 v[60:61], v[66:67], v[60:61]
	v_bfe_u32 v66, v35, 16, 1
	v_add3_u32 v37, v37, v64, s28
	v_bfe_u32 v64, v70, 16, 1
	v_and_b32_e32 v51, 0xffff0000, v51
	v_and_b32_e32 v50, 0xffff0000, v50
	v_bfe_u32 v67, v34, 16, 1
	v_add3_u32 v35, v35, v66, s28
	v_bfe_u32 v66, v72, 16, 1
	v_add3_u32 v64, v70, v64, s28
	v_pk_mul_f32 v[50:51], v[68:69], v[50:51]
	v_bfe_u32 v65, v36, 16, 1
	v_add3_u32 v34, v34, v67, s28
	v_bfe_u32 v67, v73, 16, 1
	v_add3_u32 v66, v72, v66, s28
	v_lshrrev_b32_e32 v64, 16, v64
	v_add3_u32 v36, v36, v65, s28
	v_bfe_u32 v65, v71, 16, 1
	v_add3_u32 v67, v73, v67, s28
	v_lshrrev_b32_e32 v66, 16, v66
	v_and_or_b32 v34, v34, s29, v64
	v_bfe_u32 v64, v51, 16, 1
	v_add3_u32 v65, v71, v65, s28
	v_lshrrev_b32_e32 v67, 16, v67
	v_and_or_b32 v36, v36, s29, v66
	v_bfe_u32 v66, v49, 16, 1
	v_add3_u32 v51, v51, v64, s28
	v_bfe_u32 v64, v62, 16, 1
	v_lshrrev_b32_e32 v65, 16, v65
	v_and_or_b32 v37, v37, s29, v67
	v_bfe_u32 v67, v48, 16, 1
	v_add3_u32 v49, v49, v66, s28
	v_bfe_u32 v66, v60, 16, 1
	v_add3_u32 v62, v62, v64, s28
	v_and_or_b32 v35, v35, s29, v65
	v_bfe_u32 v65, v50, 16, 1
	v_add3_u32 v48, v48, v67, s28
	v_bfe_u32 v67, v61, 16, 1
	v_add3_u32 v60, v60, v66, s28
	v_lshrrev_b32_e32 v62, 16, v62
	s_waitcnt vmcnt(3)
	v_mul_f32_e32 v39, 0x3fb8aa3b, v39
	v_add3_u32 v50, v50, v65, s28
	v_add3_u32 v61, v61, v67, s28
	v_lshrrev_b32_e32 v60, 16, v60
	v_and_or_b32 v48, v48, s29, v62
	s_waitcnt vmcnt(2)
	v_mul_f32_e32 v42, 0x3fb8aa3b, v42
	v_mul_f32_e32 v43, 0x3fb8aa3b, v43
	v_exp_f32_e32 v62, v39
	v_mul_f32_e32 v39, 0x3fb8aa3b, v44
	v_lshrrev_b32_e32 v61, 16, v61
	v_and_or_b32 v50, v50, s29, v60
	v_exp_f32_e32 v42, v42
	v_exp_f32_e32 v60, v43
	v_exp_f32_e32 v43, v39
	v_mul_f32_e32 v39, 0x3fb8aa3b, v40
	v_mul_f32_e32 v40, 0x3fb8aa3b, v45
	v_bfe_u32 v65, v63, 16, 1
	v_and_or_b32 v51, v51, s29, v61
	v_exp_f32_e32 v61, v40
	v_add3_u32 v63, v63, v65, s28
	v_lshrrev_b32_e32 v63, 16, v63
	v_mul_f32_e32 v40, 0x3fb8aa3b, v41
	v_and_or_b32 v49, v49, s29, v63
	v_mul_f32_e32 v38, 0x3fb8aa3b, v38
	v_exp_f32_e32 v63, v40
	v_rcp_f32_e32 v40, v42
	v_rcp_f32_e32 v41, v43
	v_exp_f32_e32 v38, v38
	v_exp_f32_e32 v39, v39
	v_rcp_f32_e32 v44, v60
	s_waitcnt vmcnt(1)
	v_lshlrev_b32_e32 v65, 16, v53
	v_lshlrev_b32_e32 v64, 16, v52
	v_rcp_f32_e32 v45, v61
	v_pk_mul_f32 v[64:65], v[64:65], s[16:17] op_sel_hi:[1,0]
	v_and_b32_e32 v53, 0xffff0000, v53
	v_pk_mul_f32 v[64:65], v[64:65], v[42:43]
	s_waitcnt vmcnt(0)
	v_lshlrev_b32_e32 v43, 16, v57
	v_lshlrev_b32_e32 v42, 16, v56
	v_and_b32_e32 v52, 0xffff0000, v52
	v_pk_mul_f32 v[42:43], v[40:41], v[42:43]
	v_and_b32_e32 v41, 0xffff0000, v57
	v_and_b32_e32 v40, 0xffff0000, v56
	v_pk_mul_f32 v[52:53], v[52:53], s[16:17] op_sel_hi:[1,0]
	v_pk_mul_f32 v[44:45], v[44:45], v[40:41]
	v_rcp_f32_e32 v40, v38
	v_rcp_f32_e32 v41, v39
	v_pk_mul_f32 v[52:53], v[52:53], v[60:61]
	v_rcp_f32_e32 v56, v62
	v_lshlrev_b32_e32 v61, 16, v55
	v_lshlrev_b32_e32 v60, 16, v54
	v_rcp_f32_e32 v57, v63
	v_pk_mul_f32 v[60:61], v[60:61], s[16:17] op_sel_hi:[1,0]
	v_and_b32_e32 v55, 0xffff0000, v55
	v_and_b32_e32 v54, 0xffff0000, v54
	v_pk_mul_f32 v[60:61], v[60:61], v[38:39]
	v_pk_mul_f32 v[54:55], v[54:55], s[16:17] op_sel_hi:[1,0]
	v_lshlrev_b32_e32 v39, 16, v59
	v_lshlrev_b32_e32 v38, 16, v58
	v_pk_mul_f32 v[54:55], v[54:55], v[62:63]
	v_pk_mul_f32 v[62:63], v[40:41], v[38:39]
	v_and_b32_e32 v39, 0xffff0000, v59
	v_and_b32_e32 v38, 0xffff0000, v58
	v_pk_mul_f32 v[56:57], v[56:57], v[38:39]
	v_bfe_u32 v38, v55, 16, 1
	v_bfe_u32 v39, v54, 16, 1
	v_bfe_u32 v40, v53, 16, 1
	v_bfe_u32 v41, v52, 16, 1
	v_add3_u32 v52, v52, v41, s28
	v_add3_u32 v53, v53, v40, s28
	v_add3_u32 v39, v54, v39, s28
	v_add3_u32 v38, v55, v38, s28
	v_bfe_u32 v40, v64, 16, 1
	v_bfe_u32 v41, v65, 16, 1
	v_bfe_u32 v54, v60, 16, 1
	v_bfe_u32 v55, v61, 16, 1
	v_add3_u32 v55, v61, v55, s28
	v_add3_u32 v54, v60, v54, s28
	v_add3_u32 v41, v65, v41, s28
	v_add3_u32 v40, v64, v40, s28
	v_lshrrev_b32_e32 v58, 16, v40
	v_lshrrev_b32_e32 v59, 16, v41
	v_lshrrev_b32_e32 v40, 16, v54
	v_lshrrev_b32_e32 v41, 16, v55
	v_and_or_b32 v41, v38, s29, v41
	v_and_or_b32 v40, v39, s29, v40
	v_and_or_b32 v39, v53, s29, v59
	v_and_or_b32 v38, v52, s29, v58
	v_bfe_u32 v52, v57, 16, 1
	v_bfe_u32 v53, v56, 16, 1
	v_bfe_u32 v54, v45, 16, 1
	v_bfe_u32 v55, v44, 16, 1
	v_add3_u32 v55, v44, v55, s28
	v_add3_u32 v54, v45, v54, s28
	v_add3_u32 v44, v56, v53, s28
	v_add3_u32 v45, v57, v52, s28
	v_bfe_u32 v52, v42, 16, 1
	v_bfe_u32 v53, v43, 16, 1
	v_bfe_u32 v56, v62, 16, 1
	v_bfe_u32 v57, v63, 16, 1
	v_add3_u32 v57, v63, v57, s28
	v_add3_u32 v56, v62, v56, s28
	v_add3_u32 v43, v43, v53, s28
	v_add3_u32 v42, v42, v52, s28
	s_waitcnt lgkmcnt(0)
	ds_write_b128 v142, v[18:21]
	ds_write_b128 v142, v[26:29] offset:16
	ds_write_b128 v142, v[34:37] offset:32
	ds_write_b128 v142, v[38:41] offset:48
	ds_write_b128 v142, v[2:5] offset:4096
	ds_write_b128 v142, v[6:9] offset:4112
	ds_write_b128 v142, v[10:13] offset:4128
	ds_write_b128 v142, v[14:17] offset:4144
	v_lshlrev_b32_e32 v26, 6, v140
	v_lshrrev_b32_e32 v42, 16, v42
	v_lshrrev_b32_e32 v43, 16, v43
	v_lshrrev_b32_e32 v52, 16, v56
	v_lshrrev_b32_e32 v53, 16, v57
	v_add_u32_e32 v172, v134, v26
	v_and_or_b32 v45, v45, s29, v53
	v_and_or_b32 v44, v44, s29, v52
	v_and_or_b32 v43, v54, s29, v43
	v_and_or_b32 v42, v55, s29, v42
	s_waitcnt lgkmcnt(0)
	ds_read_b128 v[14:17], v172
	ds_read_b128 v[10:13], v172 offset:1024
	ds_read_b128 v[6:9], v172 offset:2048
	ds_read_b128 v[2:5], v172 offset:3072
	s_waitcnt lgkmcnt(0)
	ds_write_b128 v142, v[22:25]
	ds_write_b128 v142, v[30:33] offset:16
	ds_write_b128 v142, v[48:51] offset:32
	ds_write_b128 v142, v[42:45] offset:48
	s_waitcnt lgkmcnt(0)
	ds_read_b128 v[18:21], v172 offset:4096
	ds_read_b128 v[34:37], v172
	s_waitcnt lgkmcnt(1)
	v_mfma_f32_16x16x32_bf16 v[38:41], v[18:21], v[14:17], 0
	v_add3_u32 v143, s17, v26, v47
	v_mfma_f32_16x16x32_bf16 v[42:45], v[18:21], v[10:13], 0
	v_mfma_f32_16x16x32_bf16 v[82:85], v[18:21], v[6:9], 0
	v_mfma_f32_16x16x32_bf16 v[86:89], v[18:21], v[2:5], 0
	ds_read_b128 v[18:21], v172 offset:5120
	ds_read_b128 v[22:25], v172 offset:6144
	ds_read_b128 v[90:93], v143 offset:1024
	s_waitcnt lgkmcnt(2)
	v_mfma_f32_16x16x32_bf16 v[50:53], v[18:21], v[14:17], 0
	v_mfma_f32_16x16x32_bf16 v[54:57], v[18:21], v[10:13], 0
	v_mfma_f32_16x16x32_bf16 v[58:61], v[18:21], v[6:9], 0
	v_mfma_f32_16x16x32_bf16 v[62:65], v[18:21], v[2:5], 0
	ds_read_b128 v[18:21], v172 offset:7168
	v_mfma_f32_16x16x32_bf16 v[152:155], v[34:37], v[14:17], 0
	s_waitcnt lgkmcnt(1)
	v_mfma_f32_16x16x32_bf16 v[156:159], v[90:93], v[14:17], 0
	v_mfma_f32_16x16x32_bf16 v[174:177], v[34:37], v[10:13], 0
	s_nop 4
	v_cndmask_b32_e64 v47, v152, 0, s[10:11]
	s_nop 0
	v_cndmask_b32_e32 v48, 0, v156, vcc
	v_cmp_lt_i32_e32 vcc, v120, v140
	v_cndmask_b32_e64 v135, 0, v157, s[0:1]
	v_cmp_le_i32_e64 s[0:1], v164, v140
	v_cndmask_b32_e32 v49, 0, v153, vcc
	v_bfe_u32 v152, v47, 16, 1
	v_cndmask_b32_e64 v136, 0, v154, s[0:1]
	v_cmp_le_i32_e64 s[0:1], v163, v140
	v_add3_u32 v47, v47, v152, s28
	v_bfe_u32 v152, v49, 16, 1
	v_cndmask_b32_e64 v137, 0, v158, s[0:1]
	v_cmp_le_i32_e64 s[0:1], v166, v140
	v_lshrrev_b32_e32 v47, 16, v47
	v_add3_u32 v49, v49, v152, s28
	v_cndmask_b32_e64 v144, 0, v155, s[0:1]
	v_and_or_b32 v154, v49, s29, v47
	v_bfe_u32 v47, v136, 16, 1
	v_add3_u32 v47, v136, v47, s28
	v_bfe_u32 v49, v144, 16, 1
	v_lshrrev_b32_e32 v47, 16, v47
	v_add3_u32 v49, v144, v49, s28
	v_and_or_b32 v155, v49, s29, v47
	v_bfe_u32 v47, v48, 16, 1
	v_add3_u32 v47, v48, v47, s28
	v_bfe_u32 v48, v135, 16, 1
	v_cmp_le_i32_e64 s[0:1], v165, v140
	v_lshrrev_b32_e32 v47, 16, v47
	v_add3_u32 v48, v135, v48, s28
	v_cndmask_b32_e64 v145, 0, v159, s[0:1]
	v_and_or_b32 v156, v48, s29, v47
	v_bfe_u32 v47, v137, 16, 1
	v_mfma_f32_16x16x32_bf16 v[178:181], v[90:93], v[10:13], 0
	v_add3_u32 v47, v137, v47, s28
	v_bfe_u32 v48, v145, 16, 1
	v_lshrrev_b32_e32 v47, 16, v47
	v_add3_u32 v48, v145, v48, s28
	v_cmp_le_i32_e64 s[0:1], v120, v168
	v_and_or_b32 v157, v48, s29, v47
	v_cndmask_b32_e64 v49, 0, v175, s[8:9]
	v_cndmask_b32_e64 v47, 0, v174, s[0:1]
	v_cmp_le_i32_e64 s[0:1], v162, v168
	v_bfe_u32 v152, v47, 16, 1
	v_add3_u32 v47, v47, v152, s28
	v_cndmask_b32_e64 v135, 0, v179, s[0:1]
	v_cmp_le_i32_e64 s[0:1], v164, v168
	v_bfe_u32 v152, v49, 16, 1
	v_lshrrev_b32_e32 v47, 16, v47
	v_cndmask_b32_e64 v136, 0, v176, s[0:1]
	v_cmp_le_i32_e64 s[0:1], v163, v168
	v_add3_u32 v49, v49, v152, s28
	v_and_or_b32 v174, v49, s29, v47
	v_cndmask_b32_e64 v137, 0, v180, s[0:1]
	v_cmp_le_i32_e64 s[0:1], v166, v168
	v_bfe_u32 v47, v136, 16, 1
	v_add3_u32 v47, v136, v47, s28
	v_cndmask_b32_e64 v144, 0, v177, s[0:1]
	v_bfe_u32 v49, v144, 16, 1
	v_cndmask_b32_e64 v48, v178, 0, s[10:11]
	v_lshrrev_b32_e32 v47, 16, v47
	v_add3_u32 v49, v144, v49, s28
	v_and_or_b32 v175, v49, s29, v47
	v_bfe_u32 v47, v48, 16, 1
	v_cmp_le_i32_e64 s[0:1], v165, v168
	v_add3_u32 v47, v48, v47, s28
	v_bfe_u32 v48, v135, 16, 1
	v_cndmask_b32_e64 v145, 0, v181, s[0:1]
	v_lshrrev_b32_e32 v47, 16, v47
	v_add3_u32 v48, v135, v48, s28
	v_mfma_f32_16x16x32_bf16 v[178:181], v[34:37], v[6:9], 0
	v_and_or_b32 v176, v48, s29, v47
	v_bfe_u32 v47, v137, 16, 1
	v_add3_u32 v47, v137, v47, s28
	v_mfma_f32_16x16x32_bf16 v[182:185], v[90:93], v[6:9], 0
	v_bfe_u32 v48, v145, 16, 1
	v_lshrrev_b32_e32 v47, 16, v47
	v_add3_u32 v48, v145, v48, s28
	v_cmp_le_i32_e64 s[0:1], v120, v160
	v_and_or_b32 v177, v48, s29, v47
	v_cndmask_b32_e64 v49, 0, v179, s[6:7]
	v_cndmask_b32_e64 v47, 0, v178, s[0:1]
	v_cmp_le_i32_e64 s[0:1], v161, v160
	v_bfe_u32 v152, v47, 16, 1
	v_add3_u32 v47, v47, v152, s28
	v_cndmask_b32_e64 v48, 0, v182, s[0:1]
	v_cmp_le_i32_e64 s[0:1], v162, v160
	v_bfe_u32 v152, v49, 16, 1
	v_lshrrev_b32_e32 v47, 16, v47
	v_cndmask_b32_e64 v135, 0, v183, s[0:1]
	v_cmp_le_i32_e64 s[0:1], v164, v160
	v_add3_u32 v49, v49, v152, s28
	v_and_or_b32 v178, v49, s29, v47
	v_cndmask_b32_e64 v136, 0, v180, s[0:1]
	v_cmp_le_i32_e64 s[0:1], v163, v160
	v_bfe_u32 v47, v136, 16, 1
	v_add3_u32 v47, v136, v47, s28
	v_cndmask_b32_e64 v137, 0, v184, s[0:1]
	v_cmp_le_i32_e64 s[0:1], v166, v160
	v_lshrrev_b32_e32 v47, 16, v47
	v_mfma_f32_16x16x32_bf16 v[34:37], v[34:37], v[2:5], 0
	v_cndmask_b32_e64 v144, 0, v181, s[0:1]
	v_bfe_u32 v49, v144, 16, 1
	v_add3_u32 v49, v144, v49, s28
	v_and_or_b32 v179, v49, s29, v47
	v_bfe_u32 v47, v48, 16, 1
	v_add3_u32 v47, v48, v47, s28
	v_bfe_u32 v48, v135, 16, 1
	v_cmp_le_i32_e64 s[0:1], v165, v160
	v_lshrrev_b32_e32 v47, 16, v47
	v_add3_u32 v48, v135, v48, s28
	v_cndmask_b32_e64 v145, 0, v185, s[0:1]
	v_and_or_b32 v180, v48, s29, v47
	v_bfe_u32 v47, v137, 16, 1
	v_or_b32_e32 v152, 48, v140
	v_add3_u32 v47, v137, v47, s28
	v_bfe_u32 v48, v145, 16, 1
	v_mfma_f32_16x16x32_bf16 v[90:93], v[90:93], v[2:5], 0
	v_cmp_le_i32_e64 s[0:1], v120, v152
	v_lshrrev_b32_e32 v47, 16, v47
	v_add3_u32 v48, v145, v48, s28
	v_cndmask_b32_e64 v34, 0, v34, s[0:1]
	v_cmp_lt_i32_e64 s[4:5], v120, v152
	v_and_or_b32 v181, v48, s29, v47
	v_bfe_u32 v47, v34, 16, 1
	v_cndmask_b32_e64 v35, 0, v35, s[4:5]
	v_lshl_add_u32 v135, v140, 7, v46
	v_cmp_le_i32_e64 s[0:1], v161, v152
	v_add3_u32 v34, v34, v47, s28
	v_bfe_u32 v47, v35, 16, 1
	v_add_u32_e32 v144, 0x2000, v135
	v_cndmask_b32_e64 v90, 0, v90, s[0:1]
	v_cmp_le_i32_e64 s[0:1], v162, v152
	v_add3_u32 v35, v35, v47, s28
	ds_read2_b64 v[46:49], v144 offset1:4
	v_cndmask_b32_e64 v91, 0, v91, s[0:1]
	v_cmp_le_i32_e64 s[0:1], v164, v152
	v_lshrrev_b32_e32 v34, 16, v34
	v_and_or_b32 v182, v35, s29, v34
	v_cndmask_b32_e64 v36, 0, v36, s[0:1]
	v_cmp_le_i32_e64 s[0:1], v163, v152
	v_bfe_u32 v34, v36, 16, 1
	v_add3_u32 v34, v36, v34, s28
	v_cndmask_b32_e64 v92, 0, v92, s[0:1]
	v_cmp_le_i32_e64 s[0:1], v166, v152
	v_lshrrev_b32_e32 v34, 16, v34
	v_add_u32_e32 v145, 0x2800, v135
	v_cndmask_b32_e64 v37, 0, v37, s[0:1]
	v_bfe_u32 v35, v37, 16, 1
	v_add3_u32 v35, v37, v35, s28
	v_and_or_b32 v183, v35, s29, v34
	v_bfe_u32 v34, v90, 16, 1
	v_add3_u32 v34, v90, v34, s28
	v_lshrrev_b32_e32 v90, 16, v34
	s_waitcnt lgkmcnt(0)
	v_mfma_f32_16x16x32_bf16 v[34:37], v[46:49], v[154:157], v[38:41]
	v_cmp_le_i32_e64 s[0:1], v165, v152
	v_add_u32_e32 v171, 0x3000, v135
	v_add_u32_e32 v170, 0x3800, v135
	v_bfe_u32 v38, v91, 16, 1
	v_add3_u32 v38, v91, v38, s28
	v_and_or_b32 v184, v38, s29, v90
	v_mfma_f32_16x16x32_bf16 v[38:41], v[46:49], v[174:177], v[42:45]
	v_cndmask_b32_e64 v93, 0, v93, s[0:1]
	ds_read2_b64 v[186:189], v170 offset1:4
	v_add_u32_e32 v153, 32, v120
	v_bfe_u32 v42, v92, 16, 1
	v_add3_u32 v42, v92, v42, s28
	v_lshrrev_b32_e32 v90, 16, v42
	v_mfma_f32_16x16x32_bf16 v[42:45], v[46:49], v[178:181], v[82:85]
	v_cmp_le_i32_e64 s[0:1], v153, v140
	v_add_u32_e32 v159, 35, v120
	v_add_u32_e32 v158, 51, v120
	v_bfe_u32 v82, v93, 16, 1
	v_add3_u32 v82, v93, v82, s28
	v_and_or_b32 v185, v82, s29, v90
	ds_read2_b64 v[82:85], v145 offset1:4
	s_waitcnt lgkmcnt(0)
	v_mfma_f32_16x16x32_bf16 v[50:53], v[82:85], v[154:157], v[50:53]
	v_mfma_f32_16x16x32_bf16 v[54:57], v[82:85], v[174:177], v[54:57]
	v_mfma_f32_16x16x32_bf16 v[58:61], v[82:85], v[178:181], v[58:61]
	v_mfma_f32_16x16x32_bf16 v[62:65], v[82:85], v[182:185], v[62:65]
	ds_read2_b64 v[82:85], v171 offset1:4
	v_mfma_f32_16x16x32_bf16 v[66:69], v[22:25], v[14:17], 0
	v_mfma_f32_16x16x32_bf16 v[70:73], v[22:25], v[10:13], 0
	v_mfma_f32_16x16x32_bf16 v[74:77], v[22:25], v[6:9], 0
	v_mfma_f32_16x16x32_bf16 v[78:81], v[22:25], v[2:5], 0
	v_mfma_f32_16x16x32_bf16 v[22:25], v[18:21], v[14:17], 0
	v_mfma_f32_16x16x32_bf16 v[26:29], v[18:21], v[10:13], 0
	s_waitcnt lgkmcnt(0)
	v_mfma_f32_16x16x32_bf16 v[66:69], v[82:85], v[154:157], v[66:69]
	v_mfma_f32_16x16x32_bf16 v[70:73], v[82:85], v[174:177], v[70:73]
	v_mfma_f32_16x16x32_bf16 v[74:77], v[82:85], v[178:181], v[74:77]
	v_mfma_f32_16x16x32_bf16 v[78:81], v[82:85], v[182:185], v[78:81]
	v_mfma_f32_16x16x32_bf16 v[82:85], v[186:189], v[154:157], v[22:25]
	v_add_u32_e32 v155, 33, v120
	v_add_u32_e32 v154, 49, v120
	v_add_u32_e32 v157, 34, v120
	ds_read_b128 v[22:25], v173
	v_mfma_f32_16x16x32_bf16 v[46:49], v[46:49], v[182:185], v[86:89]
	v_add_u32_e32 v156, 50, v120
	v_mfma_f32_16x16x32_bf16 v[86:89], v[186:189], v[174:177], v[26:29]
	s_nop 2
	ds_read_b128 v[26:29], v143 offset:3072
	v_mfma_f32_16x16x32_bf16 v[30:33], v[18:21], v[6:9], 0
	v_mfma_f32_16x16x32_bf16 v[90:93], v[186:189], v[178:181], v[30:33]
	s_waitcnt lgkmcnt(1)
	v_mfma_f32_16x16x32_bf16 v[30:33], v[22:25], v[14:17], 0
	s_waitcnt lgkmcnt(0)
	v_mfma_f32_16x16x32_bf16 v[14:17], v[26:29], v[14:17], 0
	v_mfma_f32_16x16x32_bf16 v[18:21], v[18:21], v[2:5], 0
	s_nop 4
	v_cndmask_b32_e64 v30, 0, v30, s[0:1]
	v_cmp_le_i32_e64 s[0:1], v167, v140
	v_mfma_f32_16x16x32_bf16 v[18:21], v[186:189], v[182:185], v[18:21]
	s_nop 0
	v_cndmask_b32_e64 v134, 0, v14, s[0:1]
	v_cmp_le_i32_e64 s[0:1], v155, v140
	s_nop 1
	v_cndmask_b32_e64 v14, 0, v31, s[0:1]
	v_cmp_le_i32_e64 s[0:1], v154, v140
	s_nop 1
	v_cndmask_b32_e64 v31, 0, v15, s[0:1]
	v_cmp_le_i32_e64 s[0:1], v157, v140
	s_nop 1
	v_cndmask_b32_e64 v15, 0, v32, s[0:1]
	v_cmp_le_i32_e64 s[0:1], v156, v140
	s_nop 1
	v_cndmask_b32_e64 v32, 0, v16, s[0:1]
	v_cmp_le_i32_e64 s[0:1], v159, v140
	s_nop 1
	v_cndmask_b32_e64 v16, 0, v33, s[0:1]
	v_bfe_u32 v33, v30, 16, 1
	v_add3_u32 v30, v30, v33, s28
	v_bfe_u32 v33, v14, 16, 1
	v_lshrrev_b32_e32 v30, 16, v30
	v_add3_u32 v14, v14, v33, s28
	v_and_or_b32 v14, v14, s29, v30
	v_bfe_u32 v30, v15, 16, 1
	v_add3_u32 v15, v15, v30, s28
	v_bfe_u32 v30, v16, 16, 1
	v_lshrrev_b32_e32 v15, 16, v15
	v_add3_u32 v16, v16, v30, s28
	v_and_or_b32 v15, v16, s29, v15
	v_bfe_u32 v16, v134, 16, 1
	v_add3_u32 v16, v134, v16, s28
	v_bfe_u32 v30, v31, 16, 1
	v_lshrrev_b32_e32 v16, 16, v16
	v_add3_u32 v30, v31, v30, s28
	v_and_or_b32 v16, v30, s29, v16
	v_bfe_u32 v30, v32, 16, 1
	v_add3_u32 v30, v32, v30, s28
	v_lshrrev_b32_e32 v134, 16, v30
	v_mfma_f32_16x16x32_bf16 v[30:33], v[22:25], v[10:13], 0
	v_cmp_le_i32_e64 s[0:1], v158, v140
	v_mfma_f32_16x16x32_bf16 v[10:13], v[26:29], v[10:13], 0
	s_nop 0
	v_cndmask_b32_e64 v17, 0, v17, s[0:1]
	v_cmp_le_i32_e64 s[0:1], v153, v168
	v_bfe_u32 v135, v17, 16, 1
	v_add3_u32 v17, v17, v135, s28
	s_nop 0
	v_cndmask_b32_e64 v30, 0, v30, s[0:1]
	v_cmp_le_i32_e64 s[0:1], v167, v168
	v_and_or_b32 v17, v17, s29, v134
	s_nop 0
	v_cndmask_b32_e64 v10, 0, v10, s[0:1]
	v_cmp_le_i32_e64 s[0:1], v155, v168
	s_nop 1
	v_cndmask_b32_e64 v31, 0, v31, s[0:1]
	v_cmp_le_i32_e64 s[0:1], v154, v168
	s_nop 1
	v_cndmask_b32_e64 v11, 0, v11, s[0:1]
	v_cmp_le_i32_e64 s[0:1], v157, v168
	s_nop 1
	v_cndmask_b32_e64 v32, 0, v32, s[0:1]
	v_cmp_le_i32_e64 s[0:1], v156, v168
	s_nop 1
	v_cndmask_b32_e64 v12, 0, v12, s[0:1]
	v_cmp_le_i32_e64 s[0:1], v159, v168
	s_nop 1
	v_cndmask_b32_e64 v33, 0, v33, s[0:1]
	v_cmp_le_i32_e64 s[0:1], v158, v168
	s_nop 1
	v_cndmask_b32_e64 v137, 0, v13, s[0:1]
	v_bfe_u32 v13, v30, 16, 1
	v_add3_u32 v13, v30, v13, s28
	v_bfe_u32 v30, v31, 16, 1
	v_lshrrev_b32_e32 v13, 16, v13
	v_add3_u32 v30, v31, v30, s28
	v_and_or_b32 v134, v30, s29, v13
	v_bfe_u32 v13, v32, 16, 1
	v_add3_u32 v13, v32, v13, s28
	v_bfe_u32 v30, v33, 16, 1
	v_lshrrev_b32_e32 v13, 16, v13
	v_add3_u32 v30, v33, v30, s28
	v_and_or_b32 v135, v30, s29, v13
	v_bfe_u32 v13, v10, 16, 1
	v_add3_u32 v10, v10, v13, s28
	v_bfe_u32 v13, v11, 16, 1
	v_lshrrev_b32_e32 v10, 16, v10
	v_add3_u32 v11, v11, v13, s28
	v_and_or_b32 v136, v11, s29, v10
	v_bfe_u32 v10, v12, 16, 1
	v_add3_u32 v10, v12, v10, s28
	v_lshrrev_b32_e32 v30, 16, v10
	v_mfma_f32_16x16x32_bf16 v[10:13], v[22:25], v[6:9], 0
	v_cmp_le_i32_e64 s[0:1], v167, v160
	v_bfe_u32 v31, v137, 16, 1
	v_add3_u32 v31, v137, v31, s28
	v_mfma_f32_16x16x32_bf16 v[6:9], v[26:29], v[6:9], 0
	v_and_or_b32 v137, v31, s29, v30
	s_nop 2
	v_cndmask_b32_e64 v10, v10, 0, s[10:11]
	s_nop 2
	v_cndmask_b32_e64 v6, 0, v6, s[0:1]
	v_cmp_le_i32_e64 s[0:1], v155, v160
	s_nop 1
	v_cndmask_b32_e64 v11, 0, v11, s[0:1]
	v_cmp_le_i32_e64 s[0:1], v154, v160
	s_nop 1
	v_cndmask_b32_e64 v7, 0, v7, s[0:1]
	v_cmp_le_i32_e64 s[0:1], v157, v160
	s_nop 1
	v_cndmask_b32_e64 v12, 0, v12, s[0:1]
	v_cmp_le_i32_e64 s[0:1], v156, v160
	s_nop 1
	v_cndmask_b32_e64 v8, 0, v8, s[0:1]
	v_cmp_le_i32_e64 s[0:1], v159, v160
	s_nop 1
	v_cndmask_b32_e64 v13, 0, v13, s[0:1]
	v_cmp_le_i32_e64 s[0:1], v158, v160
	s_nop 1
	v_cndmask_b32_e64 v30, 0, v9, s[0:1]
	v_bfe_u32 v9, v10, 16, 1
	v_add3_u32 v9, v10, v9, s28
	v_bfe_u32 v10, v11, 16, 1
	v_lshrrev_b32_e32 v9, 16, v9
	v_add3_u32 v10, v11, v10, s28
	v_and_or_b32 v174, v10, s29, v9
	v_bfe_u32 v9, v12, 16, 1
	v_add3_u32 v9, v12, v9, s28
	v_bfe_u32 v10, v13, 16, 1
	v_lshrrev_b32_e32 v9, 16, v9
	v_add3_u32 v10, v13, v10, s28
	v_and_or_b32 v175, v10, s29, v9
	v_bfe_u32 v9, v6, 16, 1
	v_add3_u32 v6, v6, v9, s28
	v_bfe_u32 v9, v7, 16, 1
	v_lshrrev_b32_e32 v6, 16, v6
	v_add3_u32 v7, v7, v9, s28
	v_and_or_b32 v176, v7, s29, v6
	v_bfe_u32 v6, v8, 16, 1
	v_add3_u32 v6, v8, v6, s28
	v_lshrrev_b32_e32 v10, 16, v6
	v_mfma_f32_16x16x32_bf16 v[6:9], v[22:25], v[2:5], 0
	v_bfe_u32 v11, v30, 16, 1
	v_cmp_le_i32_e64 s[0:1], v153, v152
	v_add3_u32 v11, v30, v11, s28
	v_mfma_f32_16x16x32_bf16 v[2:5], v[26:29], v[2:5], 0
	v_and_or_b32 v177, v11, s29, v10
	s_nop 2
	v_cndmask_b32_e64 v6, 0, v6, s[0:1]
	v_cmp_le_i32_e64 s[0:1], v155, v152
	s_nop 1
	v_cndmask_b32_e64 v10, v2, 0, s[10:11]
	v_cndmask_b32_e64 v2, 0, v7, s[0:1]
	v_cmp_le_i32_e64 s[0:1], v154, v152
	v_bfe_u32 v7, v6, 16, 1
	v_add3_u32 v6, v6, v7, s28
	v_cndmask_b32_e64 v11, 0, v3, s[0:1]
	v_cmp_le_i32_e64 s[0:1], v157, v152
	v_bfe_u32 v7, v2, 16, 1
	v_lshrrev_b32_e32 v6, 16, v6
	v_cndmask_b32_e64 v3, 0, v8, s[0:1]
	v_cmp_le_i32_e64 s[0:1], v156, v152
	v_add3_u32 v2, v2, v7, s28
	v_bfe_u32 v13, v3, 16, 1
	v_cndmask_b32_e64 v12, 0, v4, s[0:1]
	v_cmp_le_i32_e64 s[0:1], v159, v152
	v_and_or_b32 v2, v2, s29, v6
	v_add3_u32 v3, v3, v13, s28
	v_cndmask_b32_e64 v4, 0, v9, s[0:1]
	ds_read2_b64 v[6:9], v144 offset0:8 offset1:12
	v_bfe_u32 v13, v4, 16, 1
	v_lshrrev_b32_e32 v3, 16, v3
	v_add3_u32 v4, v4, v13, s28
	v_and_or_b32 v3, v4, s29, v3
	v_bfe_u32 v4, v10, 16, 1
	v_add3_u32 v4, v10, v4, s28
	v_bfe_u32 v10, v11, 16, 1
	v_cmp_le_i32_e64 s[0:1], v158, v152
	v_lshrrev_b32_e32 v4, 16, v4
	v_add3_u32 v10, v11, v10, s28
	v_cndmask_b32_e64 v5, 0, v5, s[0:1]
	v_and_or_b32 v4, v10, s29, v4
	v_bfe_u32 v10, v12, 16, 1
	v_add3_u32 v10, v12, v10, s28
	v_bfe_u32 v11, v5, 16, 1
	v_lshrrev_b32_e32 v10, 16, v10
	v_add3_u32 v5, v5, v11, s28
	v_and_or_b32 v5, v5, s29, v10
	s_waitcnt lgkmcnt(0)
	v_mfma_f32_16x16x32_bf16 v[22:25], v[6:9], v[14:17], v[34:37]
	v_mfma_f32_16x16x32_bf16 v[26:29], v[6:9], v[134:137], v[38:41]
	v_mfma_f32_16x16x32_bf16 v[30:33], v[6:9], v[174:177], v[42:45]
	v_mfma_f32_16x16x32_bf16 v[34:37], v[6:9], v[2:5], v[46:49]
	ds_read2_b64 v[6:9], v145 offset0:8 offset1:12
	s_waitcnt lgkmcnt(0)
	v_mfma_f32_16x16x32_bf16 v[38:41], v[6:9], v[14:17], v[50:53]
	ds_read2_b64 v[46:49], v170 offset0:8 offset1:12
	v_mfma_f32_16x16x32_bf16 v[42:45], v[6:9], v[134:137], v[54:57]
	v_mfma_f32_16x16x32_bf16 v[50:53], v[6:9], v[174:177], v[58:61]
	v_mfma_f32_16x16x32_bf16 v[54:57], v[6:9], v[2:5], v[62:65]
	ds_read2_b64 v[6:9], v171 offset0:8 offset1:12
	s_waitcnt lgkmcnt(0)
	v_mfma_f32_16x16x32_bf16 v[58:61], v[6:9], v[14:17], v[66:69]
	v_mfma_f32_16x16x32_bf16 v[62:65], v[6:9], v[134:137], v[70:73]
	v_mfma_f32_16x16x32_bf16 v[10:13], v[6:9], v[174:177], v[74:77]
	v_mfma_f32_16x16x32_bf16 v[6:9], v[6:9], v[2:5], v[78:81]
	v_mfma_f32_16x16x32_bf16 v[66:69], v[46:49], v[14:17], v[82:85]
	v_mfma_f32_16x16x32_bf16 v[70:73], v[46:49], v[134:137], v[86:89]
	v_mfma_f32_16x16x32_bf16 v[14:17], v[46:49], v[174:177], v[90:93]
	v_mfma_f32_16x16x32_bf16 v[2:5], v[46:49], v[2:5], v[18:21]
	s_or_b32 s0, s36, 4
	s_mul_i32 s10, s0, 0x104
	s_ashr_i32 s1, s35, 31
	s_mul_hi_i32 s2, s0, 0x104
	s_add_u32 s0, s10, s35
	s_addc_u32 s1, s2, s1
	s_lshl_b64 s[0:1], s[0:1], 13
	s_add_u32 s0, s21, s0
	s_addc_u32 s1, s22, s1
	v_lshl_add_u64 v[18:19], s[0:1], 0, v[96:97]
	global_load_dword v92, v[18:19], off
	global_load_dword v93, v[18:19], off offset:256
	global_load_dword v96, v[18:19], off offset:512
	global_load_dword v97, v[18:19], off offset:768
	global_load_dword v134, v[18:19], off offset:1024
	global_load_dword v135, v[18:19], off offset:1280
	global_load_dword v136, v[18:19], off offset:1536
	global_load_dword v137, v[18:19], off offset:1792
	global_load_dword v174, v[18:19], off offset:2048
	global_load_dword v175, v[18:19], off offset:2304
	global_load_dword v176, v[18:19], off offset:2560
	global_load_dword v177, v[18:19], off offset:2816
	global_load_dword v178, v[18:19], off offset:3072
	v_lshl_add_u64 v[48:49], s[0:1], 0, v[102:103]
	global_load_dword v102, v[18:19], off offset:3328
	global_load_dword v103, v[18:19], off offset:3584
	v_lshl_add_u64 v[74:75], s[0:1], 0, v[104:105]
	global_load_dword v104, v[18:19], off offset:3840
	v_lshl_add_u64 v[20:21], s[0:1], 0, v[98:99]
	v_lshl_add_u64 v[46:47], s[0:1], 0, v[100:101]
	v_lshl_add_u64 v[78:79], s[0:1], 0, v[108:109]
	global_load_dword v108, v[20:21], off
	global_load_dword v109, v[46:47], off
	v_lshl_add_u64 v[80:81], s[0:1], 0, v[112:113]
	global_load_dword v112, v[48:49], off
	v_lshl_add_u64 v[76:77], s[0:1], 0, v[106:107]
	global_load_dword v75, v[74:75], off
	v_lshl_add_u64 v[90:91], s[0:1], 0, v[132:133]
	v_lshl_add_u64 v[18:19], s[0:1], 0, v[114:115]
	v_lshl_add_u64 v[82:83], s[0:1], 0, v[116:117]
	v_lshl_add_u64 v[20:21], s[0:1], 0, v[118:119]
	v_lshl_add_u64 v[84:85], s[0:1], 0, v[122:123]
	v_lshl_add_u64 v[86:87], s[0:1], 0, v[124:125]
	v_lshl_add_u64 v[46:47], s[0:1], 0, v[126:127]
	v_lshl_add_u64 v[88:89], s[0:1], 0, v[128:129]
	v_lshl_add_u64 v[48:49], s[0:1], 0, v[130:131]
	global_load_dword v76, v[76:77], off
	s_nop 0
	global_load_dword v77, v[78:79], off
	s_nop 0
	global_load_dword v78, v[80:81], off
	global_load_dword v79, v[18:19], off
	s_nop 0
	global_load_dword v80, v[82:83], off
	global_load_dword v81, v[20:21], off
	global_load_dword v113, v[84:85], off
	global_load_dword v114, v[86:87], off
	global_load_dword v115, v[46:47], off
	global_load_dword v116, v[88:89], off
	global_load_dword v117, v[48:49], off
	s_nop 0
	global_load_dword v90, v[90:91], off
	s_add_u32 s0, s10, s33
	s_addc_u32 s1, s2, s34
	s_lshl_b64 s[0:1], s[0:1], 13
	s_add_u32 s0, s23, s0
	s_addc_u32 s1, s24, s1
	v_lshl_add_u64 v[106:107], s[0:1], 0, v[94:95]
	global_load_dwordx4 v[86:89], v[106:107], off offset:16
	global_load_dwordx4 v[98:101], v[106:107], off
	global_load_dwordx4 v[82:85], v[110:111], off
	v_cmp_ge_i32_e64 s[0:1], v161, v140
	v_or_b32_e32 v192, s31, v140
	v_readlane_b32 s36, v239, 33
	v_readlane_b32 s50, v239, 47
	v_readlane_b32 s51, v239, 48
	v_ashrrev_i32_e32 v193, 31, v192
	v_readlane_b32 s37, v239, 34
	v_readlane_b32 s38, v239, 35
	v_readlane_b32 s39, v239, 36
	v_readlane_b32 s40, v239, 37
	v_readlane_b32 s41, v239, 38
	v_readlane_b32 s42, v239, 39
	v_readlane_b32 s43, v239, 40
	v_readlane_b32 s44, v239, 41
	v_readlane_b32 s45, v239, 42
	v_readlane_b32 s46, v239, 43
	v_readlane_b32 s47, v239, 44
	v_readlane_b32 s48, v239, 45
	v_readlane_b32 s49, v239, 46
	s_waitcnt vmcnt(34)
	v_bfe_u32 v18, v92, 16, 1
	s_waitcnt vmcnt(33)
	v_bfe_u32 v19, v93, 16, 1
	s_waitcnt vmcnt(32)
	v_bfe_u32 v20, v96, 16, 1
	s_waitcnt vmcnt(31)
	v_bfe_u32 v21, v97, 16, 1
	s_waitcnt vmcnt(30)
	v_bfe_u32 v46, v134, 16, 1
	s_waitcnt vmcnt(29)
	v_bfe_u32 v47, v135, 16, 1
	v_add3_u32 v18, v92, v18, s28
	v_add3_u32 v20, v96, v20, s28
	v_add3_u32 v46, v134, v46, s28
	s_waitcnt vmcnt(26)
	v_bfe_u32 v74, v174, 16, 1
	v_add3_u32 v19, v93, v19, s28
	v_add3_u32 v21, v97, v21, s28
	v_add3_u32 v47, v135, v47, s28
	v_lshrrev_b32_e32 v18, 16, v18
	v_lshrrev_b32_e32 v20, 16, v20
	v_lshrrev_b32_e32 v46, 16, v46
	v_bfe_u32 v48, v136, 16, 1
	v_add3_u32 v74, v174, v74, s28
	v_and_or_b32 v18, v19, s29, v18
	v_and_or_b32 v19, v21, s29, v20
	v_and_or_b32 v20, v47, s29, v46
	s_waitcnt vmcnt(25)
	v_bfe_u32 v47, v175, 16, 1
	v_bfe_u32 v49, v137, 16, 1
	v_add3_u32 v48, v136, v48, s28
	v_lshrrev_b32_e32 v46, 16, v74
	v_add3_u32 v47, v175, v47, s28
	v_add3_u32 v49, v137, v49, s28
	v_lshrrev_b32_e32 v48, 16, v48
	v_and_or_b32 v46, v47, s29, v46
	s_waitcnt vmcnt(24)
	v_bfe_u32 v47, v176, 16, 1
	v_and_or_b32 v21, v49, s29, v48
	v_add3_u32 v47, v176, v47, s28
	s_waitcnt vmcnt(23)
	v_bfe_u32 v48, v177, 16, 1
	v_lshrrev_b32_e32 v47, 16, v47
	v_add3_u32 v48, v177, v48, s28
	v_and_or_b32 v47, v48, s29, v47
	s_waitcnt vmcnt(22)
	v_bfe_u32 v48, v178, 16, 1
	v_add3_u32 v48, v178, v48, s28
	s_waitcnt vmcnt(21)
	v_bfe_u32 v49, v102, 16, 1
	v_lshrrev_b32_e32 v48, 16, v48
	v_add3_u32 v49, v102, v49, s28
	v_and_or_b32 v48, v49, s29, v48
	s_waitcnt vmcnt(20)
	v_bfe_u32 v49, v103, 16, 1
	v_add3_u32 v49, v103, v49, s28
	s_waitcnt vmcnt(19)
	v_bfe_u32 v74, v104, 16, 1
	v_lshrrev_b32_e32 v49, 16, v49
	v_add3_u32 v74, v104, v74, s28
	v_and_or_b32 v49, v74, s29, v49
	s_waitcnt vmcnt(18)
	v_bfe_u32 v74, v108, 16, 1
	v_add3_u32 v74, v108, v74, s28
	s_waitcnt vmcnt(17)
	v_bfe_u32 v91, v109, 16, 1
	v_lshrrev_b32_e32 v74, 16, v74
	v_add3_u32 v91, v109, v91, s28
	v_and_or_b32 v74, v91, s29, v74
	s_waitcnt vmcnt(16)
	v_bfe_u32 v91, v112, 16, 1
	v_add3_u32 v91, v112, v91, s28
	s_waitcnt vmcnt(15)
	v_bfe_u32 v92, v75, 16, 1
	v_lshrrev_b32_e32 v91, 16, v91
	v_add3_u32 v75, v75, v92, s28
	v_and_or_b32 v75, v75, s29, v91
	s_waitcnt vmcnt(14)
	v_bfe_u32 v91, v76, 16, 1
	v_add3_u32 v76, v76, v91, s28
	s_waitcnt vmcnt(13)
	v_bfe_u32 v91, v77, 16, 1
	v_lshrrev_b32_e32 v76, 16, v76
	v_add3_u32 v77, v77, v91, s28
	v_and_or_b32 v76, v77, s29, v76
	s_waitcnt vmcnt(12)
	v_bfe_u32 v77, v78, 16, 1
	v_add3_u32 v77, v78, v77, s28
	s_waitcnt vmcnt(11)
	v_bfe_u32 v78, v79, 16, 1
	v_lshrrev_b32_e32 v77, 16, v77
	v_add3_u32 v78, v79, v78, s28
	global_load_dwordx4 v[102:105], v[110:111], off offset:256
	v_and_or_b32 v77, v78, s29, v77
	s_waitcnt vmcnt(11)
	v_bfe_u32 v78, v80, 16, 1
	v_add3_u32 v78, v80, v78, s28
	s_waitcnt vmcnt(10)
	v_bfe_u32 v79, v81, 16, 1
	v_lshrrev_b32_e32 v78, 16, v78
	v_add3_u32 v79, v81, v79, s28
	v_and_or_b32 v78, v79, s29, v78
	s_waitcnt vmcnt(9)
	v_bfe_u32 v79, v113, 16, 1
	v_add3_u32 v79, v113, v79, s28
	s_waitcnt vmcnt(8)
	v_bfe_u32 v80, v114, 16, 1
	v_lshrrev_b32_e32 v79, 16, v79
	v_add3_u32 v80, v114, v80, s28
	v_and_or_b32 v79, v80, s29, v79
	s_waitcnt vmcnt(7)
	v_bfe_u32 v80, v115, 16, 1
	v_add3_u32 v80, v115, v80, s28
	s_waitcnt vmcnt(6)
	v_bfe_u32 v81, v116, 16, 1
	v_lshrrev_b32_e32 v80, 16, v80
	v_add3_u32 v81, v116, v81, s28
	v_and_or_b32 v80, v81, s29, v80
	s_waitcnt vmcnt(5)
	v_bfe_u32 v81, v117, 16, 1
	v_add3_u32 v81, v117, v81, s28
	s_waitcnt vmcnt(4)
	v_bfe_u32 v91, v90, 16, 1
	v_lshrrev_b32_e32 v81, 16, v81
	v_add3_u32 v90, v90, v91, s28
	v_and_or_b32 v81, v90, s29, v81
	global_load_dwordx4 v[90:93], v[106:107], off offset:48
	global_load_dwordx4 v[94:97], v[106:107], off offset:32
	s_waitcnt vmcnt(5)
	v_mul_f32_e32 v87, 0x3fb8aa3b, v87
	s_waitcnt vmcnt(4)
	v_mul_f32_e32 v98, 0x3fb8aa3b, v98
	v_exp_f32_e32 v116, v87
	v_mul_f32_e32 v87, 0x3fb8aa3b, v100
	v_exp_f32_e32 v108, v98
	v_mul_f32_e32 v98, 0x3fb8aa3b, v99
	v_exp_f32_e32 v109, v87
	v_mul_f32_e32 v87, 0x3fb8aa3b, v88
	v_mul_f32_e32 v88, 0x3fb8aa3b, v101
	v_exp_f32_e32 v112, v98
	v_exp_f32_e32 v113, v88
	global_load_dwordx4 v[98:101], v[110:111], off offset:16
	s_waitcnt vmcnt(4)
	v_lshlrev_b32_e32 v115, 16, v83
	v_lshlrev_b32_e32 v114, 16, v82
	v_and_b32_e32 v83, 0xffff0000, v83
	v_and_b32_e32 v82, 0xffff0000, v82
	v_pk_mul_f32 v[114:115], v[114:115], s[16:17] op_sel_hi:[1,0]
	v_pk_mul_f32 v[82:83], v[82:83], s[16:17] op_sel_hi:[1,0]
	v_rcp_f32_e32 v118, v112
	v_pk_mul_f32 v[122:123], v[114:115], v[108:109]
	v_pk_mul_f32 v[82:83], v[82:83], v[112:113]
	v_rcp_f32_e32 v119, v113
	global_load_dwordx4 v[112:115], v[110:111], off offset:272
	v_mul_f32_e32 v86, 0x3fb8aa3b, v86
	v_mul_f32_e32 v88, 0x3fb8aa3b, v89
	v_exp_f32_e32 v86, v86
	v_exp_f32_e32 v87, v87
	v_exp_f32_e32 v117, v88
	v_rcp_f32_e32 v88, v108
	v_rcp_f32_e32 v89, v109
	v_lshlrev_b32_e32 v125, 16, v85
	v_lshlrev_b32_e32 v124, 16, v84
	v_and_b32_e32 v85, 0xffff0000, v85
	v_and_b32_e32 v84, 0xffff0000, v84
	v_pk_mul_f32 v[124:125], v[124:125], s[16:17] op_sel_hi:[1,0]
	v_pk_mul_f32 v[84:85], v[84:85], s[16:17] op_sel_hi:[1,0]
	v_pk_mul_f32 v[124:125], v[124:125], v[86:87]
	v_pk_mul_f32 v[84:85], v[84:85], v[116:117]
	s_waitcnt vmcnt(4)
	v_lshlrev_b32_e32 v109, 16, v103
	v_lshlrev_b32_e32 v108, 16, v102
	v_pk_mul_f32 v[88:89], v[88:89], v[108:109]
	v_rcp_f32_e32 v108, v86
	v_rcp_f32_e32 v109, v87
	v_and_b32_e32 v103, 0xffff0000, v103
	v_and_b32_e32 v102, 0xffff0000, v102
	v_pk_mul_f32 v[102:103], v[118:119], v[102:103]
	v_rcp_f32_e32 v118, v116
	v_rcp_f32_e32 v119, v117
	v_lshlrev_b32_e32 v87, 16, v105
	v_lshlrev_b32_e32 v86, 16, v104
	v_bfe_u32 v116, v83, 16, 1
	v_pk_mul_f32 v[86:87], v[108:109], v[86:87]
	v_bfe_u32 v108, v85, 16, 1
	v_add3_u32 v83, v83, v116, s28
	v_bfe_u32 v116, v124, 16, 1
	v_bfe_u32 v109, v84, 16, 1
	v_bfe_u32 v117, v82, 16, 1
	v_add3_u32 v85, v85, v108, s28
	v_bfe_u32 v108, v122, 16, 1
	v_add3_u32 v116, v124, v116, s28
	v_and_b32_e32 v105, 0xffff0000, v105
	v_and_b32_e32 v104, 0xffff0000, v104
	v_add3_u32 v82, v82, v117, s28
	v_add3_u32 v84, v84, v109, s28
	v_bfe_u32 v109, v123, 16, 1
	v_bfe_u32 v117, v125, 16, 1
	v_add3_u32 v108, v122, v108, s28
	v_lshrrev_b32_e32 v116, 16, v116
	v_pk_mul_f32 v[104:105], v[118:119], v[104:105]
	v_add3_u32 v117, v125, v117, s28
	v_add3_u32 v109, v123, v109, s28
	v_lshrrev_b32_e32 v108, 16, v108
	v_and_or_b32 v84, v84, s29, v116
	v_bfe_u32 v116, v103, 16, 1
	v_lshrrev_b32_e32 v109, 16, v109
	v_lshrrev_b32_e32 v117, 16, v117
	v_and_or_b32 v82, v82, s29, v108
	v_bfe_u32 v108, v105, 16, 1
	v_add3_u32 v103, v103, v116, s28
	v_bfe_u32 v116, v86, 16, 1
	v_and_or_b32 v85, v85, s29, v117
	v_and_or_b32 v83, v83, s29, v109
	v_bfe_u32 v109, v104, 16, 1
	v_bfe_u32 v117, v102, 16, 1
	v_add3_u32 v105, v105, v108, s28
	v_bfe_u32 v108, v88, 16, 1
	v_add3_u32 v86, v86, v116, s28
	v_add3_u32 v102, v102, v117, s28
	v_add3_u32 v104, v104, v109, s28
	v_bfe_u32 v109, v89, 16, 1
	v_bfe_u32 v117, v87, 16, 1
	v_add3_u32 v88, v88, v108, s28
	v_lshrrev_b32_e32 v86, 16, v86
	s_waitcnt vmcnt(3)
	v_mul_f32_e32 v91, 0x3fb8aa3b, v91
	v_add3_u32 v87, v87, v117, s28
	v_add3_u32 v89, v89, v109, s28
	v_lshrrev_b32_e32 v108, 16, v88
	v_and_or_b32 v88, v104, s29, v86
	s_waitcnt vmcnt(2)
	v_mul_f32_e32 v94, 0x3fb8aa3b, v94
	v_mul_f32_e32 v95, 0x3fb8aa3b, v95
	v_exp_f32_e32 v104, v91
	v_mul_f32_e32 v91, 0x3fb8aa3b, v96
	v_lshrrev_b32_e32 v109, 16, v89
	v_lshrrev_b32_e32 v87, 16, v87
	v_and_or_b32 v86, v102, s29, v108
	v_exp_f32_e32 v94, v94
	v_exp_f32_e32 v102, v95
	v_exp_f32_e32 v95, v91
	v_mul_f32_e32 v91, 0x3fb8aa3b, v92
	v_mul_f32_e32 v92, 0x3fb8aa3b, v97
	v_and_or_b32 v89, v105, s29, v87
	v_and_or_b32 v87, v103, s29, v109
	v_exp_f32_e32 v103, v92
	v_mul_f32_e32 v90, 0x3fb8aa3b, v90
	global_load_dwordx4 v[116:119], v[106:107], off offset:80
	global_load_dwordx4 v[122:125], v[106:107], off offset:64
	v_exp_f32_e32 v90, v90
	v_exp_f32_e32 v91, v91
	v_mul_f32_e32 v92, 0x3fb8aa3b, v93
	s_waitcnt vmcnt(3)
	v_lshlrev_b32_e32 v109, 16, v99
	v_lshlrev_b32_e32 v108, 16, v98
	v_and_b32_e32 v99, 0xffff0000, v99
	v_and_b32_e32 v98, 0xffff0000, v98
	v_exp_f32_e32 v105, v92
	v_rcp_f32_e32 v92, v94
	v_pk_mul_f32 v[98:99], v[98:99], s[16:17] op_sel_hi:[1,0]
	v_rcp_f32_e32 v93, v95
	v_pk_mul_f32 v[126:127], v[98:99], v[102:103]
	v_lshlrev_b32_e32 v99, 16, v101
	v_lshlrev_b32_e32 v98, 16, v100
	v_pk_mul_f32 v[108:109], v[108:109], s[16:17] op_sel_hi:[1,0]
	v_pk_mul_f32 v[98:99], v[98:99], s[16:17] op_sel_hi:[1,0]
	v_pk_mul_f32 v[108:109], v[108:109], v[94:95]
	s_waitcnt vmcnt(2)
	v_lshlrev_b32_e32 v95, 16, v113
	v_lshlrev_b32_e32 v94, 16, v112
	v_pk_mul_f32 v[128:129], v[98:99], v[90:91]
	v_and_b32_e32 v99, 0xffff0000, v101
	v_and_b32_e32 v98, 0xffff0000, v100
	v_pk_mul_f32 v[94:95], v[92:93], v[94:95]
	v_and_b32_e32 v93, 0xffff0000, v113
	v_and_b32_e32 v92, 0xffff0000, v112
	v_pk_mul_f32 v[112:113], v[98:99], s[16:17] op_sel_hi:[1,0]
	global_load_dwordx4 v[98:101], v[110:111], off offset:32
	v_rcp_f32_e32 v96, v102
	v_rcp_f32_e32 v97, v103
	v_rcp_f32_e32 v102, v104
	v_rcp_f32_e32 v103, v105
	v_pk_mul_f32 v[130:131], v[112:113], v[104:105]
	v_pk_mul_f32 v[96:97], v[96:97], v[92:93]
	v_rcp_f32_e32 v92, v90
	v_rcp_f32_e32 v93, v91
	v_lshlrev_b32_e32 v91, 16, v115
	v_lshlrev_b32_e32 v90, 16, v114
	v_pk_mul_f32 v[104:105], v[92:93], v[90:91]
	v_and_b32_e32 v91, 0xffff0000, v115
	v_and_b32_e32 v90, 0xffff0000, v114
	global_load_dwordx4 v[112:115], v[110:111], off offset:288
	v_pk_mul_f32 v[102:103], v[102:103], v[90:91]
	v_bfe_u32 v90, v131, 16, 1
	v_bfe_u32 v91, v130, 16, 1
	v_bfe_u32 v92, v127, 16, 1
	v_bfe_u32 v93, v126, 16, 1
	v_add3_u32 v126, v126, v93, s28
	v_add3_u32 v127, v127, v92, s28
	v_add3_u32 v91, v130, v91, s28
	v_add3_u32 v90, v131, v90, s28
	v_bfe_u32 v92, v108, 16, 1
	v_bfe_u32 v93, v109, 16, 1
	v_bfe_u32 v130, v128, 16, 1
	v_bfe_u32 v131, v129, 16, 1
	v_add3_u32 v129, v129, v131, s28
	v_add3_u32 v128, v128, v130, s28
	v_add3_u32 v93, v109, v93, s28
	v_add3_u32 v92, v108, v92, s28
	v_lshrrev_b32_e32 v108, 16, v92
	v_lshrrev_b32_e32 v109, 16, v93
	v_lshrrev_b32_e32 v92, 16, v128
	v_lshrrev_b32_e32 v93, 16, v129
	v_and_or_b32 v93, v90, s29, v93
	v_and_or_b32 v92, v91, s29, v92
	v_and_or_b32 v91, v127, s29, v109
	v_and_or_b32 v90, v126, s29, v108
	v_bfe_u32 v108, v103, 16, 1
	v_bfe_u32 v109, v102, 16, 1
	v_bfe_u32 v126, v97, 16, 1
	v_bfe_u32 v127, v96, 16, 1
	v_add3_u32 v127, v96, v127, s28
	v_add3_u32 v126, v97, v126, s28
	v_add3_u32 v96, v102, v109, s28
	v_add3_u32 v97, v103, v108, s28
	v_bfe_u32 v103, v95, 16, 1
	v_bfe_u32 v108, v104, 16, 1
	v_bfe_u32 v109, v105, 16, 1
	v_bfe_u32 v102, v94, 16, 1
	v_add3_u32 v105, v105, v109, s28
	v_add3_u32 v104, v104, v108, s28
	v_add3_u32 v95, v95, v103, s28
	v_add3_u32 v94, v94, v102, s28
	v_lshrrev_b32_e32 v95, 16, v95
	v_lshrrev_b32_e32 v102, 16, v104
	v_lshrrev_b32_e32 v103, 16, v105
	s_waitcnt vmcnt(3)
	v_mul_f32_e32 v116, 0x3fb8aa3b, v116
	v_and_or_b32 v97, v97, s29, v103
	v_and_or_b32 v96, v96, s29, v102
	v_and_or_b32 v95, v126, s29, v95
	global_load_dwordx4 v[102:105], v[106:107], off offset:112
	s_nop 0
	global_load_dwordx4 v[106:109], v[106:107], off offset:96
	v_exp_f32_e32 v126, v116
	s_waitcnt vmcnt(4)
	v_mul_f32_e32 v116, 0x3fb8aa3b, v123
	v_exp_f32_e32 v128, v116
	v_mul_f32_e32 v116, 0x3fb8aa3b, v117
	v_exp_f32_e32 v130, v116
	v_mul_f32_e32 v116, 0x3fb8aa3b, v124
	v_lshrrev_b32_e32 v94, 16, v94
	v_mul_f32_e32 v122, 0x3fb8aa3b, v122
	v_exp_f32_e32 v123, v116
	v_mul_f32_e32 v116, 0x3fb8aa3b, v118
	v_and_or_b32 v94, v127, s29, v94
	v_exp_f32_e32 v122, v122
	v_exp_f32_e32 v127, v116
	v_mul_f32_e32 v116, 0x3fb8aa3b, v125
	v_exp_f32_e32 v129, v116
	v_mul_f32_e32 v116, 0x3fb8aa3b, v119
	v_exp_f32_e32 v131, v116
	global_load_dwordx4 v[116:119], v[110:111], off offset:48
	s_waitcnt vmcnt(4)
	v_lshlrev_b32_e32 v125, 16, v99
	v_lshlrev_b32_e32 v124, 16, v98
	v_pk_mul_f32 v[124:125], v[124:125], s[16:17] op_sel_hi:[1,0]
	v_rcp_f32_e32 v132, v122
	v_pk_mul_f32 v[136:137], v[124:125], v[122:123]
	v_rcp_f32_e32 v133, v123
	global_load_dwordx4 v[122:125], v[110:111], off offset:304
	v_rcp_f32_e32 v134, v128
	v_rcp_f32_e32 v135, v129
	v_and_b32_e32 v99, 0xffff0000, v99
	v_and_b32_e32 v98, 0xffff0000, v98
	v_pk_mul_f32 v[98:99], v[98:99], s[16:17] op_sel_hi:[1,0]
	s_waitcnt vmcnt(4)
	v_lshlrev_b32_e32 v111, 16, v113
	v_pk_mul_f32 v[98:99], v[98:99], v[128:129]
	v_lshlrev_b32_e32 v110, 16, v112
	v_and_b32_e32 v113, 0xffff0000, v113
	v_and_b32_e32 v112, 0xffff0000, v112
	v_rcp_f32_e32 v128, v126
	v_rcp_f32_e32 v129, v127
	v_pk_mul_f32 v[112:113], v[134:135], v[112:113]
	v_lshlrev_b32_e32 v135, 16, v101
	v_lshlrev_b32_e32 v134, 16, v100
	v_and_b32_e32 v101, 0xffff0000, v101
	v_and_b32_e32 v100, 0xffff0000, v100
	v_pk_mul_f32 v[134:135], v[134:135], s[16:17] op_sel_hi:[1,0]
	v_pk_mul_f32 v[100:101], v[100:101], s[16:17] op_sel_hi:[1,0]
	v_pk_mul_f32 v[110:111], v[132:133], v[110:111]
	v_rcp_f32_e32 v132, v130
	v_pk_mul_f32 v[134:135], v[134:135], v[126:127]
	v_pk_mul_f32 v[100:101], v[100:101], v[130:131]
	v_rcp_f32_e32 v133, v131
	v_lshlrev_b32_e32 v127, 16, v115
	v_lshlrev_b32_e32 v126, 16, v114
	v_pk_mul_f32 v[126:127], v[128:129], v[126:127]
	v_bfe_u32 v128, v101, 16, 1
	v_bfe_u32 v130, v99, 16, 1
	v_bfe_u32 v129, v100, 16, 1
	v_bfe_u32 v131, v98, 16, 1
	v_add3_u32 v99, v99, v130, s28
	v_add3_u32 v101, v101, v128, s28
	v_bfe_u32 v128, v136, 16, 1
	v_bfe_u32 v130, v134, 16, 1
	v_and_b32_e32 v115, 0xffff0000, v115
	v_and_b32_e32 v114, 0xffff0000, v114
	v_add3_u32 v98, v98, v131, s28
	v_add3_u32 v100, v100, v129, s28
	v_bfe_u32 v129, v137, 16, 1
	v_bfe_u32 v131, v135, 16, 1
	v_add3_u32 v130, v134, v130, s28
	v_add3_u32 v128, v136, v128, s28
	v_pk_mul_f32 v[114:115], v[132:133], v[114:115]
	v_add3_u32 v131, v135, v131, s28
	v_add3_u32 v129, v137, v129, s28
	v_lshrrev_b32_e32 v128, 16, v128
	v_lshrrev_b32_e32 v130, 16, v130
	v_lshrrev_b32_e32 v129, 16, v129
	v_lshrrev_b32_e32 v131, 16, v131
	v_and_or_b32 v100, v100, s29, v130
	v_and_or_b32 v98, v98, s29, v128
	v_bfe_u32 v128, v115, 16, 1
	v_bfe_u32 v130, v113, 16, 1
	v_and_or_b32 v101, v101, s29, v131
	v_and_or_b32 v99, v99, s29, v129
	v_bfe_u32 v129, v114, 16, 1
	v_bfe_u32 v131, v112, 16, 1
	v_add3_u32 v130, v113, v130, s28
	v_add3_u32 v113, v115, v128, s28
	v_bfe_u32 v128, v126, 16, 1
	v_add3_u32 v131, v112, v131, s28
	v_add3_u32 v112, v114, v129, s28
	v_bfe_u32 v114, v110, 16, 1
	v_bfe_u32 v129, v127, 16, 1
	v_add3_u32 v126, v126, v128, s28
	s_waitcnt vmcnt(3)
	v_mul_f32_e32 v103, 0x3fb8aa3b, v103
	v_bfe_u32 v115, v111, 16, 1
	v_add3_u32 v127, v127, v129, s28
	v_add3_u32 v110, v110, v114, s28
	v_lshrrev_b32_e32 v114, 16, v126
	s_waitcnt vmcnt(2)
	v_mul_f32_e32 v106, 0x3fb8aa3b, v106
	v_mul_f32_e32 v107, 0x3fb8aa3b, v107
	v_exp_f32_e32 v126, v103
	v_mul_f32_e32 v103, 0x3fb8aa3b, v108
	v_add3_u32 v111, v111, v115, s28
	v_lshrrev_b32_e32 v115, 16, v127
	v_and_or_b32 v112, v112, s29, v114
	v_exp_f32_e32 v106, v106
	v_exp_f32_e32 v114, v107
	v_exp_f32_e32 v107, v103
	v_mul_f32_e32 v103, 0x3fb8aa3b, v104
	v_mul_f32_e32 v104, 0x3fb8aa3b, v109
	v_and_or_b32 v113, v113, s29, v115
	v_exp_f32_e32 v115, v104
	v_mul_f32_e32 v104, 0x3fb8aa3b, v105
	v_mul_f32_e32 v102, 0x3fb8aa3b, v102
	v_exp_f32_e32 v127, v104
	v_rcp_f32_e32 v104, v106
	v_rcp_f32_e32 v105, v107
	v_exp_f32_e32 v102, v102
	v_exp_f32_e32 v103, v103
	v_rcp_f32_e32 v108, v114
	s_waitcnt vmcnt(1)
	v_lshlrev_b32_e32 v129, 16, v117
	v_lshlrev_b32_e32 v128, 16, v116
	v_rcp_f32_e32 v109, v115
	v_pk_mul_f32 v[128:129], v[128:129], s[16:17] op_sel_hi:[1,0]
	v_and_b32_e32 v117, 0xffff0000, v117
	v_pk_mul_f32 v[128:129], v[128:129], v[106:107]
	s_waitcnt vmcnt(0)
	v_lshlrev_b32_e32 v107, 16, v123
	v_lshlrev_b32_e32 v106, 16, v122
	v_and_b32_e32 v116, 0xffff0000, v116
	v_pk_mul_f32 v[106:107], v[104:105], v[106:107]
	v_and_b32_e32 v105, 0xffff0000, v123
	v_and_b32_e32 v104, 0xffff0000, v122
	v_pk_mul_f32 v[116:117], v[116:117], s[16:17] op_sel_hi:[1,0]
	v_pk_mul_f32 v[108:109], v[108:109], v[104:105]
	v_rcp_f32_e32 v104, v102
	v_rcp_f32_e32 v105, v103
	v_pk_mul_f32 v[116:117], v[116:117], v[114:115]
	v_rcp_f32_e32 v114, v126
	v_lshlrev_b32_e32 v123, 16, v119
	v_lshlrev_b32_e32 v122, 16, v118
	v_rcp_f32_e32 v115, v127
	v_pk_mul_f32 v[122:123], v[122:123], s[16:17] op_sel_hi:[1,0]
	v_and_b32_e32 v119, 0xffff0000, v119
	v_and_b32_e32 v118, 0xffff0000, v118
	v_pk_mul_f32 v[122:123], v[122:123], v[102:103]
	v_pk_mul_f32 v[118:119], v[118:119], s[16:17] op_sel_hi:[1,0]
	v_lshlrev_b32_e32 v103, 16, v125
	v_lshlrev_b32_e32 v102, 16, v124
	v_pk_mul_f32 v[118:119], v[118:119], v[126:127]
	v_pk_mul_f32 v[126:127], v[104:105], v[102:103]
	v_and_b32_e32 v103, 0xffff0000, v125
	v_and_b32_e32 v102, 0xffff0000, v124
	v_pk_mul_f32 v[114:115], v[114:115], v[102:103]
	v_bfe_u32 v102, v119, 16, 1
	v_bfe_u32 v103, v118, 16, 1
	v_bfe_u32 v104, v117, 16, 1
	v_bfe_u32 v105, v116, 16, 1
	v_add3_u32 v116, v116, v105, s28
	v_add3_u32 v117, v117, v104, s28
	v_add3_u32 v103, v118, v103, s28
	v_add3_u32 v102, v119, v102, s28
	v_bfe_u32 v104, v128, 16, 1
	v_bfe_u32 v105, v129, 16, 1
	v_bfe_u32 v118, v122, 16, 1
	v_bfe_u32 v119, v123, 16, 1
	v_add3_u32 v119, v123, v119, s28
	v_add3_u32 v118, v122, v118, s28
	v_add3_u32 v105, v129, v105, s28
	v_add3_u32 v104, v128, v104, s28
	v_lshrrev_b32_e32 v122, 16, v104
	v_lshrrev_b32_e32 v123, 16, v105
	v_lshrrev_b32_e32 v104, 16, v118
	v_lshrrev_b32_e32 v105, 16, v119
	v_and_or_b32 v105, v102, s29, v105
	v_and_or_b32 v104, v103, s29, v104
	v_and_or_b32 v103, v117, s29, v123
	v_and_or_b32 v102, v116, s29, v122
	v_bfe_u32 v116, v115, 16, 1
	v_bfe_u32 v117, v114, 16, 1
	v_bfe_u32 v118, v109, 16, 1
	v_bfe_u32 v119, v108, 16, 1
	v_add3_u32 v119, v108, v119, s28
	v_add3_u32 v118, v109, v118, s28
	v_add3_u32 v108, v114, v117, s28
	v_add3_u32 v109, v115, v116, s28
	v_bfe_u32 v114, v106, 16, 1
	v_bfe_u32 v115, v107, 16, 1
	v_bfe_u32 v116, v126, 16, 1
	v_bfe_u32 v117, v127, 16, 1
	v_add3_u32 v117, v127, v117, s28
	v_add3_u32 v116, v126, v116, s28
	v_add3_u32 v107, v107, v115, s28
	v_add3_u32 v106, v106, v114, s28
	v_lshrrev_b32_e32 v110, 16, v110
	v_lshrrev_b32_e32 v111, 16, v111
	v_lshrrev_b32_e32 v106, 16, v106
	v_lshrrev_b32_e32 v107, 16, v107
	v_lshrrev_b32_e32 v114, 16, v116
	v_lshrrev_b32_e32 v115, 16, v117
	s_waitcnt lgkmcnt(0)
	ds_write_b128 v142, v[82:85]
	ds_write_b128 v142, v[90:93] offset:16
	ds_write_b128 v142, v[98:101] offset:32
	ds_write_b128 v142, v[102:105] offset:48
	ds_write_b128 v142, v[18:21] offset:4096
	ds_write_b128 v142, v[46:49] offset:4112
	ds_write_b128 v142, v[74:77] offset:4128
	ds_write_b128 v142, v[78:81] offset:4144
	v_and_or_b32 v111, v130, s29, v111
	v_and_or_b32 v110, v131, s29, v110
	v_and_or_b32 v109, v109, s29, v115
	v_and_or_b32 v108, v108, s29, v114
	v_and_or_b32 v107, v118, s29, v107
	v_and_or_b32 v106, v119, s29, v106
	s_waitcnt lgkmcnt(0)
	ds_read_b128 v[134:137], v172
	ds_read_b128 v[98:101], v172 offset:1024
	ds_read_b128 v[46:49], v172 offset:2048
	ds_read_b128 v[18:21], v172 offset:3072
	s_waitcnt lgkmcnt(0)
	ds_write_b128 v142, v[86:89]
	ds_write_b128 v142, v[94:97] offset:16
	ds_write_b128 v142, v[110:113] offset:32
	ds_write_b128 v142, v[106:109] offset:48
	s_waitcnt lgkmcnt(0)
	ds_read_b128 v[78:81], v172 offset:4096
	ds_read_b128 v[82:85], v172
	s_waitcnt lgkmcnt(1)
	v_mfma_f32_16x16x32_bf16 v[110:113], v[78:81], v[98:101], v[26:29]
	s_nop 2
	ds_read_b128 v[26:29], v172 offset:5120
	ds_read_b128 v[94:97], v172 offset:6144
	ds_read_b128 v[90:93], v172 offset:7168
	ds_read_b128 v[86:89], v143 offset:1024
	v_mfma_f32_16x16x32_bf16 v[74:77], v[78:81], v[46:49], v[30:33]
	s_waitcnt lgkmcnt(3)
	v_mfma_f32_16x16x32_bf16 v[30:33], v[26:29], v[134:137], v[38:41]
	s_waitcnt lgkmcnt(0)
	v_mfma_f32_16x16x32_bf16 v[38:41], v[86:89], v[134:137], 0
	v_mfma_f32_16x16x32_bf16 v[122:125], v[78:81], v[134:137], v[22:25]
	v_mfma_f32_16x16x32_bf16 v[22:25], v[78:81], v[18:21], v[34:37]
	s_nop 5
	v_cndmask_b32_e64 v38, 0, v38, s[0:1]
	v_cmp_ge_i32_e64 s[0:1], v169, v140
	v_mfma_f32_16x16x32_bf16 v[34:37], v[82:85], v[134:137], 0
	v_mfma_f32_16x16x32_bf16 v[114:117], v[26:29], v[98:101], v[42:45]
	v_mfma_f32_16x16x32_bf16 v[102:105], v[90:93], v[98:101], v[70:73]
	s_nop 5
	v_cndmask_b32_e64 v34, v34, 0, vcc
	v_cndmask_b32_e64 v35, 0, v35, s[0:1]
	v_cmp_ge_i32_e64 s[0:1], v162, v140
	v_bfe_u32 v42, v34, 16, 1
	v_add3_u32 v34, v34, v42, s28
	v_cndmask_b32_e64 v39, 0, v39, s[0:1]
	v_cmp_ge_i32_e64 s[0:1], v164, v140
	v_bfe_u32 v42, v35, 16, 1
	v_lshrrev_b32_e32 v34, 16, v34
	v_cndmask_b32_e64 v36, 0, v36, s[0:1]
	v_cmp_ge_i32_e64 s[0:1], v163, v140
	v_add3_u32 v35, v35, v42, s28
	v_and_or_b32 v70, v35, s29, v34
	v_cndmask_b32_e64 v40, 0, v40, s[0:1]
	v_cmp_ge_i32_e64 s[0:1], v166, v140
	v_bfe_u32 v34, v36, 16, 1
	v_add3_u32 v34, v36, v34, s28
	v_cndmask_b32_e64 v37, 0, v37, s[0:1]
	v_bfe_u32 v35, v37, 16, 1
	v_lshrrev_b32_e32 v34, 16, v34
	v_add3_u32 v35, v37, v35, s28
	v_and_or_b32 v71, v35, s29, v34
	v_bfe_u32 v34, v38, 16, 1
	v_add3_u32 v34, v38, v34, s28
	v_bfe_u32 v35, v39, 16, 1
	v_cmp_ge_i32_e64 s[0:1], v165, v140
	v_lshrrev_b32_e32 v34, 16, v34
	v_add3_u32 v35, v39, v35, s28
	v_cndmask_b32_e64 v41, 0, v41, s[0:1]
	v_and_or_b32 v72, v35, s29, v34
	v_bfe_u32 v34, v40, 16, 1
	v_add3_u32 v34, v40, v34, s28
	v_bfe_u32 v39, v41, 16, 1
	v_lshrrev_b32_e32 v38, 16, v34
	v_add3_u32 v39, v41, v39, s28
	v_mfma_f32_16x16x32_bf16 v[78:81], v[26:29], v[46:49], v[50:53]
	v_and_or_b32 v73, v39, s29, v38
	v_cmp_ge_i32_e64 s[0:1], v169, v168
	v_mfma_f32_16x16x32_bf16 v[50:53], v[94:97], v[134:137], v[58:61]
	v_mfma_f32_16x16x32_bf16 v[106:109], v[94:97], v[98:101], v[62:65]
	s_nop 1
	ds_read2_b64 v[58:61], v144 offset1:4
	v_mfma_f32_16x16x32_bf16 v[34:37], v[82:85], v[98:101], 0
	ds_read2_b64 v[62:65], v145 offset1:4
	v_mfma_f32_16x16x32_bf16 v[38:41], v[86:89], v[98:101], 0
	v_mfma_f32_16x16x32_bf16 v[26:29], v[26:29], v[18:21], v[54:57]
	s_nop 4
	v_cndmask_b32_e64 v34, v34, 0, s[8:9]
	s_nop 0
	v_cndmask_b32_e64 v142, v38, 0, vcc
	v_cndmask_b32_e64 v38, 0, v35, s[0:1]
	v_mfma_f32_16x16x32_bf16 v[54:57], v[90:93], v[134:137], v[66:69]
	v_cmp_ge_i32_e64 s[0:1], v162, v168
	v_bfe_u32 v35, v34, 16, 1
	v_add3_u32 v34, v34, v35, s28
	ds_read2_b64 v[66:69], v171 offset1:4
	v_cndmask_b32_e64 v174, 0, v39, s[0:1]
	v_cmp_ge_i32_e64 s[0:1], v164, v168
	v_lshrrev_b32_e32 v39, 16, v34
	s_waitcnt lgkmcnt(0)
	v_mfma_f32_16x16x32_bf16 v[126:129], v[66:69], v[70:73], v[50:53]
	v_cndmask_b32_e64 v42, 0, v36, s[0:1]
	v_cmp_ge_i32_e64 s[0:1], v163, v168
	v_bfe_u32 v188, v174, 16, 1
	s_add_u32 s8, s25, s18
	v_cndmask_b32_e64 v172, 0, v40, s[0:1]
	v_cmp_ge_i32_e64 s[0:1], v166, v168
	v_bfe_u32 v40, v38, 16, 1
	v_add3_u32 v38, v38, v40, s28
	v_cndmask_b32_e64 v119, 0, v37, s[0:1]
	v_cmp_ge_i32_e64 s[0:1], v165, v168
	v_mfma_f32_16x16x32_bf16 v[34:37], v[58:61], v[70:73], v[122:125]
	v_and_or_b32 v118, v38, s29, v39
	v_cndmask_b32_e64 v175, 0, v41, s[0:1]
	ds_read2_b64 v[38:41], v170 offset1:4
	v_mfma_f32_16x16x32_bf16 v[122:125], v[62:65], v[70:73], v[30:33]
	v_bfe_u32 v51, v119, 16, 1
	v_add3_u32 v51, v119, v51, s28
	v_cmp_ge_i32_e64 s[0:1], v153, v140
	v_bfe_u32 v30, v42, 16, 1
	v_add3_u32 v30, v42, v30, s28
	ds_read_b128 v[42:45], v173
	v_lshrrev_b32_e32 v50, 16, v30
	ds_read_b128 v[30:33], v143 offset:3072
	s_waitcnt lgkmcnt(2)
	v_mfma_f32_16x16x32_bf16 v[130:133], v[38:41], v[70:73], v[54:57]
	v_and_or_b32 v119, v51, s29, v50
	s_addc_u32 s9, s26, 0
	s_lshr_b32 s98, s3, 6
	s_add_i32 s98, s98, 0x800
	s_and_b32 s99, s3, 0xfffff83f
	s_cmp_eq_u32 s99, 0
	s_cselect_b32 s3, s98, 0x1000
	v_bfe_u32 v54, v142, 16, 1
	s_waitcnt lgkmcnt(1)
	v_mfma_f32_16x16x32_bf16 v[50:53], v[42:45], v[134:137], 0
	v_add3_u32 v54, v142, v54, s28
	v_lshrrev_b32_e32 v173, 16, v54
	s_cmpk_lt_i32 s3, 0x820
	s_waitcnt lgkmcnt(0)
	v_mfma_f32_16x16x32_bf16 v[54:57], v[30:33], v[134:137], 0
	s_nop 2
	v_cndmask_b32_e64 v50, 0, v50, s[0:1]
	v_cmp_ge_i32_e64 s[0:1], v167, v140
	v_lshlrev_b64 v[136:137], 1, v[120:121]
	v_lshl_add_u64 v[134:135], v[120:121], 2, s[50:51]
	global_load_dwordx4 v[180:183], v[134:135], off
	v_cndmask_b32_e64 v54, 0, v54, s[0:1]
	v_cmp_ge_i32_e64 s[0:1], v155, v140
	v_bfe_u32 v121, v172, 16, 1
	v_add3_u32 v121, v172, v121, s28
	v_cndmask_b32_e64 v51, 0, v51, s[0:1]
	v_cmp_ge_i32_e64 s[0:1], v154, v140
	v_bfe_u32 v70, v51, 16, 1
	v_add3_u32 v51, v51, v70, s28
	v_cndmask_b32_e64 v55, 0, v55, s[0:1]
	v_cmp_ge_i32_e64 s[0:1], v157, v140
	v_bfe_u32 v70, v50, 16, 1
	v_add3_u32 v50, v50, v70, s28
	v_cndmask_b32_e64 v52, 0, v52, s[0:1]
	v_cmp_ge_i32_e64 s[0:1], v156, v140
	v_lshrrev_b32_e32 v50, 16, v50
	v_and_or_b32 v176, v51, s29, v50
	v_cndmask_b32_e64 v56, 0, v56, s[0:1]
	v_cmp_ge_i32_e64 s[0:1], v159, v140
	v_bfe_u32 v51, v52, 16, 1
	v_add3_u32 v51, v52, v51, s28
	v_cndmask_b32_e64 v53, 0, v53, s[0:1]
	v_bfe_u32 v50, v53, 16, 1
	v_cmp_ge_i32_e64 s[0:1], v158, v140
	v_add3_u32 v50, v53, v50, s28
	v_lshrrev_b32_e32 v51, 16, v51
	v_cndmask_b32_e64 v57, 0, v57, s[0:1]
	v_and_or_b32 v177, v50, s29, v51
	v_mad_i64_i32 v[50:51], s[0:1], v192, s27, v[138:139]
	v_lshl_add_u64 v[50:51], v[50:51], 0, s[18:19]
	v_lshl_add_u64 v[142:143], v[50:51], 0, v[136:137]
	global_load_dwordx2 v[194:195], v[142:143], off offset:1024
	s_mov_b32 s100, 0x16400
	s_mov_b32 s101, 0
	global_load_dwordx4 v[230:233], v[134:135], off
	global_load_dwordx4 v[234:237], v[134:135], off offset:64
	global_load_dwordx4 v[240:243], v[134:135], off offset:128
	global_load_dwordx4 v[244:247], v[134:135], off offset:192
	global_load_dwordx2 v[196:197], v[142:143], off offset:1056
	global_load_dwordx2 v[198:199], v[142:143], off offset:1088
	global_load_dwordx2 v[200:201], v[142:143], off offset:1120
	v_lshl_add_u64 v[226:227], v[142:143], 0, s[100:101]
	global_load_dwordx2 v[202:203], v[226:227], off offset:1024
	global_load_dwordx2 v[204:205], v[226:227], off offset:1056
	global_load_dwordx2 v[206:207], v[226:227], off offset:1088
	global_load_dwordx2 v[208:209], v[226:227], off offset:1120
	v_lshl_add_u64 v[226:227], v[226:227], 0, s[100:101]
	global_load_dwordx2 v[210:211], v[226:227], off offset:1024
	global_load_dwordx2 v[212:213], v[226:227], off offset:1056
	global_load_dwordx2 v[214:215], v[226:227], off offset:1088
	global_load_dwordx2 v[216:217], v[226:227], off offset:1120
	v_lshl_add_u64 v[226:227], v[226:227], 0, s[100:101]
	global_load_dwordx2 v[218:219], v[226:227], off offset:1024
	global_load_dwordx2 v[220:221], v[226:227], off offset:1056
	global_load_dwordx2 v[222:223], v[226:227], off offset:1088
	global_load_dwordx2 v[224:225], v[226:227], off offset:1120
	v_bfe_u32 v51, v54, 16, 1
	ds_read2_b64 v[70:73], v144 offset0:8 offset1:12
	v_bfe_u32 v50, v55, 16, 1
	v_add3_u32 v51, v54, v51, s28
	v_add3_u32 v50, v55, v50, s28
	v_lshrrev_b32_e32 v51, 16, v51
	v_and_or_b32 v178, v50, s29, v51
	v_bfe_u32 v50, v57, 16, 1
	v_bfe_u32 v51, v56, 16, 1
	v_add3_u32 v50, v57, v50, s28
	v_add3_u32 v51, v56, v51, s28
	ds_read2_b64 v[54:57], v145 offset0:8 offset1:12
	v_lshrrev_b32_e32 v51, 16, v51
	v_and_or_b32 v179, v50, s29, v51
	ds_read2_b64 v[50:53], v171 offset0:8 offset1:12
	v_lshrrev_b32_e32 v121, 16, v121
	s_waitcnt lgkmcnt(2)
	v_mfma_f32_16x16x32_bf16 v[184:187], v[70:73], v[176:179], v[34:37]
	v_cmp_lt_i32_e64 s[0:1], v147, v148
	s_nop 1
	v_add3_u32 v34, v174, v188, s28
	v_and_or_b32 v120, v34, s29, v173
	ds_read2_b64 v[34:37], v170 offset0:8 offset1:12
	s_waitcnt lgkmcnt(2)
	v_mfma_f32_16x16x32_bf16 v[188:191], v[54:57], v[176:179], v[122:125]
	v_mul_f32_e32 v140, v185, v185
	v_fmac_f32_e32 v140, v184, v184
	v_fmac_f32_e32 v140, v186, v186
	s_waitcnt lgkmcnt(1)
	v_mfma_f32_16x16x32_bf16 v[126:129], v[50:53], v[176:179], v[126:129]
	v_fmac_f32_e32 v140, v187, v187
	s_nop 1
	v_fmac_f32_e32 v140, v188, v188
	v_bfe_u32 v122, v175, 16, 1
	v_fmac_f32_e32 v140, v189, v189
	v_add3_u32 v122, v175, v122, s28
	v_fmac_f32_e32 v140, v190, v190
	v_and_or_b32 v121, v122, s29, v121
	s_waitcnt lgkmcnt(0)
	v_mfma_f32_16x16x32_bf16 v[122:125], v[34:37], v[176:179], v[130:133]
	v_fmac_f32_e32 v140, v191, v191
	v_mov_b32_e32 v178, v184
	v_pk_mul_f32 v[132:133], v[126:127], v[126:127]
	v_cndmask_b32_e64 v130, v146, v147, s[0:1]
	v_add_f32_e32 v132, v140, v132
	v_lshlrev_b32_e32 v170, 2, v130
	v_pk_mul_f32 v[130:131], v[128:129], v[128:129]
	v_add_f32_e32 v132, v133, v132
	v_add_f32_e32 v130, v130, v132
	v_add_f32_e32 v140, v131, v130
	v_pk_mul_f32 v[132:133], v[122:123], v[122:123]
	v_pk_mul_f32 v[130:131], v[124:125], v[124:125]
	v_add_f32_e32 v132, v140, v132
	v_add_f32_e32 v132, v133, v132
	v_add_f32_e32 v130, v130, v132
	v_add_f32_e32 v140, v131, v130
	ds_bpermute_b32 v144, v170, v140
	v_cmp_lt_i32_e64 s[0:1], v149, v148
	v_mfma_f32_16x16x32_bf16 v[130:133], v[58:61], v[118:121], v[110:113]
	v_mov_b32_e32 v179, v186
	v_mov_b32_e32 v186, v185
	s_waitcnt lgkmcnt(0)
	v_add_f32_e32 v140, v140, v144
	v_cndmask_b32_e64 v110, v146, v149, s[0:1]
	v_lshlrev_b32_e32 v171, 2, v110
	ds_bpermute_b32 v144, v171, v140
	v_mfma_f32_16x16x32_bf16 v[110:113], v[62:65], v[118:121], v[114:117]
	s_waitcnt lgkmcnt(0)
	s_nop 1
	v_add_f32_e32 v114, v140, v144
	v_fmamk_f32 v114, v114, 0x3c800000, v150
	v_mul_f32_e32 v115, 0x4b800000, v114
	v_cmp_gt_f32_e64 s[0:1], s30, v114
	v_mfma_f32_16x16x32_bf16 v[10:13], v[94:97], v[46:49], v[10:13]
	s_nop 0
	v_cndmask_b32_e64 v114, v114, v115, s[0:1]
	v_rsq_f32_e32 v140, v114
	v_mfma_f32_16x16x32_bf16 v[114:117], v[66:69], v[118:121], v[106:109]
	s_nop 2
	v_mul_f32_e32 v106, 0x45800000, v140
	s_waitcnt vmcnt(19)
	v_lshlrev_b32_e32 v108, 16, v194
	v_mul_f32_e32 v144, 0xbfb8aa3b, v108
	v_exp_f32_e32 v145, v144
	v_and_b32_e32 v144, 0xffff0000, v194
	v_mul_f32_e32 v172, 0xbfb8aa3b, v144
	v_exp_f32_e32 v173, v172
	v_lshlrev_b32_e32 v109, 16, v195
	v_add_f32_e32 v145, 1.0, v145
	v_rcp_f32_e32 v172, v145
	v_add_f32_e32 v173, 1.0, v173
	v_rcp_f32_e32 v174, v173
	v_mul_f32_e32 v173, 0xbfb8aa3b, v109
	v_exp_f32_e32 v173, v173
	v_and_b32_e32 v145, 0xffff0000, v195
	v_mul_f32_e32 v175, 0xbfb8aa3b, v145
	v_exp_f32_e32 v175, v175
	v_add_f32_e32 v173, 1.0, v173
	v_rcp_f32_e32 v173, v173
	v_cndmask_b32_e64 v140, v140, v106, s[0:1]
	v_lshlrev_b64 v[106:107], 11, v[192:193]
	v_pk_mul_f32 v[178:179], v[178:179], v[140:141] op_sel_hi:[1,0]
	v_pk_mul_f32 v[108:109], v[172:173], v[108:109]
	v_add_f32_e32 v172, 1.0, v175
	v_rcp_f32_e32 v175, v172
	v_mov_b32_e32 v192, v180
	v_mov_b32_e32 v193, v182
	v_pk_mul_f32 v[178:179], v[192:193], v[178:179]
	v_pk_mul_f32 v[172:173], v[186:187], v[140:141] op_sel_hi:[1,0]
	v_mov_b32_e32 v182, v181
	v_pk_mul_f32 v[108:109], v[108:109], v[178:179]
	v_pk_mul_f32 v[172:173], v[182:183], v[172:173]
	v_pk_mul_f32 v[144:145], v[174:175], v[144:145]
	v_lshl_add_u64 v[106:107], s[8:9], 0, v[106:107]
	v_pk_mul_f32 v[144:145], v[144:145], v[172:173]
	v_and_b32_sdwa v172, v109, v151 dst_sel:DWORD dst_unused:UNUSED_PAD src0_sel:WORD_1 src1_sel:DWORD
	v_and_b32_sdwa v173, v108, v151 dst_sel:DWORD dst_unused:UNUSED_PAD src0_sel:WORD_1 src1_sel:DWORD
	v_add3_u32 v108, v108, v173, s28
	v_add3_u32 v109, v109, v172, s28
	v_and_b32_sdwa v172, v145, v151 dst_sel:DWORD dst_unused:UNUSED_PAD src0_sel:WORD_1 src1_sel:DWORD
	v_and_b32_sdwa v173, v144, v151 dst_sel:DWORD dst_unused:UNUSED_PAD src0_sel:WORD_1 src1_sel:DWORD
	v_add3_u32 v145, v145, v172, s28
	v_add3_u32 v144, v144, v173, s28
	v_and_b32_e32 v145, 0xffff0000, v145
	v_and_b32_e32 v144, 0xffff0000, v144
	v_or_b32_sdwa v109, v145, v109 dst_sel:DWORD dst_unused:UNUSED_PAD src0_sel:DWORD src1_sel:WORD_1
	v_or_b32_sdwa v108, v144, v108 dst_sel:DWORD dst_unused:UNUSED_PAD src0_sel:DWORD src1_sel:WORD_1
	v_lshl_add_u64 v[144:145], v[106:107], 0, v[136:137]
	global_store_dwordx2 v[144:145], v[108:109], off
	v_mfma_f32_16x16x32_bf16 v[106:109], v[38:41], v[118:121], v[102:105]
	s_waitcnt vmcnt(15)
	v_lshlrev_b32_e32 v119, 16, v196
	v_and_b32_e32 v179, 0xffff0000, v196
	v_mul_f32_e32 v118, v188, v140
	v_mul_f32_e32 v102, 0xbfb8aa3b, v119
	v_exp_f32_e32 v120, v102
	v_lshlrev_b32_e32 v181, 16, v197
	v_and_b32_e32 v177, 0xffff0000, v197
	v_mul_f32_e32 v178, v189, v140
	v_add_f32_e32 v120, 1.0, v120
	v_rcp_f32_e32 v121, v120
	v_mul_f32_e32 v176, v191, v140
	v_mul_f32_e32 v180, v190, v140
	v_mfma_f32_16x16x32_bf16 v[102:105], v[42:45], v[98:101], 0
	v_cmp_ge_i32_e64 s[0:1], v153, v168
	v_mov_b32_e32 v120, v234
	v_mul_f32_e32 v172, 0xbfb8aa3b, v179
	v_exp_f32_e32 v172, v172
	v_pk_mul_f32 v[118:119], v[120:121], v[118:119]
	v_mov_b32_e32 v120, v235
	v_pk_mul_f32 v[118:119], v[118:119], v[118:119] op_sel:[0,1] op_sel_hi:[1,0]
	v_mfma_f32_16x16x32_bf16 v[98:101], v[30:33], v[98:101], 0
	v_add_f32_e32 v119, 1.0, v172
	v_rcp_f32_e32 v121, v119
	v_mul_f32_e32 v119, 0xbfb8aa3b, v181
	v_exp_f32_e32 v119, v119
	v_mov_b32_e32 v172, v236
	v_pk_mul_f32 v[120:121], v[120:121], v[178:179]
	v_mov_b32_e32 v178, v237
	v_add_f32_e32 v119, 1.0, v119
	v_rcp_f32_e32 v173, v119
	v_mul_f32_e32 v119, 0xbfb8aa3b, v177
	v_exp_f32_e32 v119, v119
	v_pk_mul_f32 v[120:121], v[120:121], v[120:121] op_sel:[0,1] op_sel_hi:[1,0]
	v_pk_mul_f32 v[172:173], v[172:173], v[180:181]
	v_cndmask_b32_e64 v102, 0, v102, s[0:1]
	v_add_f32_e32 v119, 1.0, v119
	v_rcp_f32_e32 v179, v119
	v_bfe_u32 v119, v118, 16, 1
	v_add3_u32 v118, v118, v119, s28
	v_bfe_u32 v119, v120, 16, 1
	v_pk_mul_f32 v[174:175], v[178:179], v[176:177]
	v_pk_mul_f32 v[172:173], v[172:173], v[172:173] op_sel:[0,1] op_sel_hi:[1,0]
	v_lshrrev_b32_e32 v118, 16, v118
	v_add3_u32 v119, v120, v119, s28
	v_pk_mul_f32 v[174:175], v[174:175], v[174:175] op_sel:[0,1] op_sel_hi:[1,0]
	v_and_or_b32 v118, v119, s29, v118
	v_bfe_u32 v119, v172, 16, 1
	v_add3_u32 v119, v172, v119, s28
	v_bfe_u32 v120, v174, 16, 1
	v_lshrrev_b32_e32 v119, 16, v119
	v_add3_u32 v120, v174, v120, s28
	v_and_or_b32 v119, v120, s29, v119
	global_store_dwordx2 v[144:145], v[118:119], off offset:32
	v_cmp_ge_i32_e64 s[0:1], v167, v168
	v_mfma_f32_16x16x32_bf16 v[6:9], v[94:97], v[18:21], v[6:9]
	v_cndmask_b32_e64 v118, 0, v98, s[0:1]
	v_cmp_ge_i32_e64 s[0:1], v155, v168
	v_mfma_f32_16x16x32_bf16 v[14:17], v[90:93], v[46:49], v[14:17]
	s_nop 0
	v_cndmask_b32_e64 v98, 0, v103, s[0:1]
	v_cmp_ge_i32_e64 s[0:1], v154, v168
	v_mfma_f32_16x16x32_bf16 v[2:5], v[90:93], v[18:21], v[2:5]
	s_nop 0
	v_cndmask_b32_e64 v103, 0, v99, s[0:1]
	v_cmp_ge_i32_e64 s[0:1], v157, v168
	s_nop 1
	v_cndmask_b32_e64 v99, 0, v104, s[0:1]
	v_cmp_ge_i32_e64 s[0:1], v156, v168
	s_nop 1
	v_cndmask_b32_e64 v104, 0, v100, s[0:1]
	v_cmp_ge_i32_e64 s[0:1], v159, v168
	s_nop 1
	v_cndmask_b32_e64 v100, 0, v105, s[0:1]
	v_bfe_u32 v105, v98, 16, 1
	v_add3_u32 v98, v98, v105, s28
	v_bfe_u32 v105, v102, 16, 1
	v_add3_u32 v102, v102, v105, s28
	v_lshrrev_b32_e32 v102, 16, v102
	v_and_or_b32 v98, v98, s29, v102
	v_bfe_u32 v102, v100, 16, 1
	v_add3_u32 v100, v100, v102, s28
	v_bfe_u32 v102, v99, 16, 1
	v_add3_u32 v99, v99, v102, s28
	v_lshrrev_b32_e32 v99, 16, v99
	v_bfe_u32 v102, v118, 16, 1
	v_cmp_ge_i32_e64 s[0:1], v158, v168
	v_and_or_b32 v99, v100, s29, v99
	v_bfe_u32 v100, v103, 16, 1
	v_add3_u32 v102, v118, v102, s28
	v_cndmask_b32_e64 v101, 0, v101, s[0:1]
	v_add3_u32 v100, v103, v100, s28
	v_lshrrev_b32_e32 v102, 16, v102
	v_and_or_b32 v100, v100, s29, v102
	v_bfe_u32 v102, v101, 16, 1
	v_add3_u32 v101, v101, v102, s28
	v_bfe_u32 v102, v104, 16, 1
	v_add3_u32 v102, v104, v102, s28
	v_lshrrev_b32_e32 v102, 16, v102
	v_and_or_b32 v101, v101, s29, v102
	v_mul_f32_e32 v102, v126, v140
	s_waitcnt vmcnt(15)
	v_lshlrev_b32_e32 v103, 16, v198
	v_mul_f32_e32 v104, 0xbfb8aa3b, v103
	v_exp_f32_e32 v104, v104
	v_mfma_f32_16x16x32_bf16 v[118:121], v[70:73], v[98:101], v[130:133]
	v_add_f32_e32 v104, 1.0, v104
	v_rcp_f32_e32 v105, v104
	s_nop 0
	v_and_b32_e32 v131, 0xffff0000, v198
	v_mul_f32_e32 v126, 0xbfb8aa3b, v131
	v_exp_f32_e32 v126, v126
	v_mul_f32_e32 v130, v127, v140
	v_lshlrev_b32_e32 v127, 16, v199
	v_mov_b32_e32 v104, v240
	v_pk_mul_f32 v[102:103], v[104:105], v[102:103]
	v_mov_b32_e32 v104, v241
	v_pk_mul_f32 v[102:103], v[102:103], v[102:103] op_sel:[0,1] op_sel_hi:[1,0]
	v_and_b32_e32 v133, 0xffff0000, v199
	v_add_f32_e32 v103, 1.0, v126
	v_rcp_f32_e32 v105, v103
	v_mul_f32_e32 v103, 0xbfb8aa3b, v127
	v_exp_f32_e32 v103, v103
	v_mul_f32_e32 v126, v128, v140
	v_pk_mul_f32 v[104:105], v[104:105], v[130:131]
	v_mov_b32_e32 v130, v242
	v_add_f32_e32 v103, 1.0, v103
	v_rcp_f32_e32 v131, v103
	v_mul_f32_e32 v103, 0xbfb8aa3b, v133
	v_exp_f32_e32 v103, v103
	v_pk_mul_f32 v[104:105], v[104:105], v[104:105] op_sel:[0,1] op_sel_hi:[1,0]
	v_pk_mul_f32 v[126:127], v[130:131], v[126:127]
	v_mul_f32_e32 v132, v129, v140
	v_add_f32_e32 v103, 1.0, v103
	v_rcp_f32_e32 v131, v103
	v_bfe_u32 v103, v102, 16, 1
	v_mov_b32_e32 v130, v243
	v_add3_u32 v102, v102, v103, s28
	v_bfe_u32 v103, v104, 16, 1
	v_pk_mul_f32 v[126:127], v[126:127], v[126:127] op_sel:[0,1] op_sel_hi:[1,0]
	v_pk_mul_f32 v[128:129], v[130:131], v[132:133]
	v_lshrrev_b32_e32 v102, 16, v102
	v_add3_u32 v103, v104, v103, s28
	v_pk_mul_f32 v[128:129], v[128:129], v[128:129] op_sel:[0,1] op_sel_hi:[1,0]
	v_and_or_b32 v102, v103, s29, v102
	v_bfe_u32 v103, v126, 16, 1
	v_add3_u32 v103, v126, v103, s28
	v_bfe_u32 v104, v128, 16, 1
	v_lshrrev_b32_e32 v103, 16, v103
	v_add3_u32 v104, v128, v104, s28
	v_and_or_b32 v103, v104, s29, v103
	global_store_dwordx2 v[144:145], v[102:103], off offset:64
	s_waitcnt vmcnt(15)
	v_lshlrev_b32_e32 v131, 16, v200
	v_mul_f32_e32 v102, 0xbfb8aa3b, v131
	v_exp_f32_e32 v130, v102
	v_mfma_f32_16x16x32_bf16 v[102:105], v[50:53], v[98:101], v[114:117]
	s_nop 2
	v_add_f32_e32 v115, 1.0, v130
	v_rcp_f32_e32 v115, v115
	v_and_b32_e32 v117, 0xffff0000, v200
	v_mul_f32_e32 v116, 0xbfb8aa3b, v117
	v_exp_f32_e32 v116, v116
	v_mul_f32_e32 v114, v122, v140
	v_mul_f32_e32 v122, v123, v140
	v_mfma_f32_16x16x32_bf16 v[110:113], v[54:57], v[98:101], v[110:113]
	v_mov_b32_e32 v130, v244
	v_pk_mul_f32 v[114:115], v[114:115], v[130:131]
	v_lshlrev_b32_e32 v131, 16, v201
	v_pk_mul_f32 v[114:115], v[114:115], v[114:115] op_sel:[0,1] op_sel_hi:[1,0]
	v_mov_b32_e32 v130, v246
	v_add_f32_e32 v115, 1.0, v116
	v_rcp_f32_e32 v123, v115
	v_mul_f32_e32 v115, 0xbfb8aa3b, v131
	v_exp_f32_e32 v115, v115
	v_mov_b32_e32 v116, v245
	v_and_b32_e32 v127, 0xffff0000, v201
	v_pk_mul_f32 v[116:117], v[122:123], v[116:117]
	v_add_f32_e32 v115, 1.0, v115
	v_rcp_f32_e32 v123, v115
	v_mul_f32_e32 v115, 0xbfb8aa3b, v127
	v_exp_f32_e32 v115, v115
	v_mul_f32_e32 v122, v124, v140
	v_pk_mul_f32 v[122:123], v[122:123], v[130:131]
	v_pk_mul_f32 v[116:117], v[116:117], v[116:117] op_sel:[0,1] op_sel_hi:[1,0]
	v_add_f32_e32 v115, 1.0, v115
	v_rcp_f32_e32 v131, v115
	v_bfe_u32 v115, v114, 16, 1
	v_mul_f32_e32 v130, v125, v140
	v_mov_b32_e32 v126, v247
	v_add3_u32 v114, v114, v115, s28
	v_bfe_u32 v115, v116, 16, 1
	v_pk_mul_f32 v[124:125], v[130:131], v[126:127]
	v_lshrrev_b32_e32 v114, 16, v114
	v_add3_u32 v115, v116, v115, s28
	v_or_b32_e32 v126, s31, v168
	v_and_or_b32 v116, v115, s29, v114
	v_mad_i64_i32 v[114:115], s[0:1], v126, s27, v[138:139]
	v_lshl_add_u64 v[114:115], v[114:115], 0, s[18:19]
	v_lshl_add_u64 v[114:115], v[114:115], 0, v[136:137]
	v_pk_mul_f32 v[122:123], v[122:123], v[122:123] op_sel:[0,1] op_sel_hi:[1,0]
	v_pk_mul_f32 v[124:125], v[124:125], v[124:125] op_sel:[0,1] op_sel_hi:[1,0]
	v_bfe_u32 v117, v122, 16, 1
	v_add3_u32 v117, v122, v117, s28
	v_bfe_u32 v122, v124, 16, 1
	v_lshrrev_b32_e32 v117, 16, v117
	v_add3_u32 v122, v124, v122, s28
	v_and_or_b32 v117, v122, s29, v117
	global_store_dwordx2 v[144:145], v[116:117], off offset:96
	v_mul_f32_e32 v116, v119, v119
	v_fmac_f32_e32 v116, v118, v118
	v_fmac_f32_e32 v116, v120, v120
	v_fmac_f32_e32 v116, v121, v121
	v_fmac_f32_e32 v116, v110, v110
	v_fmac_f32_e32 v116, v111, v111
	v_fmac_f32_e32 v116, v112, v112
	v_mfma_f32_16x16x32_bf16 v[98:101], v[34:37], v[98:101], v[106:109]
	v_fmac_f32_e32 v116, v113, v113
	v_ashrrev_i32_e32 v127, 31, v126
	s_nop 0
	v_pk_mul_f32 v[108:109], v[102:103], v[102:103]
	v_pk_mul_f32 v[106:107], v[104:105], v[104:105]
	v_add_f32_e32 v108, v116, v108
	v_add_f32_e32 v108, v109, v108
	v_add_f32_e32 v106, v106, v108
	v_add_f32_e32 v116, v107, v106
	v_pk_mul_f32 v[108:109], v[98:99], v[98:99]
	v_pk_mul_f32 v[106:107], v[100:101], v[100:101]
	v_add_f32_e32 v108, v116, v108
	v_add_f32_e32 v108, v109, v108
	v_add_f32_e32 v106, v106, v108
	v_add_f32_e32 v106, v107, v106
	ds_bpermute_b32 v107, v170, v106
	s_waitcnt lgkmcnt(0)
	v_add_f32_e32 v106, v106, v107
	ds_bpermute_b32 v107, v171, v106
	s_waitcnt lgkmcnt(0)
	v_add_f32_e32 v94, v106, v107
	v_fmamk_f32 v94, v94, 0x3c800000, v150
	v_mul_f32_e32 v95, 0x4b800000, v94
	v_cmp_gt_f32_e64 s[0:1], s30, v94
	s_waitcnt vmcnt(15)
	v_lshlrev_b32_e32 v96, 16, v202
	v_cndmask_b32_e64 v94, v94, v95, s[0:1]
	v_rsq_f32_e32 v94, v94
	v_mul_f32_e32 v106, 0xbfb8aa3b, v96
	v_exp_f32_e32 v107, v106
	v_and_b32_e32 v106, 0xffff0000, v202
	v_mul_f32_e32 v95, 0x45800000, v94
	v_cndmask_b32_e64 v130, v94, v95, s[0:1]
	v_mul_f32_e32 v108, 0xbfb8aa3b, v106
	v_mul_f32_e32 v97, v118, v130
	v_exp_f32_e32 v118, v108
	v_add_f32_e32 v107, 1.0, v107
	v_rcp_f32_e32 v108, v107
	v_mov_b32_e32 v109, v230
	v_add_f32_e32 v107, 1.0, v118
	v_rcp_f32_e32 v122, v107
	v_pk_mul_f32 v[96:97], v[108:109], v[96:97]
	v_mul_f32_e32 v107, v119, v130
	v_pk_mul_f32 v[96:97], v[96:97], v[96:97] op_sel:[0,1] op_sel_hi:[1,0]
	v_mov_b32_e32 v123, v231
	v_pk_mul_f32 v[106:107], v[122:123], v[106:107]
	v_lshlrev_b32_e32 v108, 16, v203
	v_pk_mul_f32 v[106:107], v[106:107], v[106:107] op_sel:[0,1] op_sel_hi:[1,0]
	v_mul_f32_e32 v97, 0xbfb8aa3b, v108
	v_and_b32_e32 v118, 0xffff0000, v203
	v_exp_f32_e32 v97, v97
	v_mul_f32_e32 v107, 0xbfb8aa3b, v118
	v_exp_f32_e32 v107, v107
	v_mov_b32_e32 v123, v232
	v_add_f32_e32 v97, 1.0, v97
	v_rcp_f32_e32 v122, v97
	v_add_f32_e32 v97, 1.0, v107
	v_rcp_f32_e32 v124, v97
	v_mul_f32_e32 v109, v120, v130
	v_bfe_u32 v97, v96, 16, 1
	v_pk_mul_f32 v[108:109], v[122:123], v[108:109]
	v_mul_f32_e32 v119, v121, v130
	v_add3_u32 v96, v96, v97, s28
	v_bfe_u32 v97, v106, 16, 1
	v_pk_mul_f32 v[108:109], v[108:109], v[108:109] op_sel:[0,1] op_sel_hi:[1,0]
	v_mov_b32_e32 v125, v233
	v_pk_mul_f32 v[118:119], v[124:125], v[118:119]
	v_lshrrev_b32_e32 v96, 16, v96
	v_add3_u32 v97, v106, v97, s28
	v_pk_mul_f32 v[118:119], v[118:119], v[118:119] op_sel:[0,1] op_sel_hi:[1,0]
	v_and_or_b32 v96, v97, s29, v96
	v_bfe_u32 v97, v108, 16, 1
	v_lshlrev_b64 v[94:95], 11, v[126:127]
	v_add3_u32 v97, v108, v97, s28
	v_bfe_u32 v106, v118, 16, 1
	v_lshl_add_u64 v[94:95], s[8:9], 0, v[94:95]
	v_lshrrev_b32_e32 v97, 16, v97
	v_add3_u32 v106, v118, v106, s28
	v_and_or_b32 v97, v106, s29, v97
	v_lshl_add_u64 v[94:95], v[94:95], 0, v[136:137]
	global_store_dwordx2 v[94:95], v[96:97], off
	s_waitcnt vmcnt(15)
	v_lshlrev_b32_e32 v97, 16, v204
	v_mul_f32_e32 v90, 0xbfb8aa3b, v97
	v_exp_f32_e32 v118, v90
	v_mul_f32_e32 v96, v110, v130
	v_and_b32_e32 v121, 0xffff0000, v204
	v_mul_f32_e32 v120, v111, v130
	v_add_f32_e32 v110, 1.0, v118
	v_rcp_f32_e32 v119, v110
	v_mul_f32_e32 v116, v113, v130
	v_mfma_f32_16x16x32_bf16 v[90:93], v[82:85], v[46:49], 0
	v_cmp_ge_i32_e64 s[0:1], v161, v160
	v_mov_b32_e32 v118, v234
	v_mul_f32_e32 v106, 0xbfb8aa3b, v121
	v_exp_f32_e32 v106, v106
	v_pk_mul_f32 v[96:97], v[118:119], v[96:97]
	v_lshlrev_b32_e32 v119, 16, v205
	v_pk_mul_f32 v[96:97], v[96:97], v[96:97] op_sel:[0,1] op_sel_hi:[1,0]
	v_mov_b32_e32 v110, v235
	v_add_f32_e32 v97, 1.0, v106
	v_rcp_f32_e32 v111, v97
	v_mul_f32_e32 v97, 0xbfb8aa3b, v119
	v_exp_f32_e32 v97, v97
	v_and_b32_e32 v117, 0xffff0000, v205
	v_pk_mul_f32 v[106:107], v[110:111], v[120:121]
	v_mul_f32_e32 v118, v112, v130
	v_add_f32_e32 v97, 1.0, v97
	v_rcp_f32_e32 v111, v97
	v_mul_f32_e32 v97, 0xbfb8aa3b, v117
	v_exp_f32_e32 v97, v97
	v_mov_b32_e32 v110, v236
	v_pk_mul_f32 v[110:111], v[110:111], v[118:119]
	v_mov_b32_e32 v118, v237
	v_add_f32_e32 v97, 1.0, v97
	v_rcp_f32_e32 v119, v97
	v_pk_mul_f32 v[106:107], v[106:107], v[106:107] op_sel:[0,1] op_sel_hi:[1,0]
	v_bfe_u32 v97, v96, 16, 1
	v_add3_u32 v96, v96, v97, s28
	v_pk_mul_f32 v[108:109], v[118:119], v[116:117]
	v_bfe_u32 v97, v106, 16, 1
	v_pk_mul_f32 v[110:111], v[110:111], v[110:111] op_sel:[0,1] op_sel_hi:[1,0]
	v_lshrrev_b32_e32 v96, 16, v96
	v_add3_u32 v97, v106, v97, s28
	v_pk_mul_f32 v[108:109], v[108:109], v[108:109] op_sel:[0,1] op_sel_hi:[1,0]
	v_and_or_b32 v96, v97, s29, v96
	v_bfe_u32 v97, v110, 16, 1
	v_add3_u32 v97, v110, v97, s28
	v_bfe_u32 v106, v108, 16, 1
	v_lshrrev_b32_e32 v97, 16, v97
	v_add3_u32 v106, v108, v106, s28
	v_and_or_b32 v97, v106, s29, v97
	global_store_dwordx2 v[94:95], v[96:97], off offset:32
	v_mfma_f32_16x16x32_bf16 v[110:113], v[86:89], v[46:49], 0
	v_cndmask_b32_e64 v90, v90, 0, s[6:7]
	v_bfe_u32 v97, v90, 16, 1
	v_add3_u32 v90, v90, v97, s28
	v_lshrrev_b32_e32 v90, 16, v90
	v_mfma_f32_16x16x32_bf16 v[86:89], v[86:89], v[18:21], 0
	s_nop 2
	v_cndmask_b32_e64 v96, 0, v110, s[0:1]
	v_cmp_ge_i32_e64 s[0:1], v169, v160
	v_mfma_f32_16x16x32_bf16 v[82:85], v[82:85], v[18:21], 0
	s_nop 0
	v_cndmask_b32_e64 v91, 0, v91, s[0:1]
	v_cmp_ge_i32_e64 s[0:1], v162, v160
	v_bfe_u32 v97, v91, 16, 1
	v_add3_u32 v91, v91, v97, s28
	v_cndmask_b32_e64 v118, 0, v111, s[0:1]
	v_cmp_ge_i32_e64 s[0:1], v164, v160
	v_and_or_b32 v90, v91, s29, v90
	s_nop 0
	v_cndmask_b32_e64 v92, 0, v92, s[0:1]
	v_cmp_ge_i32_e64 s[0:1], v163, v160
	v_bfe_u32 v91, v92, 16, 1
	v_add3_u32 v91, v92, v91, s28
	v_cndmask_b32_e64 v119, 0, v112, s[0:1]
	v_cmp_ge_i32_e64 s[0:1], v166, v160
	v_lshrrev_b32_e32 v91, 16, v91
	v_mul_f32_e32 v112, v103, v130
	v_cndmask_b32_e64 v93, 0, v93, s[0:1]
	v_bfe_u32 v92, v93, 16, 1
	v_add3_u32 v92, v93, v92, s28
	v_and_or_b32 v91, v92, s29, v91
	v_bfe_u32 v92, v96, 16, 1
	v_add3_u32 v92, v96, v92, s28
	v_cmp_ge_i32_e64 s[0:1], v165, v160
	v_lshrrev_b32_e32 v114, 16, v92
	v_mul_f32_e32 v92, v102, v130
	v_cndmask_b32_e64 v120, 0, v113, s[0:1]
	v_cmp_ge_i32_e64 s[0:1], v161, v152
	v_bfe_u32 v115, v118, 16, 1
	s_waitcnt vmcnt(15)
	v_lshlrev_b32_e32 v93, 16, v206
	v_mul_f32_e32 v110, 0xbfb8aa3b, v93
	v_exp_f32_e32 v110, v110
	v_and_b32_e32 v113, 0xffff0000, v206
	v_add_f32_e32 v102, 1.0, v110
	v_rcp_f32_e32 v111, v102
	v_mul_f32_e32 v102, 0xbfb8aa3b, v113
	v_exp_f32_e32 v102, v102
	v_mov_b32_e32 v110, v240
	v_pk_mul_f32 v[92:93], v[110:111], v[92:93]
	v_lshlrev_b32_e32 v111, 16, v207
	v_pk_mul_f32 v[92:93], v[92:93], v[92:93] op_sel:[0,1] op_sel_hi:[1,0]
	v_mul_f32_e32 v110, v104, v130
	v_add_f32_e32 v93, 1.0, v102
	v_rcp_f32_e32 v103, v93
	v_mul_f32_e32 v93, 0xbfb8aa3b, v111
	v_exp_f32_e32 v93, v93
	v_mov_b32_e32 v102, v241
	v_pk_mul_f32 v[102:103], v[102:103], v[112:113]
	v_and_b32_e32 v113, 0xffff0000, v207
	v_add_f32_e32 v93, 1.0, v93
	v_rcp_f32_e32 v107, v93
	v_mul_f32_e32 v93, 0xbfb8aa3b, v113
	v_exp_f32_e32 v93, v93
	v_mov_b32_e32 v106, v242
	v_pk_mul_f32 v[106:107], v[106:107], v[110:111]
	v_pk_mul_f32 v[102:103], v[102:103], v[102:103] op_sel:[0,1] op_sel_hi:[1,0]
	v_add_f32_e32 v93, 1.0, v93
	v_rcp_f32_e32 v111, v93
	v_bfe_u32 v93, v92, 16, 1
	v_mul_f32_e32 v112, v105, v130
	v_mov_b32_e32 v110, v243
	v_add3_u32 v92, v92, v93, s28
	v_bfe_u32 v93, v102, 16, 1
	v_pk_mul_f32 v[106:107], v[106:107], v[106:107] op_sel:[0,1] op_sel_hi:[1,0]
	v_pk_mul_f32 v[104:105], v[110:111], v[112:113]
	v_lshrrev_b32_e32 v92, 16, v92
	v_add3_u32 v93, v102, v93, s28
	v_pk_mul_f32 v[104:105], v[104:105], v[104:105] op_sel:[0,1] op_sel_hi:[1,0]
	v_and_or_b32 v92, v93, s29, v92
	v_bfe_u32 v93, v106, 16, 1
	v_add3_u32 v93, v106, v93, s28
	v_bfe_u32 v102, v104, 16, 1
	v_lshrrev_b32_e32 v93, 16, v93
	v_add3_u32 v102, v104, v102, s28
	v_and_or_b32 v93, v102, s29, v93
	global_store_dwordx2 v[94:95], v[92:93], off offset:64
	v_bfe_u32 v93, v119, 16, 1
	v_cndmask_b32_e64 v111, 0, v86, s[0:1]
	v_cmp_ge_i32_e64 s[0:1], v169, v152
	v_add3_u32 v93, v119, v93, s28
	v_bfe_u32 v106, v120, 16, 1
	v_cndmask_b32_e64 v86, 0, v83, s[0:1]
	v_cmp_ge_i32_e64 s[0:1], v162, v152
	v_add3_u32 v92, v118, v115, s28
	v_lshrrev_b32_e32 v93, 16, v93
	v_add3_u32 v106, v120, v106, s28
	v_cndmask_b32_e64 v112, 0, v87, s[0:1]
	v_cmp_ge_i32_e64 s[0:1], v164, v152
	v_and_or_b32 v92, v92, s29, v114
	v_and_or_b32 v93, v106, s29, v93
	v_cndmask_b32_e64 v110, v82, 0, s[4:5]
	v_cndmask_b32_e64 v113, 0, v84, s[0:1]
	v_cmp_ge_i32_e64 s[0:1], v163, v152
	v_mfma_f32_16x16x32_bf16 v[106:109], v[58:61], v[90:93], v[74:77]
	s_nop 0
	v_cndmask_b32_e64 v114, 0, v88, s[0:1]
	v_cmp_ge_i32_e64 s[0:1], v166, v152
	v_bfe_u32 v74, v110, 16, 1
	v_bfe_u32 v76, v86, 16, 1
	v_cndmask_b32_e64 v75, 0, v85, s[0:1]
	v_add3_u32 v74, v110, v74, s28
	v_add3_u32 v76, v86, v76, s28
	v_mfma_f32_16x16x32_bf16 v[84:87], v[38:41], v[90:93], v[14:17]
	v_lshrrev_b32_e32 v74, 16, v74
	v_and_or_b32 v74, v76, s29, v74
	v_cmp_ge_i32_e64 s[0:1], v165, v152
	v_bfe_u32 v14, v113, 16, 1
	v_add3_u32 v14, v113, v14, s28
	v_lshrrev_b32_e32 v76, 16, v14
	v_mfma_f32_16x16x32_bf16 v[14:17], v[42:45], v[46:49], 0
	v_cndmask_b32_e64 v115, 0, v89, s[0:1]
	v_cmp_ge_i32_e64 s[0:1], v167, v160
	v_bfe_u32 v77, v75, 16, 1
	v_mfma_f32_16x16x32_bf16 v[46:49], v[30:33], v[46:49], 0
	v_add3_u32 v75, v75, v77, s28
	s_nop 2
	v_cndmask_b32_e64 v14, v14, 0, vcc
	s_waitcnt vmcnt(15)
	v_lshlrev_b32_e32 v77, 16, v209
	v_mfma_f32_16x16x32_bf16 v[80:83], v[62:65], v[90:93], v[78:81]
	v_and_or_b32 v75, v75, s29, v76
	v_mov_b32_e32 v76, v246
	v_mfma_f32_16x16x32_bf16 v[10:13], v[66:69], v[90:93], v[10:13]
	v_cndmask_b32_e64 v92, 0, v46, s[0:1]
	v_cmp_ge_i32_e64 s[0:1], v155, v160
	v_and_b32_e32 v79, 0xffff0000, v209
	v_mov_b32_e32 v78, v247
	v_cndmask_b32_e64 v15, 0, v15, s[0:1]
	v_bfe_u32 v46, v15, 16, 1
	v_cmp_ge_i32_e64 s[0:1], v154, v160
	v_add3_u32 v15, v15, v46, s28
	v_bfe_u32 v46, v14, 16, 1
	v_cndmask_b32_e64 v93, 0, v47, s[0:1]
	v_cmp_ge_i32_e64 s[0:1], v157, v160
	v_add3_u32 v14, v14, v46, s28
	v_lshrrev_b32_e32 v14, 16, v14
	v_cndmask_b32_e64 v16, 0, v16, s[0:1]
	v_cmp_ge_i32_e64 s[0:1], v156, v160
	v_and_or_b32 v46, v15, s29, v14
	v_bfe_u32 v15, v16, 16, 1
	v_cndmask_b32_e64 v110, 0, v48, s[0:1]
	v_cmp_ge_i32_e64 s[0:1], v159, v160
	v_add3_u32 v15, v16, v15, s28
	v_lshrrev_b32_e32 v16, 16, v15
	v_cndmask_b32_e64 v17, 0, v17, s[0:1]
	v_bfe_u32 v14, v17, 16, 1
	v_lshlrev_b32_e32 v15, 16, v208
	v_add3_u32 v14, v17, v14, s28
	v_mul_f32_e32 v17, 0xbfb8aa3b, v15
	v_exp_f32_e32 v17, v17
	v_cmp_ge_i32_e64 s[0:1], v158, v160
	v_and_or_b32 v47, v14, s29, v16
	v_mul_f32_e32 v16, v98, v130
	v_add_f32_e32 v14, 1.0, v17
	v_cndmask_b32_e64 v113, 0, v49, s[0:1]
	v_rcp_f32_e32 v17, v14
	v_and_b32_e32 v49, 0xffff0000, v208
	v_mul_f32_e32 v48, 0xbfb8aa3b, v49
	v_exp_f32_e32 v48, v48
	v_mov_b32_e32 v14, v244
	v_pk_mul_f32 v[14:15], v[16:17], v[14:15]
	v_mul_f32_e32 v16, v99, v130
	v_pk_mul_f32 v[14:15], v[14:15], v[14:15] op_sel:[0,1] op_sel_hi:[1,0]
	v_or_b32_e32 v96, s31, v160
	v_add_f32_e32 v15, 1.0, v48
	v_rcp_f32_e32 v17, v15
	v_mul_f32_e32 v15, 0xbfb8aa3b, v77
	v_exp_f32_e32 v15, v15
	v_mov_b32_e32 v48, v245
	v_pk_mul_f32 v[16:17], v[16:17], v[48:49]
	v_mul_f32_e32 v48, v100, v130
	v_add_f32_e32 v15, 1.0, v15
	v_rcp_f32_e32 v49, v15
	v_mul_f32_e32 v15, 0xbfb8aa3b, v79
	v_exp_f32_e32 v15, v15
	v_pk_mul_f32 v[16:17], v[16:17], v[16:17] op_sel:[0,1] op_sel_hi:[1,0]
	v_pk_mul_f32 v[48:49], v[48:49], v[76:77]
	v_mul_f32_e32 v76, v101, v130
	v_add_f32_e32 v15, 1.0, v15
	v_rcp_f32_e32 v77, v15
	v_bfe_u32 v15, v14, 16, 1
	v_add3_u32 v14, v14, v15, s28
	v_bfe_u32 v15, v16, 16, 1
	v_add3_u32 v15, v16, v15, s28
	v_mad_i64_i32 v[16:17], s[0:1], v96, s27, v[138:139]
	v_lshl_add_u64 v[16:17], v[16:17], 0, s[18:19]
	v_pk_mul_f32 v[76:77], v[76:77], v[78:79]
	v_lshl_add_u64 v[78:79], v[16:17], 0, v[136:137]
	v_pk_mul_f32 v[48:49], v[48:49], v[48:49] op_sel:[0,1] op_sel_hi:[1,0]
	v_lshrrev_b32_e32 v14, 16, v14
	v_pk_mul_f32 v[76:77], v[76:77], v[76:77] op_sel:[0,1] op_sel_hi:[1,0]
	v_and_or_b32 v14, v15, s29, v14
	v_bfe_u32 v15, v48, 16, 1
	v_add3_u32 v15, v48, v15, s28
	v_bfe_u32 v16, v76, 16, 1
	v_lshrrev_b32_e32 v15, 16, v15
	v_add3_u32 v16, v76, v16, s28
	v_and_or_b32 v15, v16, s29, v15
	global_store_dwordx2 v[94:95], v[14:15], off offset:96
	v_bfe_u32 v15, v92, 16, 1
	v_bfe_u32 v116, v93, 16, 1
	v_add3_u32 v15, v92, v15, s28
	v_add3_u32 v14, v93, v116, s28
	v_lshrrev_b32_e32 v15, 16, v15
	v_and_or_b32 v48, v14, s29, v15
	v_bfe_u32 v15, v110, 16, 1
	v_bfe_u32 v14, v113, 16, 1
	v_add3_u32 v15, v110, v15, s28
	v_add3_u32 v14, v113, v14, s28
	v_lshrrev_b32_e32 v15, 16, v15
	v_and_or_b32 v49, v14, s29, v15
	v_bfe_u32 v14, v111, 16, 1
	v_add3_u32 v14, v111, v14, s28
	v_mfma_f32_16x16x32_bf16 v[92:95], v[70:73], v[46:49], v[106:109]
	v_bfe_u32 v15, v112, 16, 1
	v_lshrrev_b32_e32 v14, 16, v14
	v_add3_u32 v15, v112, v15, s28
	v_and_or_b32 v76, v15, s29, v14
	v_mfma_f32_16x16x32_bf16 v[14:17], v[50:53], v[46:49], v[10:13]
	v_ashrrev_i32_e32 v97, 31, v96
	s_nop 1
	v_bfe_u32 v10, v114, 16, 1
	v_add3_u32 v10, v114, v10, s28
	v_mfma_f32_16x16x32_bf16 v[80:83], v[54:57], v[46:49], v[80:83]
	v_lshrrev_b32_e32 v77, 16, v10
	v_mfma_f32_16x16x32_bf16 v[10:13], v[34:37], v[46:49], v[84:87]
	v_mul_f32_e64 v48, v14, v14
	v_mul_f32_e64 v49, v15, v15
	v_pk_mul_f32 v[46:47], v[16:17], v[16:17]
	v_mul_f32_e32 v84, v93, v93
	v_fmac_f32_e32 v84, v92, v92
	v_fmac_f32_e32 v84, v94, v94
	v_fmac_f32_e32 v84, v95, v95
	v_fmac_f32_e32 v84, v80, v80
	v_fmac_f32_e32 v84, v81, v81
	v_fmac_f32_e32 v84, v82, v82
	v_fmac_f32_e32 v84, v83, v83
	v_add_f32_e32 v48, v84, v48
	v_add_f32_e32 v48, v49, v48
	v_add_f32_e32 v46, v46, v48
	v_add_f32_e32 v84, v47, v46
	v_pk_mul_f32 v[48:49], v[10:11], v[10:11]
	v_pk_mul_f32 v[46:47], v[12:13], v[12:13]
	v_add_f32_e32 v48, v84, v48
	v_add_f32_e32 v48, v49, v48
	v_add_f32_e32 v46, v46, v48
	v_add_f32_e32 v84, v47, v46
	ds_bpermute_b32 v85, v170, v84
	v_bfe_u32 v46, v115, 16, 1
	v_add3_u32 v46, v115, v46, s28
	v_and_or_b32 v77, v46, s29, v77
	s_nop 1
	v_mfma_f32_16x16x32_bf16 v[46:49], v[58:61], v[74:77], v[22:25]
	s_waitcnt lgkmcnt(0)
	v_add_f32_e32 v58, v84, v85
	ds_bpermute_b32 v59, v171, v58
	v_mov_b32_e32 v61, v230
	v_mfma_f32_16x16x32_bf16 v[22:25], v[62:65], v[74:77], v[26:29]
	s_waitcnt lgkmcnt(0)
	s_nop 0
	v_add_f32_e32 v26, v58, v59
	v_fmamk_f32 v26, v26, 0x3c800000, v150
	v_mul_f32_e32 v27, 0x4b800000, v26
	v_cmp_gt_f32_e64 s[0:1], s30, v26
	s_nop 1
	v_cndmask_b32_e64 v26, v26, v27, s[0:1]
	v_rsq_f32_e32 v58, v26
	v_mfma_f32_16x16x32_bf16 v[26:29], v[66:69], v[74:77], v[6:9]
	v_mov_b32_e32 v67, v232
	s_nop 1
	v_mul_f32_e32 v6, 0x45800000, v58
	s_waitcnt vmcnt(15)
	v_lshlrev_b32_e32 v8, 16, v210
	v_cndmask_b32_e64 v68, v58, v6, s[0:1]
	v_mul_f32_e32 v58, 0xbfb8aa3b, v8
	v_exp_f32_e32 v59, v58
	v_and_b32_e32 v58, 0xffff0000, v210
	v_mul_f32_e32 v60, 0xbfb8aa3b, v58
	v_exp_f32_e32 v62, v60
	v_add_f32_e32 v59, 1.0, v59
	v_rcp_f32_e32 v60, v59
	v_mul_f32_e32 v9, v92, v68
	v_add_f32_e32 v59, 1.0, v62
	v_rcp_f32_e32 v88, v59
	v_pk_mul_f32 v[8:9], v[60:61], v[8:9]
	v_mul_f32_e32 v59, v93, v68
	v_pk_mul_f32 v[8:9], v[8:9], v[8:9] op_sel:[0,1] op_sel_hi:[1,0]
	v_mov_b32_e32 v89, v231
	v_pk_mul_f32 v[58:59], v[88:89], v[58:59]
	v_lshlrev_b32_e32 v60, 16, v211
	v_pk_mul_f32 v[58:59], v[58:59], v[58:59] op_sel:[0,1] op_sel_hi:[1,0]
	v_mul_f32_e32 v9, 0xbfb8aa3b, v60
	v_and_b32_e32 v62, 0xffff0000, v211
	v_exp_f32_e32 v9, v9
	v_mul_f32_e32 v59, 0xbfb8aa3b, v62
	v_exp_f32_e32 v59, v59
	v_mul_f32_e32 v61, v94, v68
	v_add_f32_e32 v9, 1.0, v9
	v_rcp_f32_e32 v66, v9
	v_add_f32_e32 v9, 1.0, v59
	v_rcp_f32_e32 v90, v9
	v_bfe_u32 v9, v8, 16, 1
	v_pk_mul_f32 v[60:61], v[66:67], v[60:61]
	v_mul_f32_e32 v63, v95, v68
	v_add3_u32 v8, v8, v9, s28
	v_bfe_u32 v9, v58, 16, 1
	v_pk_mul_f32 v[60:61], v[60:61], v[60:61] op_sel:[0,1] op_sel_hi:[1,0]
	v_mov_b32_e32 v91, v233
	v_pk_mul_f32 v[62:63], v[90:91], v[62:63]
	v_lshrrev_b32_e32 v8, 16, v8
	v_add3_u32 v9, v58, v9, s28
	v_pk_mul_f32 v[62:63], v[62:63], v[62:63] op_sel:[0,1] op_sel_hi:[1,0]
	v_and_or_b32 v8, v9, s29, v8
	v_bfe_u32 v9, v60, 16, 1
	v_lshlrev_b64 v[6:7], 11, v[96:97]
	v_add3_u32 v9, v60, v9, s28
	v_bfe_u32 v58, v62, 16, 1
	v_lshl_add_u64 v[6:7], s[8:9], 0, v[6:7]
	v_lshrrev_b32_e32 v9, 16, v9
	v_add3_u32 v58, v62, v58, s28
	v_and_or_b32 v9, v58, s29, v9
	v_lshl_add_u64 v[58:59], v[6:7], 0, v[136:137]
	global_store_dwordx2 v[58:59], v[8:9], off
	v_mfma_f32_16x16x32_bf16 v[6:9], v[38:41], v[74:77], v[2:5]
	v_mul_f32_e32 v38, v80, v68
	v_cmp_ge_i32_e64 s[0:1], v153, v152
	s_waitcnt vmcnt(15)
	v_lshlrev_b32_e32 v39, 16, v212
	v_mul_f32_e32 v2, 0xbfb8aa3b, v39
	v_exp_f32_e32 v40, v2
	v_mfma_f32_16x16x32_bf16 v[2:5], v[42:45], v[18:21], 0
	v_and_b32_e32 v43, 0xffff0000, v212
	v_mul_f32_e32 v42, 0xbfb8aa3b, v43
	v_add_f32_e32 v40, 1.0, v40
	v_rcp_f32_e32 v41, v40
	v_exp_f32_e32 v44, v42
	v_lshlrev_b32_e32 v45, 16, v213
	v_mul_f32_e32 v42, v81, v68
	v_mfma_f32_16x16x32_bf16 v[18:21], v[30:33], v[18:21], 0
	v_cndmask_b32_e64 v2, 0, v2, s[0:1]
	v_bfe_u32 v30, v2, 16, 1
	v_add3_u32 v2, v2, v30, s28
	v_lshrrev_b32_e32 v2, 16, v2
	v_mov_b32_e32 v40, v234
	v_pk_mul_f32 v[38:39], v[40:41], v[38:39]
	v_mov_b32_e32 v40, v235
	v_pk_mul_f32 v[38:39], v[38:39], v[38:39] op_sel:[0,1] op_sel_hi:[1,0]
	v_and_b32_e32 v61, 0xffff0000, v213
	v_add_f32_e32 v39, 1.0, v44
	v_rcp_f32_e32 v41, v39
	v_mul_f32_e32 v39, 0xbfb8aa3b, v45
	v_exp_f32_e32 v39, v39
	v_mul_f32_e32 v44, v82, v68
	v_pk_mul_f32 v[40:41], v[40:41], v[42:43]
	v_mov_b32_e32 v42, v236
	v_add_f32_e32 v39, 1.0, v39
	v_rcp_f32_e32 v43, v39
	v_mul_f32_e32 v39, 0xbfb8aa3b, v61
	v_exp_f32_e32 v39, v39
	v_mul_f32_e32 v60, v83, v68
	v_pk_mul_f32 v[42:43], v[42:43], v[44:45]
	v_mov_b32_e32 v44, v237
	v_add_f32_e32 v39, 1.0, v39
	v_rcp_f32_e32 v45, v39
	v_pk_mul_f32 v[40:41], v[40:41], v[40:41] op_sel:[0,1] op_sel_hi:[1,0]
	v_bfe_u32 v39, v38, 16, 1
	v_add3_u32 v38, v38, v39, s28
	v_pk_mul_f32 v[44:45], v[44:45], v[60:61]
	v_bfe_u32 v39, v40, 16, 1
	v_pk_mul_f32 v[42:43], v[42:43], v[42:43] op_sel:[0,1] op_sel_hi:[1,0]
	v_lshrrev_b32_e32 v38, 16, v38
	v_add3_u32 v39, v40, v39, s28
	v_pk_mul_f32 v[44:45], v[44:45], v[44:45] op_sel:[0,1] op_sel_hi:[1,0]
	v_and_or_b32 v38, v39, s29, v38
	v_bfe_u32 v39, v42, 16, 1
	v_add3_u32 v39, v42, v39, s28
	v_bfe_u32 v40, v44, 16, 1
	v_lshrrev_b32_e32 v39, 16, v39
	v_add3_u32 v40, v44, v40, s28
	v_and_or_b32 v39, v40, s29, v39
	global_store_dwordx2 v[58:59], v[38:39], off offset:32
	v_cndmask_b32_e64 v18, v18, 0, vcc
	v_cmp_ge_i32_e32 vcc, v155, v152
	v_mul_f32_e32 v44, v15, v68
	v_cndmask_b32_e32 v3, 0, v3, vcc
	v_cmp_ge_i32_e32 vcc, v154, v152
	v_bfe_u32 v30, v3, 16, 1
	v_add3_u32 v3, v3, v30, s28
	v_cndmask_b32_e32 v19, 0, v19, vcc
	v_cmp_ge_i32_e32 vcc, v157, v152
	v_and_or_b32 v30, v3, s29, v2
	s_waitcnt vmcnt(15)
	v_and_b32_e32 v45, 0xffff0000, v214
	v_cndmask_b32_e32 v4, 0, v4, vcc
	v_cmp_ge_i32_e32 vcc, v156, v152
	v_bfe_u32 v2, v4, 16, 1
	v_add3_u32 v2, v4, v2, s28
	v_cndmask_b32_e32 v20, 0, v20, vcc
	v_cmp_ge_i32_e32 vcc, v159, v152
	v_lshrrev_b32_e32 v2, 16, v2
	v_lshlrev_b32_e32 v15, 16, v215
	v_cndmask_b32_e32 v5, 0, v5, vcc
	v_bfe_u32 v3, v5, 16, 1
	v_add3_u32 v3, v5, v3, s28
	v_and_or_b32 v31, v3, s29, v2
	v_bfe_u32 v2, v18, 16, 1
	v_cmp_ge_i32_e32 vcc, v158, v152
	v_add3_u32 v2, v18, v2, s28
	v_bfe_u32 v3, v19, 16, 1
	v_cndmask_b32_e32 v21, 0, v21, vcc
	v_lshrrev_b32_e32 v2, 16, v2
	v_add3_u32 v3, v19, v3, s28
	v_and_or_b32 v32, v3, s29, v2
	v_bfe_u32 v3, v21, 16, 1
	v_add3_u32 v4, v21, v3, s28
	v_lshlrev_b32_e32 v3, 16, v214
	v_mul_f32_e32 v5, 0xbfb8aa3b, v3
	v_exp_f32_e32 v5, v5
	v_bfe_u32 v2, v20, 16, 1
	v_add3_u32 v2, v20, v2, s28
	v_lshrrev_b32_e32 v2, 16, v2
	v_and_or_b32 v33, v4, s29, v2
	v_add_f32_e32 v4, 1.0, v5
	v_rcp_f32_e32 v5, v4
	v_mul_f32_e32 v2, v14, v68
	v_mul_f32_e32 v14, 0xbfb8aa3b, v45
	v_exp_f32_e32 v14, v14
	v_mov_b32_e32 v4, v240
	v_pk_mul_f32 v[2:3], v[4:5], v[2:3]
	v_mov_b32_e32 v4, v241
	v_pk_mul_f32 v[2:3], v[2:3], v[2:3] op_sel:[0,1] op_sel_hi:[1,0]
	v_mov_b32_e32 v38, v242
	v_add_f32_e32 v3, 1.0, v14
	v_rcp_f32_e32 v5, v3
	v_mul_f32_e32 v3, 0xbfb8aa3b, v15
	v_exp_f32_e32 v3, v3
	v_mul_f32_e32 v14, v16, v68
	v_pk_mul_f32 v[4:5], v[4:5], v[44:45]
	v_and_b32_e32 v45, 0xffff0000, v215
	v_add_f32_e32 v3, 1.0, v3
	v_rcp_f32_e32 v39, v3
	v_mul_f32_e32 v3, 0xbfb8aa3b, v45
	v_exp_f32_e32 v3, v3
	v_pk_mul_f32 v[4:5], v[4:5], v[4:5] op_sel:[0,1] op_sel_hi:[1,0]
	v_pk_mul_f32 v[14:15], v[38:39], v[14:15]
	v_mul_f32_e32 v44, v17, v68
	v_add_f32_e32 v3, 1.0, v3
	v_rcp_f32_e32 v39, v3
	v_bfe_u32 v3, v2, 16, 1
	v_mov_b32_e32 v38, v243
	v_add3_u32 v2, v2, v3, s28
	v_bfe_u32 v3, v4, 16, 1
	v_pk_mul_f32 v[14:15], v[14:15], v[14:15] op_sel:[0,1] op_sel_hi:[1,0]
	v_pk_mul_f32 v[16:17], v[38:39], v[44:45]
	v_lshrrev_b32_e32 v2, 16, v2
	v_add3_u32 v3, v4, v3, s28
	v_pk_mul_f32 v[16:17], v[16:17], v[16:17] op_sel:[0,1] op_sel_hi:[1,0]
	v_and_or_b32 v2, v3, s29, v2
	v_bfe_u32 v3, v14, 16, 1
	v_add3_u32 v3, v14, v3, s28
	v_bfe_u32 v4, v16, 16, 1
	v_lshrrev_b32_e32 v3, 16, v3
	v_add3_u32 v4, v16, v4, s28
	v_and_or_b32 v3, v4, s29, v3
	global_store_dwordx2 v[58:59], v[2:3], off offset:64
	v_mfma_f32_16x16x32_bf16 v[14:17], v[54:57], v[30:33], v[22:25]
	s_nop 1
	s_waitcnt vmcnt(15)
	v_lshlrev_b32_e32 v23, 16, v216
	v_mul_f32_e32 v2, 0xbfb8aa3b, v23
	v_exp_f32_e32 v22, v2
	v_mfma_f32_16x16x32_bf16 v[2:5], v[50:53], v[30:33], v[26:29]
	v_mul_f32_e32 v24, v10, v68
	v_add_f32_e32 v10, 1.0, v22
	s_nop 0
	v_and_b32_e32 v27, 0xffff0000, v216
	v_rcp_f32_e32 v25, v10
	v_mul_f32_e32 v10, 0xbfb8aa3b, v27
	v_exp_f32_e32 v26, v10
	v_mul_f32_e32 v10, v11, v68
	v_and_b32_e32 v29, 0xffff0000, v217
	v_mfma_f32_16x16x32_bf16 v[18:21], v[70:73], v[30:33], v[46:49]
	v_add_f32_e32 v11, 1.0, v26
	v_rcp_f32_e32 v11, v11
	v_mov_b32_e32 v22, v244
	v_pk_mul_f32 v[22:23], v[24:25], v[22:23]
	v_lshlrev_b32_e32 v25, 16, v217
	v_pk_mul_f32 v[22:23], v[22:23], v[22:23] op_sel:[0,1] op_sel_hi:[1,0]
	v_mov_b32_e32 v26, v245
	v_mul_f32_e32 v23, 0xbfb8aa3b, v25
	v_exp_f32_e32 v23, v23
	v_pk_mul_f32 v[10:11], v[10:11], v[26:27]
	v_mul_f32_e32 v26, v12, v68
	v_pk_mul_f32 v[10:11], v[10:11], v[10:11] op_sel:[0,1] op_sel_hi:[1,0]
	v_mov_b32_e32 v24, v246
	v_add_f32_e32 v11, 1.0, v23
	v_rcp_f32_e32 v27, v11
	v_mul_f32_e32 v11, 0xbfb8aa3b, v29
	v_exp_f32_e32 v11, v11
	v_mov_b32_e32 v28, v247
	v_pk_mul_f32 v[24:25], v[26:27], v[24:25]
	v_mul_f32_e32 v26, v13, v68
	v_add_f32_e32 v11, 1.0, v11
	v_rcp_f32_e32 v27, v11
	v_bfe_u32 v11, v22, 16, 1
	v_add3_u32 v11, v22, v11, s28
	v_lshrrev_b32_e32 v11, 16, v11
	v_pk_mul_f32 v[12:13], v[26:27], v[28:29]
	v_or_b32_e32 v26, s31, v152
	v_pk_mul_f32 v[12:13], v[12:13], v[12:13] op_sel:[0,1] op_sel_hi:[1,0]
	v_pk_mul_f32 v[24:25], v[24:25], v[24:25] op_sel:[0,1] op_sel_hi:[1,0]
	v_bfe_u32 v13, v10, 16, 1
	v_add3_u32 v10, v10, v13, s28
	v_and_or_b32 v22, v10, s29, v11
	v_mad_i64_i32 v[10:11], s[0:1], v26, s27, v[138:139]
	v_lshl_add_u64 v[10:11], v[10:11], 0, s[18:19]
	v_lshl_add_u64 v[10:11], v[10:11], 0, v[136:137]
	v_bfe_u32 v13, v24, 16, 1
	v_add3_u32 v13, v24, v13, s28
	v_bfe_u32 v23, v12, 16, 1
	v_lshrrev_b32_e32 v13, 16, v13
	v_add3_u32 v12, v12, v23, s28
	v_and_or_b32 v23, v12, s29, v13
	global_store_dwordx2 v[58:59], v[22:23], off offset:96
	v_mul_f32_e32 v27, v19, v19
	v_fmac_f32_e32 v27, v18, v18
	v_fmac_f32_e32 v27, v20, v20
	v_fmac_f32_e32 v27, v21, v21
	v_fmac_f32_e32 v27, v14, v14
	v_fmac_f32_e32 v27, v15, v15
	v_fmac_f32_e32 v27, v16, v16
	v_mfma_f32_16x16x32_bf16 v[6:9], v[34:37], v[30:33], v[6:9]
	v_fmac_f32_e32 v27, v17, v17
	v_pk_mul_f32 v[30:31], v[2:3], v[2:3]
	v_pk_mul_f32 v[12:13], v[4:5], v[4:5]
	v_add_f32_e32 v27, v27, v30
	v_add_f32_e32 v27, v31, v27
	v_add_f32_e32 v12, v12, v27
	v_add_f32_e32 v27, v13, v12
	s_nop 0
	v_pk_mul_f32 v[30:31], v[6:7], v[6:7]
	v_pk_mul_f32 v[12:13], v[8:9], v[8:9]
	v_add_f32_e32 v27, v27, v30
	v_add_f32_e32 v27, v31, v27
	v_add_f32_e32 v12, v12, v27
	v_add_f32_e32 v12, v13, v12
	ds_bpermute_b32 v13, v170, v12
	v_ashrrev_i32_e32 v27, 31, v26
	s_waitcnt lgkmcnt(0)
	v_add_f32_e32 v12, v12, v13
	ds_bpermute_b32 v13, v171, v12
	s_waitcnt lgkmcnt(0)
	v_add_f32_e32 v12, v12, v13
	v_fmamk_f32 v12, v12, 0x3c800000, v150
	v_mul_f32_e32 v13, 0x4b800000, v12
	v_cmp_gt_f32_e32 vcc, s30, v12
	v_mov_b32_e32 v33, v230
	v_cndmask_b32_e32 v12, v12, v13, vcc
	v_rsq_f32_e32 v12, v12
	s_nop 0
	v_mul_f32_e32 v13, 0x45800000, v12
	v_cndmask_b32_e32 v34, v12, v13, vcc
	v_lshlrev_b64 v[12:13], 11, v[26:27]
	s_waitcnt vmcnt(15)
	v_lshlrev_b32_e32 v26, 16, v218
	v_mul_f32_e32 v27, v18, v34
	v_mul_f32_e32 v18, 0xbfb8aa3b, v26
	v_exp_f32_e32 v32, v18
	v_and_b32_e32 v18, 0xffff0000, v218
	v_mul_f32_e32 v28, 0xbfb8aa3b, v18
	v_exp_f32_e32 v28, v28
	v_add_f32_e32 v32, 1.0, v32
	v_rcp_f32_e32 v32, v32
	v_mul_f32_e32 v19, v19, v34
	v_add_f32_e32 v22, 1.0, v28
	v_rcp_f32_e32 v22, v22
	v_pk_mul_f32 v[26:27], v[32:33], v[26:27]
	v_mul_f32_e32 v21, v21, v34
	v_pk_mul_f32 v[26:27], v[26:27], v[26:27] op_sel:[0,1] op_sel_hi:[1,0]
	v_mov_b32_e32 v23, v231
	v_pk_mul_f32 v[18:19], v[22:23], v[18:19]
	v_lshlrev_b32_e32 v22, 16, v219
	v_pk_mul_f32 v[18:19], v[18:19], v[18:19] op_sel:[0,1] op_sel_hi:[1,0]
	v_mul_f32_e32 v23, v20, v34
	v_mul_f32_e32 v19, 0xbfb8aa3b, v22
	v_and_b32_e32 v20, 0xffff0000, v219
	v_exp_f32_e32 v19, v19
	v_mul_f32_e32 v27, 0xbfb8aa3b, v20
	v_exp_f32_e32 v27, v27
	v_mov_b32_e32 v29, v232
	v_add_f32_e32 v19, 1.0, v19
	v_rcp_f32_e32 v28, v19
	v_add_f32_e32 v19, 1.0, v27
	v_rcp_f32_e32 v24, v19
	v_bfe_u32 v19, v26, 16, 1
	v_pk_mul_f32 v[22:23], v[28:29], v[22:23]
	v_add3_u32 v19, v26, v19, s28
	v_mov_b32_e32 v25, v233
	v_pk_mul_f32 v[20:21], v[24:25], v[20:21]
	v_pk_mul_f32 v[22:23], v[22:23], v[22:23] op_sel:[0,1] op_sel_hi:[1,0]
	v_pk_mul_f32 v[20:21], v[20:21], v[20:21] op_sel:[0,1] op_sel_hi:[1,0]
	v_lshrrev_b32_e32 v19, 16, v19
	v_bfe_u32 v21, v18, 16, 1
	v_add3_u32 v18, v18, v21, s28
	v_and_or_b32 v18, v18, s29, v19
	v_bfe_u32 v19, v22, 16, 1
	v_add3_u32 v19, v22, v19, s28
	v_bfe_u32 v21, v20, 16, 1
	v_lshl_add_u64 v[12:13], s[8:9], 0, v[12:13]
	v_lshrrev_b32_e32 v19, 16, v19
	v_add3_u32 v20, v20, v21, s28
	v_and_or_b32 v19, v20, s29, v19
	v_lshl_add_u64 v[12:13], v[12:13], 0, v[136:137]
	global_store_dwordx2 v[12:13], v[18:19], off
	s_waitcnt vmcnt(15)
	v_lshlrev_b32_e32 v23, 16, v220
	v_mul_f32_e32 v22, 0xbfb8aa3b, v23
	v_exp_f32_e32 v24, v22
	v_mul_f32_e32 v22, v14, v34
	v_and_b32_e32 v27, 0xffff0000, v220
	v_mul_f32_e32 v26, v15, v34
	v_add_f32_e32 v14, 1.0, v24
	v_rcp_f32_e32 v25, v14
	v_mul_f32_e32 v14, 0xbfb8aa3b, v27
	v_exp_f32_e32 v14, v14
	v_mov_b32_e32 v24, v234
	v_add_f32_e32 v14, 1.0, v14
	v_pk_mul_f32 v[22:23], v[24:25], v[22:23]
	v_rcp_f32_e32 v15, v14
	v_lshlrev_b32_e32 v25, 16, v221
	v_mul_f32_e32 v14, 0xbfb8aa3b, v25
	v_exp_f32_e32 v18, v14
	v_mov_b32_e32 v14, v235
	v_pk_mul_f32 v[14:15], v[14:15], v[26:27]
	v_and_b32_e32 v27, 0xffff0000, v221
	v_pk_mul_f32 v[14:15], v[14:15], v[14:15] op_sel:[0,1] op_sel_hi:[1,0]
	v_mul_f32_e32 v24, v16, v34
	v_add_f32_e32 v15, 1.0, v18
	v_rcp_f32_e32 v19, v15
	v_mul_f32_e32 v15, 0xbfb8aa3b, v27
	v_exp_f32_e32 v15, v15
	v_mov_b32_e32 v18, v236
	v_pk_mul_f32 v[18:19], v[18:19], v[24:25]
	v_mov_b32_e32 v24, v237
	v_add_f32_e32 v15, 1.0, v15
	v_rcp_f32_e32 v25, v15
	v_mul_f32_e32 v26, v17, v34
	v_pk_mul_f32 v[22:23], v[22:23], v[22:23] op_sel:[0,1] op_sel_hi:[1,0]
	v_pk_mul_f32 v[16:17], v[24:25], v[26:27]
	v_bfe_u32 v15, v22, 16, 1
	v_pk_mul_f32 v[16:17], v[16:17], v[16:17] op_sel:[0,1] op_sel_hi:[1,0]
	v_add3_u32 v15, v22, v15, s28
	v_bfe_u32 v17, v14, 16, 1
	v_pk_mul_f32 v[18:19], v[18:19], v[18:19] op_sel:[0,1] op_sel_hi:[1,0]
	v_lshrrev_b32_e32 v15, 16, v15
	v_add3_u32 v14, v14, v17, s28
	v_and_or_b32 v14, v14, s29, v15
	v_bfe_u32 v15, v18, 16, 1
	v_add3_u32 v15, v18, v15, s28
	v_bfe_u32 v17, v16, 16, 1
	v_lshrrev_b32_e32 v15, 16, v15
	v_add3_u32 v16, v16, v17, s28
	v_and_or_b32 v15, v16, s29, v15
	global_store_dwordx2 v[12:13], v[14:15], off offset:32
	s_nop 0
	v_mul_f32_e32 v24, v3, v34
	s_waitcnt vmcnt(15)
	v_lshlrev_b32_e32 v19, 16, v222
	v_mul_f32_e32 v18, 0xbfb8aa3b, v19
	v_exp_f32_e32 v22, v18
	v_mul_f32_e32 v18, v2, v34
	v_and_b32_e32 v25, 0xffff0000, v222
	v_mul_f32_e32 v20, v5, v34
	v_add_f32_e32 v2, 1.0, v22
	v_rcp_f32_e32 v23, v2
	v_mul_f32_e32 v2, 0xbfb8aa3b, v25
	v_exp_f32_e32 v2, v2
	v_mov_b32_e32 v22, v240
	v_add_f32_e32 v2, 1.0, v2
	v_pk_mul_f32 v[18:19], v[22:23], v[18:19]
	v_rcp_f32_e32 v3, v2
	v_lshlrev_b32_e32 v23, 16, v223
	v_mul_f32_e32 v2, 0xbfb8aa3b, v23
	v_exp_f32_e32 v14, v2
	v_mov_b32_e32 v2, v241
	v_pk_mul_f32 v[2:3], v[2:3], v[24:25]
	v_and_b32_e32 v21, 0xffff0000, v223
	v_pk_mul_f32 v[2:3], v[2:3], v[2:3] op_sel:[0,1] op_sel_hi:[1,0]
	v_mul_f32_e32 v22, v4, v34
	v_add_f32_e32 v3, 1.0, v14
	v_rcp_f32_e32 v15, v3
	v_mul_f32_e32 v3, 0xbfb8aa3b, v21
	v_exp_f32_e32 v3, v3
	v_mov_b32_e32 v14, v242
	v_pk_mul_f32 v[14:15], v[14:15], v[22:23]
	v_mov_b32_e32 v22, v243
	v_add_f32_e32 v3, 1.0, v3
	v_rcp_f32_e32 v23, v3
	v_pk_mul_f32 v[18:19], v[18:19], v[18:19] op_sel:[0,1] op_sel_hi:[1,0]
	v_pk_mul_f32 v[14:15], v[14:15], v[14:15] op_sel:[0,1] op_sel_hi:[1,0]
	v_bfe_u32 v3, v18, 16, 1
	v_pk_mul_f32 v[4:5], v[22:23], v[20:21]
	v_add3_u32 v3, v18, v3, s28
	v_pk_mul_f32 v[4:5], v[4:5], v[4:5] op_sel:[0,1] op_sel_hi:[1,0]
	v_lshrrev_b32_e32 v3, 16, v3
	v_bfe_u32 v5, v2, 16, 1
	v_add3_u32 v2, v2, v5, s28
	v_and_or_b32 v2, v2, s29, v3
	v_bfe_u32 v3, v14, 16, 1
	v_add3_u32 v3, v14, v3, s28
	v_bfe_u32 v5, v4, 16, 1
	v_lshrrev_b32_e32 v3, 16, v3
	v_add3_u32 v4, v4, v5, s28
	v_and_or_b32 v3, v4, s29, v3
	global_store_dwordx2 v[12:13], v[2:3], off offset:64
	s_waitcnt vmcnt(15)
	v_lshlrev_b32_e32 v15, 16, v224
	v_mul_f32_e32 v14, 0xbfb8aa3b, v15
	v_exp_f32_e32 v14, v14
	v_and_b32_e32 v19, 0xffff0000, v224
	v_mul_f32_e32 v16, v6, v34
	v_add_f32_e32 v6, 1.0, v14
	v_rcp_f32_e32 v17, v6
	v_mul_f32_e32 v6, v7, v34
	v_mov_b32_e32 v14, v244
	v_mul_f32_e32 v2, 0xbfb8aa3b, v19
	v_exp_f32_e32 v2, v2
	v_pk_mul_f32 v[14:15], v[16:17], v[14:15]
	v_lshlrev_b32_e32 v17, 16, v225
	v_mov_b32_e32 v18, v245
	v_add_f32_e32 v2, 1.0, v2
	v_rcp_f32_e32 v7, v2
	v_mul_f32_e32 v2, 0xbfb8aa3b, v17
	v_exp_f32_e32 v10, v2
	v_and_b32_e32 v11, 0xffff0000, v225
	v_pk_mul_f32 v[2:3], v[6:7], v[18:19]
	v_mul_f32_e32 v6, v8, v34
	v_pk_mul_f32 v[2:3], v[2:3], v[2:3] op_sel:[0,1] op_sel_hi:[1,0]
	v_mov_b32_e32 v16, v246
	v_add_f32_e32 v3, 1.0, v10
	v_rcp_f32_e32 v7, v3
	v_mul_f32_e32 v3, 0xbfb8aa3b, v11
	v_exp_f32_e32 v3, v3
	v_mov_b32_e32 v10, v247
	v_pk_mul_f32 v[6:7], v[6:7], v[16:17]
	v_mul_f32_e32 v16, v9, v34
	v_add_f32_e32 v3, 1.0, v3
	v_rcp_f32_e32 v17, v3
	v_pk_mul_f32 v[14:15], v[14:15], v[14:15] op_sel:[0,1] op_sel_hi:[1,0]
	v_pk_mul_f32 v[6:7], v[6:7], v[6:7] op_sel:[0,1] op_sel_hi:[1,0]
	v_bfe_u32 v3, v14, 16, 1
	v_pk_mul_f32 v[4:5], v[16:17], v[10:11]
	v_add3_u32 v3, v14, v3, s28
	v_pk_mul_f32 v[4:5], v[4:5], v[4:5] op_sel:[0,1] op_sel_hi:[1,0]
	v_lshrrev_b32_e32 v3, 16, v3
	v_bfe_u32 v5, v2, 16, 1
	v_add3_u32 v2, v2, v5, s28
	v_and_or_b32 v2, v2, s29, v3
	v_bfe_u32 v3, v6, 16, 1
	v_add3_u32 v3, v6, v3, s28
	v_bfe_u32 v5, v4, 16, 1
	v_lshrrev_b32_e32 v3, 16, v3
	v_add3_u32 v4, v4, v5, s28
	v_and_or_b32 v3, v4, s29, v3
	global_store_dwordx2 v[12:13], v[2:3], off offset:96
	s_waitcnt lgkmcnt(0)
	s_cbranch_scc0 .LBB0_1015

.LBB0_2235:
	s_and_b32 s0, s3, 3
	v_add_u32_e32 v3, s33, v2
	v_mov_b64_e32 v[138:139], s[16:17]
	v_mad_i64_i32 v[52:53], s[4:5], v3, s29, v[138:139]
	s_lshl_b32 s20, s0, 7
	s_mov_b32 s21, s15
	v_lshl_add_u64 v[4:5], v[52:53], 0, s[20:21]
	global_load_dwordx4 v[20:23], v[4:5], off offset:512
	global_load_dwordx4 v[24:27], v[4:5], off offset:528
	global_load_dwordx4 v[28:31], v[4:5], off offset:544
	global_load_dwordx4 v[32:35], v[4:5], off offset:560
	global_load_dwordx4 v[36:39], v[4:5], off offset:576
	global_load_dwordx4 v[40:43], v[4:5], off offset:592
	global_load_dwordx4 v[44:47], v[4:5], off offset:608
	global_load_dwordx4 v[48:51], v[4:5], off offset:624
	s_lshl_b32 s14, s0, 6
	v_lshl_add_u32 v71, v2, 1, s19
	s_cmp_gt_i32 s35, 3
	v_ashrrev_i32_e32 v70, 4, v2
	s_cselect_b32 s1, 0x107, 3
	v_ashrrev_i32_e32 v3, 31, v2
	v_add_u32_e32 v54, 0x400, v2
	v_add_u32_e32 v56, 0x440, v2
	v_add_u32_e32 v58, 0x480, v2
	v_add_u32_e32 v60, 0x4c0, v2
	v_add_u32_e32 v62, 0x500, v2
	v_add_u32_e32 v64, 0x540, v2
	v_add_u32_e32 v66, 0x580, v2
	v_add_u32_e32 v68, 0x5c0, v2
	v_add_u32_e32 v18, 0x600, v2
	v_add_u32_e32 v14, 0x640, v2
	v_add_u32_e32 v16, 0x680, v2
	v_add_u32_e32 v12, 0x6c0, v2
	v_add_u32_e32 v10, 0x700, v2
	v_add_u32_e32 v8, 0x740, v2
	v_add_u32_e32 v4, 0x780, v2
	v_add_u32_e32 v6, 0x7c0, v2
	s_sub_i32 s37, s1, s35
	s_lshl_b32 s1, s2, 3
	v_lshlrev_b32_e32 v120, 2, v70
	v_and_b32_e32 v140, 15, v2
	v_ashrrev_i32_e32 v55, 31, v54
	v_ashrrev_i32_e32 v57, 31, v56
	v_ashrrev_i32_e32 v59, 31, v58
	v_ashrrev_i32_e32 v61, 31, v60
	v_ashrrev_i32_e32 v63, 31, v62
	v_ashrrev_i32_e32 v65, 31, v64
	v_ashrrev_i32_e32 v67, 31, v66
	v_ashrrev_i32_e32 v69, 31, v68
	v_ashrrev_i32_e32 v19, 31, v18
	v_ashrrev_i32_e32 v15, 31, v14
	v_ashrrev_i32_e32 v17, 31, v16
	v_ashrrev_i32_e32 v13, 31, v12
	v_ashrrev_i32_e32 v11, 31, v10
	v_ashrrev_i32_e32 v9, 31, v8
	v_ashrrev_i32_e32 v5, 31, v4
	v_ashrrev_i32_e32 v7, 31, v6
	s_or_b32 s38, s1, s0
	s_ashr_i32 s36, s35, 31
	v_lshlrev_b64 v[94:95], 7, v[2:3]
	v_lshl_add_u64 v[110:111], v[52:53], 0, s[14:15]
	v_lshl_add_u32 v142, v2, 6, s19
	v_ashrrev_i32_e32 v121, 31, v120
	s_waitcnt vmcnt(7)
	ds_write_b16 v71, v20 offset:8192
	ds_write_b16_d16_hi v71, v20 offset:8320
	ds_write_b16 v71, v21 offset:8448
	ds_write_b16_d16_hi v71, v21 offset:8576
	ds_write_b16 v71, v22 offset:8704
	ds_write_b16_d16_hi v71, v22 offset:8832
	ds_write_b16 v71, v23 offset:8960
	ds_write_b16_d16_hi v71, v23 offset:9088
	s_waitcnt vmcnt(6)
	ds_write_b16 v71, v24 offset:9216
	ds_write_b16_d16_hi v71, v24 offset:9344
	ds_write_b16 v71, v25 offset:9472
	ds_write_b16_d16_hi v71, v25 offset:9600
	ds_write_b16 v71, v26 offset:9728
	ds_write_b16_d16_hi v71, v26 offset:9856
	ds_write_b16 v71, v27 offset:9984
	ds_write_b16_d16_hi v71, v27 offset:10112
	s_waitcnt vmcnt(5)
	ds_write_b16 v71, v28 offset:10240
	ds_write_b16_d16_hi v71, v28 offset:10368
	ds_write_b16 v71, v29 offset:10496
	ds_write_b16_d16_hi v71, v29 offset:10624
	ds_write_b16 v71, v30 offset:10752
	ds_write_b16_d16_hi v71, v30 offset:10880
	ds_write_b16 v71, v31 offset:11008
	ds_write_b16_d16_hi v71, v31 offset:11136
	s_waitcnt vmcnt(4)
	ds_write_b16 v71, v32 offset:11264
	ds_write_b16_d16_hi v71, v32 offset:11392
	ds_write_b16 v71, v33 offset:11520
	ds_write_b16_d16_hi v71, v33 offset:11648
	ds_write_b16 v71, v34 offset:11776
	ds_write_b16_d16_hi v71, v34 offset:11904
	ds_write_b16 v71, v35 offset:12032
	ds_write_b16_d16_hi v71, v35 offset:12160
	s_waitcnt vmcnt(3)
	ds_write_b16 v71, v36 offset:12288
	ds_write_b16_d16_hi v71, v36 offset:12416
	ds_write_b16 v71, v37 offset:12544
	ds_write_b16_d16_hi v71, v37 offset:12672
	ds_write_b16 v71, v38 offset:12800
	ds_write_b16_d16_hi v71, v38 offset:12928
	ds_write_b16 v71, v39 offset:13056
	ds_write_b16_d16_hi v71, v39 offset:13184
	s_waitcnt vmcnt(2)
	ds_write_b16 v71, v40 offset:13312
	ds_write_b16_d16_hi v71, v40 offset:13440
	ds_write_b16 v71, v41 offset:13568
	ds_write_b16_d16_hi v71, v41 offset:13696
	ds_write_b16 v71, v42 offset:13824
	ds_write_b16_d16_hi v71, v42 offset:13952
	ds_write_b16 v71, v43 offset:14080
	ds_write_b16_d16_hi v71, v43 offset:14208
	s_waitcnt vmcnt(1)
	ds_write_b16 v71, v44 offset:14336
	ds_write_b16_d16_hi v71, v44 offset:14464
	ds_write_b16 v71, v45 offset:14592
	ds_write_b16_d16_hi v71, v45 offset:14720
	ds_write_b16 v71, v46 offset:14848
	ds_write_b16_d16_hi v71, v46 offset:14976
	ds_write_b16 v71, v47 offset:15104
	ds_write_b16_d16_hi v71, v47 offset:15232
	s_waitcnt vmcnt(0)
	ds_write_b16 v71, v48 offset:15360
	ds_write_b16_d16_hi v71, v48 offset:15488
	ds_write_b16 v71, v49 offset:15616
	ds_write_b16_d16_hi v71, v49 offset:15744
	ds_write_b16 v71, v50 offset:15872
	ds_write_b16_d16_hi v71, v50 offset:16000
	ds_write_b16 v71, v51 offset:16128
	ds_write_b16_d16_hi v71, v51 offset:16256
	v_and_b32_e32 v49, -16, v2
	v_lshlrev_b32_e32 v20, 3, v70
	v_add_u32_e32 v134, s19, v49
	v_sub_u32_e32 v48, v134, v20
	s_mul_i32 s0, s38, 0x104
	s_mul_hi_i32 s1, s38, 0x104
	s_add_u32 s0, s0, s35
	s_addc_u32 s1, s1, s36
	s_lshl_b64 s[0:1], s[0:1], 13
	s_add_u32 s4, s23, s0
	s_addc_u32 s5, s24, s1
	v_lshlrev_b64 v[96:97], 2, v[2:3]
	v_lshl_add_u64 v[2:3], s[4:5], 0, v[96:97]
	global_load_dword v26, v[2:3], off
	global_load_dword v27, v[2:3], off offset:256
	global_load_dword v28, v[2:3], off offset:512
	global_load_dword v29, v[2:3], off offset:768
	global_load_dword v30, v[2:3], off offset:1024
	global_load_dword v31, v[2:3], off offset:1280
	global_load_dword v32, v[2:3], off offset:1536
	global_load_dword v33, v[2:3], off offset:1792
	global_load_dword v38, v[2:3], off offset:2048
	global_load_dword v39, v[2:3], off offset:2304
	global_load_dword v40, v[2:3], off offset:2560
	global_load_dword v41, v[2:3], off offset:2816
	global_load_dword v42, v[2:3], off offset:3072
	global_load_dword v43, v[2:3], off offset:3328
	global_load_dword v44, v[2:3], off offset:3584
	v_lshlrev_b64 v[98:99], 2, v[54:55]
	global_load_dword v45, v[2:3], off offset:3840
	v_lshlrev_b64 v[100:101], 2, v[56:57]
	v_lshlrev_b64 v[130:131], 2, v[4:5]
	v_lshl_add_u64 v[4:5], s[4:5], 0, v[98:99]
	v_lshlrev_b64 v[128:129], 2, v[8:9]
	v_lshl_add_u64 v[8:9], s[4:5], 0, v[100:101]
	global_load_dword v50, v[4:5], off
	global_load_dword v51, v[8:9], off
	v_lshlrev_b64 v[102:103], 2, v[58:59]
	v_lshlrev_b64 v[104:105], 2, v[60:61]
	v_lshlrev_b64 v[126:127], 2, v[10:11]
	v_lshl_add_u64 v[10:11], s[4:5], 0, v[102:103]
	v_lshlrev_b64 v[124:125], 2, v[12:13]
	v_lshl_add_u64 v[12:13], s[4:5], 0, v[104:105]
	global_load_dword v52, v[10:11], off
	global_load_dword v53, v[12:13], off
	v_lshlrev_b64 v[106:107], 2, v[62:63]
	v_lshlrev_b64 v[112:113], 2, v[66:67]
	v_lshlrev_b64 v[108:109], 2, v[64:65]
	v_lshlrev_b64 v[114:115], 2, v[68:69]
	v_lshlrev_b64 v[116:117], 2, v[18:19]
	v_lshlrev_b64 v[118:119], 2, v[14:15]
	v_lshlrev_b64 v[122:123], 2, v[16:17]
	v_lshl_add_u64 v[14:15], s[4:5], 0, v[106:107]
	v_lshl_add_u64 v[16:17], s[4:5], 0, v[112:113]
	v_lshl_add_u64 v[2:3], s[4:5], 0, v[108:109]
	v_lshl_add_u64 v[4:5], s[4:5], 0, v[114:115]
	v_lshl_add_u64 v[18:19], s[4:5], 0, v[116:117]
	v_lshl_add_u64 v[20:21], s[4:5], 0, v[118:119]
	v_lshl_add_u64 v[8:9], s[4:5], 0, v[122:123]
	v_lshl_add_u64 v[22:23], s[4:5], 0, v[124:125]
	v_lshl_add_u64 v[10:11], s[4:5], 0, v[126:127]
	v_lshl_add_u64 v[24:25], s[4:5], 0, v[128:129]
	v_lshl_add_u64 v[12:13], s[4:5], 0, v[130:131]
	global_load_dword v14, v[14:15], off
	s_nop 0
	global_load_dword v15, v[2:3], off
	s_nop 0
	global_load_dword v16, v[16:17], off
	s_nop 0
	global_load_dword v17, v[4:5], off
	global_load_dword v54, v[18:19], off
	global_load_dword v55, v[20:21], off
	global_load_dword v56, v[8:9], off
	global_load_dword v57, v[22:23], off
	global_load_dword v58, v[10:11], off
	global_load_dword v59, v[24:25], off
	global_load_dword v60, v[12:13], off
	v_lshlrev_b64 v[132:133], 2, v[6:7]
	v_lshl_add_u64 v[6:7], s[4:5], 0, v[132:133]
	s_add_u32 s0, s25, s0
	s_addc_u32 s1, s26, s1
	v_lshl_add_u64 v[46:47], s[0:1], 0, v[94:95]
	v_add_u32_e32 v161, 16, v120
	v_cmp_gt_i32_e64 s[10:11], v120, v140
	v_cmp_le_i32_e32 vcc, v161, v140
	v_add_u32_e32 v162, 17, v120
	v_cmp_le_i32_e64 s[0:1], v162, v140
	v_or_b32_e32 v164, 2, v120
	v_add_u32_e32 v163, 18, v120
	v_or_b32_e32 v166, 3, v120
	v_add_u32_e32 v165, 19, v120
	v_or_b32_e32 v168, 16, v140
	v_cmp_lt_i32_e64 s[8:9], v120, v168
	v_or_b32_e32 v160, 32, v140
	v_cmp_lt_i32_e64 s[6:7], v120, v160
	v_lshl_add_u32 v173, v160, 6, v134
	v_add_u32_e32 v167, 48, v120
	v_or_b32_e32 v169, 1, v120
	s_waitcnt vmcnt(30)
	v_bfe_u32 v2, v26, 16, 1
	v_add3_u32 v2, v26, v2, s30
	global_load_dword v26, v[6:7], off
	global_load_dwordx4 v[22:25], v[46:47], off offset:16
	global_load_dwordx4 v[34:37], v[46:47], off
	global_load_dwordx4 v[18:21], v[110:111], off
	s_waitcnt vmcnt(32)
	v_bfe_u32 v4, v28, 16, 1
	s_waitcnt vmcnt(30)
	v_bfe_u32 v8, v30, 16, 1
	v_bfe_u32 v3, v27, 16, 1
	s_waitcnt vmcnt(26)
	v_bfe_u32 v6, v38, 16, 1
	v_add3_u32 v6, v38, v6, s30
	s_waitcnt vmcnt(25)
	v_bfe_u32 v7, v39, 16, 1
	v_bfe_u32 v5, v29, 16, 1
	v_bfe_u32 v9, v31, 16, 1
	v_add3_u32 v4, v28, v4, s30
	v_add3_u32 v8, v30, v8, s30
	v_lshrrev_b32_e32 v6, 16, v6
	v_add3_u32 v7, v39, v7, s30
	v_add3_u32 v3, v27, v3, s30
	v_add3_u32 v5, v29, v5, s30
	v_add3_u32 v9, v31, v9, s30
	v_lshrrev_b32_e32 v2, 16, v2
	v_lshrrev_b32_e32 v4, 16, v4
	v_lshrrev_b32_e32 v8, 16, v8
	v_and_or_b32 v6, v7, s31, v6
	s_waitcnt vmcnt(24)
	v_bfe_u32 v7, v40, 16, 1
	v_and_or_b32 v2, v3, s31, v2
	v_and_or_b32 v3, v5, s31, v4
	v_and_or_b32 v4, v9, s31, v8
	v_add3_u32 v7, v40, v7, s30
	s_waitcnt vmcnt(23)
	v_bfe_u32 v8, v41, 16, 1
	v_lshrrev_b32_e32 v7, 16, v7
	v_add3_u32 v8, v41, v8, s30
	v_and_or_b32 v7, v8, s31, v7
	s_waitcnt vmcnt(22)
	v_bfe_u32 v8, v42, 16, 1
	v_bfe_u32 v10, v32, 16, 1
	v_add3_u32 v8, v42, v8, s30
	s_waitcnt vmcnt(21)
	v_bfe_u32 v9, v43, 16, 1
	v_add3_u32 v10, v32, v10, s30
	v_bfe_u32 v5, v33, 16, 1
	v_lshrrev_b32_e32 v8, 16, v8
	v_add3_u32 v9, v43, v9, s30
	v_lshrrev_b32_e32 v10, 16, v10
	v_add3_u32 v5, v33, v5, s30
	v_and_or_b32 v8, v9, s31, v8
	s_waitcnt vmcnt(20)
	v_bfe_u32 v9, v44, 16, 1
	v_and_or_b32 v5, v5, s31, v10
	v_add3_u32 v9, v44, v9, s30
	s_waitcnt vmcnt(19)
	v_bfe_u32 v10, v45, 16, 1
	v_lshrrev_b32_e32 v9, 16, v9
	v_add3_u32 v10, v45, v10, s30
	v_and_or_b32 v9, v10, s31, v9
	s_waitcnt vmcnt(18)
	v_bfe_u32 v10, v50, 16, 1
	v_add3_u32 v10, v50, v10, s30
	s_waitcnt vmcnt(17)
	v_bfe_u32 v11, v51, 16, 1
	v_lshrrev_b32_e32 v10, 16, v10
	v_add3_u32 v11, v51, v11, s30
	v_and_or_b32 v10, v11, s31, v10
	s_waitcnt vmcnt(16)
	v_bfe_u32 v11, v52, 16, 1
	v_add3_u32 v11, v52, v11, s30
	s_waitcnt vmcnt(15)
	v_bfe_u32 v12, v53, 16, 1
	v_lshrrev_b32_e32 v11, 16, v11
	v_add3_u32 v12, v53, v12, s30
	v_and_or_b32 v11, v12, s31, v11
	s_waitcnt vmcnt(14)
	v_bfe_u32 v12, v14, 16, 1
	v_add3_u32 v12, v14, v12, s30
	s_waitcnt vmcnt(13)
	v_bfe_u32 v13, v15, 16, 1
	v_lshrrev_b32_e32 v12, 16, v12
	v_add3_u32 v13, v15, v13, s30
	v_and_or_b32 v12, v13, s31, v12
	s_waitcnt vmcnt(12)
	v_bfe_u32 v13, v16, 16, 1
	v_add3_u32 v13, v16, v13, s30
	s_waitcnt vmcnt(11)
	v_bfe_u32 v14, v17, 16, 1
	global_load_dwordx4 v[38:41], v[110:111], off offset:256
	v_lshrrev_b32_e32 v13, 16, v13
	v_add3_u32 v14, v17, v14, s30
	v_and_or_b32 v13, v14, s31, v13
	s_waitcnt vmcnt(11)
	v_bfe_u32 v14, v54, 16, 1
	v_add3_u32 v14, v54, v14, s30
	s_waitcnt vmcnt(10)
	v_bfe_u32 v15, v55, 16, 1
	v_lshrrev_b32_e32 v14, 16, v14
	v_add3_u32 v15, v55, v15, s30
	v_and_or_b32 v14, v15, s31, v14
	s_waitcnt vmcnt(9)
	v_bfe_u32 v15, v56, 16, 1
	v_add3_u32 v15, v56, v15, s30
	s_waitcnt vmcnt(8)
	v_bfe_u32 v16, v57, 16, 1
	v_lshrrev_b32_e32 v15, 16, v15
	v_add3_u32 v16, v57, v16, s30
	v_and_or_b32 v15, v16, s31, v15
	s_waitcnt vmcnt(7)
	v_bfe_u32 v16, v58, 16, 1
	v_add3_u32 v16, v58, v16, s30
	s_waitcnt vmcnt(6)
	v_bfe_u32 v17, v59, 16, 1
	v_lshrrev_b32_e32 v16, 16, v16
	v_add3_u32 v17, v59, v17, s30
	v_and_or_b32 v16, v17, s31, v16
	s_waitcnt vmcnt(5)
	v_bfe_u32 v17, v60, 16, 1
	v_add3_u32 v17, v60, v17, s30
	s_waitcnt vmcnt(4)
	v_bfe_u32 v27, v26, 16, 1
	v_lshrrev_b32_e32 v17, 16, v17
	v_add3_u32 v26, v26, v27, s30
	v_and_or_b32 v17, v26, s31, v17
	global_load_dwordx4 v[26:29], v[46:47], off offset:48
	global_load_dwordx4 v[30:33], v[46:47], off offset:32
	s_waitcnt vmcnt(4)
	v_mul_f32_e32 v34, 0x3fb8aa3b, v34
	v_mul_f32_e32 v23, 0x3fb8aa3b, v23
	v_exp_f32_e32 v42, v34
	v_mul_f32_e32 v34, 0x3fb8aa3b, v35
	v_exp_f32_e32 v50, v23
	v_mul_f32_e32 v23, 0x3fb8aa3b, v36
	v_exp_f32_e32 v44, v34
	v_exp_f32_e32 v43, v23
	v_mul_f32_e32 v23, 0x3fb8aa3b, v24
	v_mul_f32_e32 v24, 0x3fb8aa3b, v37
	global_load_dwordx4 v[34:37], v[110:111], off offset:16
	v_exp_f32_e32 v45, v24
	s_waitcnt vmcnt(4)
	v_lshlrev_b32_e32 v55, 16, v19
	v_lshlrev_b32_e32 v54, 16, v18
	v_and_b32_e32 v19, 0xffff0000, v19
	v_and_b32_e32 v18, 0xffff0000, v18
	v_mul_f32_e32 v24, 0x3fb8aa3b, v25
	v_pk_mul_f32 v[54:55], v[54:55], s[18:19] op_sel_hi:[1,0]
	v_pk_mul_f32 v[18:19], v[18:19], s[18:19] op_sel_hi:[1,0]
	v_exp_f32_e32 v51, v24
	v_rcp_f32_e32 v24, v42
	v_rcp_f32_e32 v52, v44
	v_pk_mul_f32 v[54:55], v[54:55], v[42:43]
	v_pk_mul_f32 v[18:19], v[18:19], v[44:45]
	v_rcp_f32_e32 v25, v43
	v_rcp_f32_e32 v53, v45
	global_load_dwordx4 v[42:45], v[110:111], off offset:272
	v_mul_f32_e32 v22, 0x3fb8aa3b, v22
	v_exp_f32_e32 v22, v22
	v_exp_f32_e32 v23, v23
	v_lshlrev_b32_e32 v59, 16, v21
	v_lshlrev_b32_e32 v58, 16, v20
	v_pk_mul_f32 v[58:59], v[58:59], s[18:19] op_sel_hi:[1,0]
	v_and_b32_e32 v21, 0xffff0000, v21
	v_and_b32_e32 v20, 0xffff0000, v20
	v_pk_mul_f32 v[58:59], v[58:59], v[22:23]
	v_pk_mul_f32 v[20:21], v[20:21], s[18:19] op_sel_hi:[1,0]
	s_waitcnt vmcnt(4)
	v_lshlrev_b32_e32 v57, 16, v39
	v_lshlrev_b32_e32 v56, 16, v38
	v_and_b32_e32 v39, 0xffff0000, v39
	v_and_b32_e32 v38, 0xffff0000, v38
	v_pk_mul_f32 v[38:39], v[52:53], v[38:39]
	v_rcp_f32_e32 v52, v22
	v_rcp_f32_e32 v53, v23
	v_lshlrev_b32_e32 v23, 16, v41
	v_lshlrev_b32_e32 v22, 16, v40
	v_pk_mul_f32 v[24:25], v[24:25], v[56:57]
	v_rcp_f32_e32 v56, v50
	v_pk_mul_f32 v[20:21], v[20:21], v[50:51]
	v_rcp_f32_e32 v57, v51
	v_pk_mul_f32 v[22:23], v[52:53], v[22:23]
	v_bfe_u32 v52, v19, 16, 1
	v_bfe_u32 v50, v21, 16, 1
	v_add3_u32 v19, v19, v52, s30
	v_bfe_u32 v52, v58, 16, 1
	v_bfe_u32 v51, v20, 16, 1
	v_add3_u32 v21, v21, v50, s30
	v_bfe_u32 v50, v54, 16, 1
	v_add3_u32 v52, v58, v52, s30
	v_and_b32_e32 v41, 0xffff0000, v41
	v_and_b32_e32 v40, 0xffff0000, v40
	v_bfe_u32 v53, v18, 16, 1
	v_add3_u32 v20, v20, v51, s30
	v_bfe_u32 v51, v55, 16, 1
	v_add3_u32 v50, v54, v50, s30
	v_lshrrev_b32_e32 v52, 16, v52
	v_pk_mul_f32 v[40:41], v[56:57], v[40:41]
	v_add3_u32 v18, v18, v53, s30
	v_bfe_u32 v53, v59, 16, 1
	v_add3_u32 v51, v55, v51, s30
	v_lshrrev_b32_e32 v50, 16, v50
	v_and_or_b32 v20, v20, s31, v52
	v_bfe_u32 v52, v39, 16, 1
	v_add3_u32 v53, v59, v53, s30
	v_lshrrev_b32_e32 v51, 16, v51
	v_and_or_b32 v18, v18, s31, v50
	v_bfe_u32 v50, v41, 16, 1
	v_add3_u32 v39, v39, v52, s30
	v_bfe_u32 v52, v22, 16, 1
	v_lshrrev_b32_e32 v53, 16, v53
	v_and_or_b32 v19, v19, s31, v51
	v_bfe_u32 v51, v40, 16, 1
	v_add3_u32 v41, v41, v50, s30
	v_bfe_u32 v50, v24, 16, 1
	v_add3_u32 v22, v22, v52, s30
	v_and_or_b32 v21, v21, s31, v53
	v_bfe_u32 v53, v38, 16, 1
	v_add3_u32 v40, v40, v51, s30
	v_add3_u32 v24, v24, v50, s30
	v_lshrrev_b32_e32 v22, 16, v22
	s_waitcnt vmcnt(3)
	v_mul_f32_e32 v27, 0x3fb8aa3b, v27
	v_add3_u32 v38, v38, v53, s30
	v_bfe_u32 v51, v25, 16, 1
	v_bfe_u32 v53, v23, 16, 1
	v_lshrrev_b32_e32 v50, 16, v24
	v_and_or_b32 v24, v40, s31, v22
	s_waitcnt vmcnt(2)
	v_mul_f32_e32 v30, 0x3fb8aa3b, v30
	v_mul_f32_e32 v31, 0x3fb8aa3b, v31
	v_exp_f32_e32 v40, v27
	v_mul_f32_e32 v27, 0x3fb8aa3b, v32
	v_add3_u32 v23, v23, v53, s30
	v_add3_u32 v25, v25, v51, s30
	v_and_or_b32 v22, v38, s31, v50
	v_exp_f32_e32 v30, v30
	v_exp_f32_e32 v38, v31
	v_exp_f32_e32 v31, v27
	v_lshrrev_b32_e32 v51, 16, v25
	v_lshrrev_b32_e32 v23, 16, v23
	v_mul_f32_e32 v27, 0x3fb8aa3b, v28
	v_mul_f32_e32 v28, 0x3fb8aa3b, v33
	v_and_or_b32 v25, v41, s31, v23
	v_and_or_b32 v23, v39, s31, v51
	v_exp_f32_e32 v39, v28
	s_waitcnt vmcnt(1)
	v_lshlrev_b32_e32 v51, 16, v35
	v_lshlrev_b32_e32 v50, 16, v34
	v_mul_f32_e32 v26, 0x3fb8aa3b, v26
	v_mul_f32_e32 v28, 0x3fb8aa3b, v29
	v_pk_mul_f32 v[50:51], v[50:51], s[18:19] op_sel_hi:[1,0]
	v_exp_f32_e32 v26, v26
	v_exp_f32_e32 v27, v27
	v_exp_f32_e32 v41, v28
	v_rcp_f32_e32 v28, v30
	v_pk_mul_f32 v[62:63], v[50:51], v[30:31]
	v_and_b32_e32 v35, 0xffff0000, v35
	v_and_b32_e32 v34, 0xffff0000, v34
	global_load_dwordx4 v[50:53], v[46:47], off offset:80
	global_load_dwordx4 v[54:57], v[46:47], off offset:64
	v_rcp_f32_e32 v29, v31
	v_pk_mul_f32 v[34:35], v[34:35], s[18:19] op_sel_hi:[1,0]
	s_waitcnt vmcnt(2)
	v_lshlrev_b32_e32 v31, 16, v43
	v_pk_mul_f32 v[64:65], v[34:35], v[38:39]
	v_lshlrev_b32_e32 v35, 16, v37
	v_lshlrev_b32_e32 v34, 16, v36
	v_lshlrev_b32_e32 v30, 16, v42
	v_pk_mul_f32 v[34:35], v[34:35], s[18:19] op_sel_hi:[1,0]
	v_pk_mul_f32 v[30:31], v[28:29], v[30:31]
	v_and_b32_e32 v29, 0xffff0000, v43
	v_and_b32_e32 v28, 0xffff0000, v42
	v_pk_mul_f32 v[42:43], v[34:35], v[26:27]
	v_and_b32_e32 v35, 0xffff0000, v37
	v_and_b32_e32 v34, 0xffff0000, v36
	v_pk_mul_f32 v[58:59], v[34:35], s[18:19] op_sel_hi:[1,0]
	global_load_dwordx4 v[34:37], v[110:111], off offset:32
	v_rcp_f32_e32 v32, v38
	v_rcp_f32_e32 v33, v39
	v_pk_mul_f32 v[66:67], v[58:59], v[40:41]
	global_load_dwordx4 v[58:61], v[110:111], off offset:288
	v_rcp_f32_e32 v38, v40
	v_pk_mul_f32 v[32:33], v[32:33], v[28:29]
	v_rcp_f32_e32 v28, v26
	v_rcp_f32_e32 v29, v27
	v_rcp_f32_e32 v39, v41
	v_lshlrev_b32_e32 v27, 16, v45
	v_lshlrev_b32_e32 v26, 16, v44
	v_pk_mul_f32 v[40:41], v[28:29], v[26:27]
	v_bfe_u32 v28, v65, 16, 1
	v_bfe_u32 v29, v64, 16, 1
	v_and_b32_e32 v27, 0xffff0000, v45
	v_and_b32_e32 v26, 0xffff0000, v44
	v_add3_u32 v44, v64, v29, s30
	v_add3_u32 v45, v65, v28, s30
	v_bfe_u32 v28, v62, 16, 1
	v_bfe_u32 v29, v63, 16, 1
	v_bfe_u32 v64, v42, 16, 1
	v_bfe_u32 v65, v43, 16, 1
	v_pk_mul_f32 v[38:39], v[38:39], v[26:27]
	v_bfe_u32 v26, v67, 16, 1
	v_bfe_u32 v27, v66, 16, 1
	v_add3_u32 v43, v43, v65, s30
	v_add3_u32 v42, v42, v64, s30
	v_add3_u32 v29, v63, v29, s30
	v_add3_u32 v28, v62, v28, s30
	v_add3_u32 v27, v66, v27, s30
	v_add3_u32 v26, v67, v26, s30
	v_lshrrev_b32_e32 v62, 16, v28
	v_lshrrev_b32_e32 v63, 16, v29
	v_lshrrev_b32_e32 v28, 16, v42
	v_lshrrev_b32_e32 v29, 16, v43
	v_and_or_b32 v29, v26, s31, v29
	v_and_or_b32 v28, v27, s31, v28
	v_and_or_b32 v27, v45, s31, v63
	v_and_or_b32 v26, v44, s31, v62
	v_bfe_u32 v42, v39, 16, 1
	v_bfe_u32 v43, v38, 16, 1
	v_bfe_u32 v44, v33, 16, 1
	v_bfe_u32 v45, v32, 16, 1
	v_add3_u32 v45, v32, v45, s30
	v_add3_u32 v44, v33, v44, s30
	v_add3_u32 v32, v38, v43, s30
	v_add3_u32 v33, v39, v42, s30
	v_bfe_u32 v38, v30, 16, 1
	v_bfe_u32 v39, v31, 16, 1
	v_bfe_u32 v42, v40, 16, 1
	v_bfe_u32 v43, v41, 16, 1
	v_add3_u32 v41, v41, v43, s30
	v_add3_u32 v40, v40, v42, s30
	v_add3_u32 v31, v31, v39, s30
	v_add3_u32 v30, v30, v38, s30
	v_lshrrev_b32_e32 v30, 16, v30
	v_lshrrev_b32_e32 v31, 16, v31
	v_lshrrev_b32_e32 v38, 16, v40
	v_lshrrev_b32_e32 v39, 16, v41
	v_and_or_b32 v33, v33, s31, v39
	v_and_or_b32 v32, v32, s31, v38
	v_and_or_b32 v31, v44, s31, v31
	v_and_or_b32 v30, v45, s31, v30
	global_load_dwordx4 v[38:41], v[46:47], off offset:112
	global_load_dwordx4 v[42:45], v[46:47], off offset:96
	s_waitcnt vmcnt(5)
	v_mul_f32_e32 v47, 0x3fb8aa3b, v50
	v_exp_f32_e32 v62, v47
	s_waitcnt vmcnt(4)
	v_mul_f32_e32 v47, 0x3fb8aa3b, v55
	v_mul_f32_e32 v46, 0x3fb8aa3b, v54
	v_exp_f32_e32 v54, v47
	v_mul_f32_e32 v47, 0x3fb8aa3b, v51
	v_mul_f32_e32 v50, 0x3fb8aa3b, v52
	v_exp_f32_e32 v64, v47
	v_mul_f32_e32 v47, 0x3fb8aa3b, v56
	v_exp_f32_e32 v63, v50
	v_mul_f32_e32 v50, 0x3fb8aa3b, v57
	v_exp_f32_e32 v46, v46
	v_exp_f32_e32 v47, v47
	v_exp_f32_e32 v55, v50
	v_mul_f32_e32 v50, 0x3fb8aa3b, v53
	v_exp_f32_e32 v65, v50
	global_load_dwordx4 v[50:53], v[110:111], off offset:48
	s_waitcnt vmcnt(4)
	v_lshlrev_b32_e32 v57, 16, v35
	v_lshlrev_b32_e32 v56, 16, v34
	v_and_b32_e32 v35, 0xffff0000, v35
	v_and_b32_e32 v34, 0xffff0000, v34
	v_pk_mul_f32 v[56:57], v[56:57], s[18:19] op_sel_hi:[1,0]
	v_pk_mul_f32 v[34:35], v[34:35], s[18:19] op_sel_hi:[1,0]
	v_rcp_f32_e32 v68, v54
	v_pk_mul_f32 v[70:71], v[56:57], v[46:47]
	v_pk_mul_f32 v[34:35], v[34:35], v[54:55]
	v_rcp_f32_e32 v69, v55
	global_load_dwordx4 v[54:57], v[110:111], off offset:304
	v_rcp_f32_e32 v66, v46
	v_rcp_f32_e32 v67, v47
	s_waitcnt vmcnt(4)
	v_lshlrev_b32_e32 v47, 16, v59
	v_lshlrev_b32_e32 v46, 16, v58
	v_lshlrev_b32_e32 v73, 16, v37
	v_pk_mul_f32 v[46:47], v[66:67], v[46:47]
	v_rcp_f32_e32 v66, v62
	v_rcp_f32_e32 v67, v63
	v_lshlrev_b32_e32 v72, 16, v36
	v_pk_mul_f32 v[72:73], v[72:73], s[18:19] op_sel_hi:[1,0]
	v_and_b32_e32 v37, 0xffff0000, v37
	v_and_b32_e32 v36, 0xffff0000, v36
	v_and_b32_e32 v59, 0xffff0000, v59
	v_and_b32_e32 v58, 0xffff0000, v58
	v_pk_mul_f32 v[72:73], v[72:73], v[62:63]
	v_pk_mul_f32 v[36:37], v[36:37], s[18:19] op_sel_hi:[1,0]
	v_lshlrev_b32_e32 v63, 16, v61
	v_lshlrev_b32_e32 v62, 16, v60
	v_pk_mul_f32 v[58:59], v[68:69], v[58:59]
	v_rcp_f32_e32 v68, v64
	v_pk_mul_f32 v[36:37], v[36:37], v[64:65]
	v_rcp_f32_e32 v69, v65
	v_pk_mul_f32 v[62:63], v[66:67], v[62:63]
	v_bfe_u32 v66, v35, 16, 1
	v_bfe_u32 v64, v37, 16, 1
	v_add3_u32 v35, v35, v66, s30
	v_bfe_u32 v66, v72, 16, 1
	v_bfe_u32 v65, v36, 16, 1
	v_add3_u32 v37, v37, v64, s30
	v_bfe_u32 v64, v70, 16, 1
	v_add3_u32 v66, v72, v66, s30
	v_and_b32_e32 v61, 0xffff0000, v61
	v_and_b32_e32 v60, 0xffff0000, v60
	v_bfe_u32 v67, v34, 16, 1
	v_add3_u32 v36, v36, v65, s30
	v_bfe_u32 v65, v71, 16, 1
	v_add3_u32 v64, v70, v64, s30
	v_lshrrev_b32_e32 v66, 16, v66
	v_pk_mul_f32 v[60:61], v[68:69], v[60:61]
	v_add3_u32 v34, v34, v67, s30
	v_bfe_u32 v67, v73, 16, 1
	v_add3_u32 v65, v71, v65, s30
	v_lshrrev_b32_e32 v64, 16, v64
	v_and_or_b32 v36, v36, s31, v66
	v_bfe_u32 v66, v59, 16, 1
	v_add3_u32 v67, v73, v67, s30
	v_lshrrev_b32_e32 v65, 16, v65
	v_and_or_b32 v34, v34, s31, v64
	v_bfe_u32 v64, v61, 16, 1
	v_add3_u32 v59, v59, v66, s30
	v_bfe_u32 v66, v62, 16, 1
	v_lshrrev_b32_e32 v67, 16, v67
	v_and_or_b32 v35, v35, s31, v65
	v_bfe_u32 v65, v60, 16, 1
	v_add3_u32 v61, v61, v64, s30
	v_bfe_u32 v64, v46, 16, 1
	v_add3_u32 v62, v62, v66, s30
	v_and_or_b32 v37, v37, s31, v67
	v_bfe_u32 v67, v58, 16, 1
	v_add3_u32 v60, v60, v65, s30
	v_bfe_u32 v65, v47, 16, 1
	v_add3_u32 v46, v46, v64, s30
	v_lshrrev_b32_e32 v62, 16, v62
	s_waitcnt vmcnt(3)
	v_mul_f32_e32 v39, 0x3fb8aa3b, v39
	v_add3_u32 v58, v58, v67, s30
	v_add3_u32 v47, v47, v65, s30
	v_lshrrev_b32_e32 v46, 16, v46
	v_and_or_b32 v60, v60, s31, v62
	s_waitcnt vmcnt(2)
	v_mul_f32_e32 v42, 0x3fb8aa3b, v42
	v_mul_f32_e32 v43, 0x3fb8aa3b, v43
	v_exp_f32_e32 v62, v39
	v_mul_f32_e32 v39, 0x3fb8aa3b, v44
	v_lshrrev_b32_e32 v47, 16, v47
	v_and_or_b32 v58, v58, s31, v46
	v_exp_f32_e32 v42, v42
	v_exp_f32_e32 v46, v43
	v_exp_f32_e32 v43, v39
	v_mul_f32_e32 v39, 0x3fb8aa3b, v40
	v_mul_f32_e32 v40, 0x3fb8aa3b, v45
	v_bfe_u32 v67, v63, 16, 1
	v_and_or_b32 v59, v59, s31, v47
	v_exp_f32_e32 v47, v40
	v_add3_u32 v63, v63, v67, s30
	v_lshrrev_b32_e32 v63, 16, v63
	v_mul_f32_e32 v40, 0x3fb8aa3b, v41
	v_and_or_b32 v61, v61, s31, v63
	v_mul_f32_e32 v38, 0x3fb8aa3b, v38
	v_exp_f32_e32 v63, v40
	v_rcp_f32_e32 v40, v42
	v_rcp_f32_e32 v41, v43
	v_exp_f32_e32 v38, v38
	v_exp_f32_e32 v39, v39
	v_rcp_f32_e32 v44, v46
	s_waitcnt vmcnt(1)
	v_lshlrev_b32_e32 v65, 16, v51
	v_lshlrev_b32_e32 v64, 16, v50
	v_rcp_f32_e32 v45, v47
	v_pk_mul_f32 v[64:65], v[64:65], s[18:19] op_sel_hi:[1,0]
	v_and_b32_e32 v51, 0xffff0000, v51
	v_pk_mul_f32 v[64:65], v[64:65], v[42:43]
	s_waitcnt vmcnt(0)
	v_lshlrev_b32_e32 v43, 16, v55
	v_lshlrev_b32_e32 v42, 16, v54
	v_and_b32_e32 v50, 0xffff0000, v50
	v_pk_mul_f32 v[42:43], v[40:41], v[42:43]
	v_and_b32_e32 v41, 0xffff0000, v55
	v_and_b32_e32 v40, 0xffff0000, v54
	v_pk_mul_f32 v[50:51], v[50:51], s[18:19] op_sel_hi:[1,0]
	v_pk_mul_f32 v[44:45], v[44:45], v[40:41]
	v_rcp_f32_e32 v40, v38
	v_rcp_f32_e32 v41, v39
	v_pk_mul_f32 v[50:51], v[50:51], v[46:47]
	v_rcp_f32_e32 v46, v62
	v_lshlrev_b32_e32 v55, 16, v53
	v_lshlrev_b32_e32 v54, 16, v52
	v_rcp_f32_e32 v47, v63
	v_pk_mul_f32 v[54:55], v[54:55], s[18:19] op_sel_hi:[1,0]
	v_and_b32_e32 v53, 0xffff0000, v53
	v_and_b32_e32 v52, 0xffff0000, v52
	v_pk_mul_f32 v[54:55], v[54:55], v[38:39]
	v_pk_mul_f32 v[52:53], v[52:53], s[18:19] op_sel_hi:[1,0]
	v_lshlrev_b32_e32 v39, 16, v57
	v_lshlrev_b32_e32 v38, 16, v56
	v_pk_mul_f32 v[52:53], v[52:53], v[62:63]
	v_pk_mul_f32 v[62:63], v[40:41], v[38:39]
	v_and_b32_e32 v39, 0xffff0000, v57
	v_and_b32_e32 v38, 0xffff0000, v56
	v_pk_mul_f32 v[46:47], v[46:47], v[38:39]
	v_bfe_u32 v38, v53, 16, 1
	v_bfe_u32 v39, v52, 16, 1
	v_bfe_u32 v40, v51, 16, 1
	v_bfe_u32 v41, v50, 16, 1
	v_add3_u32 v50, v50, v41, s30
	v_add3_u32 v51, v51, v40, s30
	v_add3_u32 v39, v52, v39, s30
	v_add3_u32 v38, v53, v38, s30
	v_bfe_u32 v40, v64, 16, 1
	v_bfe_u32 v41, v65, 16, 1
	v_bfe_u32 v52, v54, 16, 1
	v_bfe_u32 v53, v55, 16, 1
	v_add3_u32 v53, v55, v53, s30
	v_add3_u32 v52, v54, v52, s30
	v_add3_u32 v41, v65, v41, s30
	v_add3_u32 v40, v64, v40, s30
	v_lshrrev_b32_e32 v54, 16, v40
	v_lshrrev_b32_e32 v55, 16, v41
	v_lshrrev_b32_e32 v40, 16, v52
	v_lshrrev_b32_e32 v41, 16, v53
	v_and_or_b32 v41, v38, s31, v41
	v_and_or_b32 v40, v39, s31, v40
	v_and_or_b32 v39, v51, s31, v55
	v_and_or_b32 v38, v50, s31, v54
	v_bfe_u32 v50, v47, 16, 1
	v_bfe_u32 v51, v46, 16, 1
	v_bfe_u32 v52, v45, 16, 1
	v_bfe_u32 v53, v44, 16, 1
	v_add3_u32 v53, v44, v53, s30
	v_add3_u32 v52, v45, v52, s30
	v_add3_u32 v44, v46, v51, s30
	v_add3_u32 v45, v47, v50, s30
	v_bfe_u32 v46, v42, 16, 1
	v_bfe_u32 v47, v43, 16, 1
	v_bfe_u32 v50, v62, 16, 1
	v_bfe_u32 v51, v63, 16, 1
	v_add3_u32 v51, v63, v51, s30
	v_add3_u32 v50, v62, v50, s30
	v_add3_u32 v43, v43, v47, s30
	v_add3_u32 v42, v42, v46, s30
	s_waitcnt lgkmcnt(0)
	ds_write_b128 v142, v[18:21]
	ds_write_b128 v142, v[26:29] offset:16
	ds_write_b128 v142, v[34:37] offset:32
	ds_write_b128 v142, v[38:41] offset:48
	ds_write_b128 v142, v[2:5] offset:4096
	ds_write_b128 v142, v[6:9] offset:4112
	ds_write_b128 v142, v[10:13] offset:4128
	ds_write_b128 v142, v[14:17] offset:4144
	v_lshlrev_b32_e32 v26, 6, v140
	v_lshrrev_b32_e32 v42, 16, v42
	v_lshrrev_b32_e32 v43, 16, v43
	v_lshrrev_b32_e32 v46, 16, v50
	v_lshrrev_b32_e32 v47, 16, v51
	v_add_u32_e32 v172, v134, v26
	v_and_or_b32 v45, v45, s31, v47
	v_and_or_b32 v44, v44, s31, v46
	v_and_or_b32 v43, v52, s31, v43
	v_and_or_b32 v42, v53, s31, v42
	s_waitcnt lgkmcnt(0)
	ds_read_b128 v[14:17], v172
	ds_read_b128 v[10:13], v172 offset:1024
	ds_read_b128 v[6:9], v172 offset:2048
	ds_read_b128 v[2:5], v172 offset:3072
	s_waitcnt lgkmcnt(0)
	ds_write_b128 v142, v[22:25]
	ds_write_b128 v142, v[30:33] offset:16
	ds_write_b128 v142, v[58:61] offset:32
	ds_write_b128 v142, v[42:45] offset:48
	s_waitcnt lgkmcnt(0)
	ds_read_b128 v[18:21], v172 offset:4096
	ds_read_b128 v[34:37], v172
	s_waitcnt lgkmcnt(1)
	v_mfma_f32_16x16x32_bf16 v[38:41], v[18:21], v[14:17], 0
	v_add3_u32 v143, s19, v26, v49
	v_mfma_f32_16x16x32_bf16 v[42:45], v[18:21], v[10:13], 0
	v_mfma_f32_16x16x32_bf16 v[82:85], v[18:21], v[6:9], 0
	v_mfma_f32_16x16x32_bf16 v[86:89], v[18:21], v[2:5], 0
	ds_read_b128 v[18:21], v172 offset:5120
	ds_read_b128 v[22:25], v172 offset:6144
	ds_read_b128 v[90:93], v143 offset:1024
	s_waitcnt lgkmcnt(2)
	v_mfma_f32_16x16x32_bf16 v[50:53], v[18:21], v[14:17], 0
	v_mfma_f32_16x16x32_bf16 v[54:57], v[18:21], v[10:13], 0
	v_mfma_f32_16x16x32_bf16 v[58:61], v[18:21], v[6:9], 0
	v_mfma_f32_16x16x32_bf16 v[62:65], v[18:21], v[2:5], 0
	ds_read_b128 v[18:21], v172 offset:7168
	v_mfma_f32_16x16x32_bf16 v[152:155], v[34:37], v[14:17], 0
	s_waitcnt lgkmcnt(1)
	v_mfma_f32_16x16x32_bf16 v[156:159], v[90:93], v[14:17], 0
	v_mfma_f32_16x16x32_bf16 v[174:177], v[34:37], v[10:13], 0
	s_nop 4
	v_cndmask_b32_e64 v46, v152, 0, s[10:11]
	s_nop 0
	v_cndmask_b32_e32 v47, 0, v156, vcc
	v_cmp_lt_i32_e32 vcc, v120, v140
	v_cndmask_b32_e64 v135, 0, v157, s[0:1]
	v_cmp_le_i32_e64 s[0:1], v164, v140
	v_cndmask_b32_e32 v49, 0, v153, vcc
	v_bfe_u32 v152, v46, 16, 1
	v_cndmask_b32_e64 v136, 0, v154, s[0:1]
	v_cmp_le_i32_e64 s[0:1], v163, v140
	v_add3_u32 v46, v46, v152, s30
	v_bfe_u32 v152, v49, 16, 1
	v_cndmask_b32_e64 v137, 0, v158, s[0:1]
	v_cmp_le_i32_e64 s[0:1], v166, v140
	v_lshrrev_b32_e32 v46, 16, v46
	v_add3_u32 v49, v49, v152, s30
	v_cndmask_b32_e64 v144, 0, v155, s[0:1]
	v_and_or_b32 v154, v49, s31, v46
	v_bfe_u32 v46, v136, 16, 1
	v_add3_u32 v46, v136, v46, s30
	v_bfe_u32 v49, v144, 16, 1
	v_lshrrev_b32_e32 v46, 16, v46
	v_add3_u32 v49, v144, v49, s30
	v_and_or_b32 v155, v49, s31, v46
	v_bfe_u32 v46, v47, 16, 1
	v_add3_u32 v46, v47, v46, s30
	v_bfe_u32 v47, v135, 16, 1
	v_cmp_le_i32_e64 s[0:1], v165, v140
	v_lshrrev_b32_e32 v46, 16, v46
	v_add3_u32 v47, v135, v47, s30
	v_cndmask_b32_e64 v145, 0, v159, s[0:1]
	v_and_or_b32 v156, v47, s31, v46
	v_bfe_u32 v46, v137, 16, 1
	v_mfma_f32_16x16x32_bf16 v[178:181], v[90:93], v[10:13], 0
	v_add3_u32 v46, v137, v46, s30
	v_bfe_u32 v47, v145, 16, 1
	v_lshrrev_b32_e32 v46, 16, v46
	v_add3_u32 v47, v145, v47, s30
	v_cmp_le_i32_e64 s[0:1], v120, v168
	v_and_or_b32 v157, v47, s31, v46
	v_cndmask_b32_e64 v49, 0, v175, s[8:9]
	v_cndmask_b32_e64 v46, 0, v174, s[0:1]
	v_cmp_le_i32_e64 s[0:1], v162, v168
	v_bfe_u32 v152, v46, 16, 1
	v_add3_u32 v46, v46, v152, s30
	v_cndmask_b32_e64 v135, 0, v179, s[0:1]
	v_cmp_le_i32_e64 s[0:1], v164, v168
	v_bfe_u32 v152, v49, 16, 1
	v_lshrrev_b32_e32 v46, 16, v46
	v_cndmask_b32_e64 v136, 0, v176, s[0:1]
	v_cmp_le_i32_e64 s[0:1], v163, v168
	v_add3_u32 v49, v49, v152, s30
	v_and_or_b32 v174, v49, s31, v46
	v_cndmask_b32_e64 v137, 0, v180, s[0:1]
	v_cmp_le_i32_e64 s[0:1], v166, v168
	v_bfe_u32 v46, v136, 16, 1
	v_add3_u32 v46, v136, v46, s30
	v_cndmask_b32_e64 v144, 0, v177, s[0:1]
	v_bfe_u32 v49, v144, 16, 1
	v_cndmask_b32_e64 v47, v178, 0, s[10:11]
	v_lshrrev_b32_e32 v46, 16, v46
	v_add3_u32 v49, v144, v49, s30
	v_and_or_b32 v175, v49, s31, v46
	v_bfe_u32 v46, v47, 16, 1
	v_cmp_le_i32_e64 s[0:1], v165, v168
	v_add3_u32 v46, v47, v46, s30
	v_bfe_u32 v47, v135, 16, 1
	v_cndmask_b32_e64 v145, 0, v181, s[0:1]
	v_lshrrev_b32_e32 v46, 16, v46
	v_add3_u32 v47, v135, v47, s30
	v_mfma_f32_16x16x32_bf16 v[178:181], v[34:37], v[6:9], 0
	v_and_or_b32 v176, v47, s31, v46
	v_bfe_u32 v46, v137, 16, 1
	v_add3_u32 v46, v137, v46, s30
	v_mfma_f32_16x16x32_bf16 v[182:185], v[90:93], v[6:9], 0
	v_bfe_u32 v47, v145, 16, 1
	v_lshrrev_b32_e32 v46, 16, v46
	v_add3_u32 v47, v145, v47, s30
	v_cmp_le_i32_e64 s[0:1], v120, v160
	v_and_or_b32 v177, v47, s31, v46
	v_cndmask_b32_e64 v49, 0, v179, s[6:7]
	v_cndmask_b32_e64 v46, 0, v178, s[0:1]
	v_cmp_le_i32_e64 s[0:1], v161, v160
	v_bfe_u32 v152, v46, 16, 1
	v_add3_u32 v46, v46, v152, s30
	v_cndmask_b32_e64 v47, 0, v182, s[0:1]
	v_cmp_le_i32_e64 s[0:1], v162, v160
	v_bfe_u32 v152, v49, 16, 1
	v_lshrrev_b32_e32 v46, 16, v46
	v_cndmask_b32_e64 v135, 0, v183, s[0:1]
	v_cmp_le_i32_e64 s[0:1], v164, v160
	v_add3_u32 v49, v49, v152, s30
	v_and_or_b32 v178, v49, s31, v46
	v_cndmask_b32_e64 v136, 0, v180, s[0:1]
	v_cmp_le_i32_e64 s[0:1], v163, v160
	v_bfe_u32 v46, v136, 16, 1
	v_add3_u32 v46, v136, v46, s30
	v_cndmask_b32_e64 v137, 0, v184, s[0:1]
	v_cmp_le_i32_e64 s[0:1], v166, v160
	v_lshrrev_b32_e32 v46, 16, v46
	v_mfma_f32_16x16x32_bf16 v[34:37], v[34:37], v[2:5], 0
	v_cndmask_b32_e64 v144, 0, v181, s[0:1]
	v_bfe_u32 v49, v144, 16, 1
	v_add3_u32 v49, v144, v49, s30
	v_and_or_b32 v179, v49, s31, v46
	v_bfe_u32 v46, v47, 16, 1
	v_add3_u32 v46, v47, v46, s30
	v_bfe_u32 v47, v135, 16, 1
	v_cmp_le_i32_e64 s[0:1], v165, v160
	v_lshrrev_b32_e32 v46, 16, v46
	v_add3_u32 v47, v135, v47, s30
	v_cndmask_b32_e64 v145, 0, v185, s[0:1]
	v_and_or_b32 v180, v47, s31, v46
	v_bfe_u32 v46, v137, 16, 1
	v_or_b32_e32 v152, 48, v140
	v_add3_u32 v46, v137, v46, s30
	v_bfe_u32 v47, v145, 16, 1
	v_mfma_f32_16x16x32_bf16 v[90:93], v[90:93], v[2:5], 0
	v_cmp_le_i32_e64 s[0:1], v120, v152
	v_lshrrev_b32_e32 v46, 16, v46
	v_add3_u32 v47, v145, v47, s30
	v_cndmask_b32_e64 v34, 0, v34, s[0:1]
	v_cmp_lt_i32_e64 s[4:5], v120, v152
	v_and_or_b32 v181, v47, s31, v46
	v_bfe_u32 v46, v34, 16, 1
	v_cndmask_b32_e64 v35, 0, v35, s[4:5]
	v_lshl_add_u32 v135, v140, 7, v48
	v_cmp_le_i32_e64 s[0:1], v161, v152
	v_add3_u32 v34, v34, v46, s30
	v_bfe_u32 v46, v35, 16, 1
	v_add_u32_e32 v144, 0x2000, v135
	v_cndmask_b32_e64 v90, 0, v90, s[0:1]
	v_cmp_le_i32_e64 s[0:1], v162, v152
	v_add3_u32 v35, v35, v46, s30
	ds_read2_b64 v[46:49], v144 offset1:4
	v_cndmask_b32_e64 v91, 0, v91, s[0:1]
	v_cmp_le_i32_e64 s[0:1], v164, v152
	v_lshrrev_b32_e32 v34, 16, v34
	v_and_or_b32 v182, v35, s31, v34
	v_cndmask_b32_e64 v36, 0, v36, s[0:1]
	v_cmp_le_i32_e64 s[0:1], v163, v152
	v_bfe_u32 v34, v36, 16, 1
	v_add3_u32 v34, v36, v34, s30
	v_cndmask_b32_e64 v92, 0, v92, s[0:1]
	v_cmp_le_i32_e64 s[0:1], v166, v152
	v_lshrrev_b32_e32 v34, 16, v34
	v_add_u32_e32 v145, 0x2800, v135
	v_cndmask_b32_e64 v37, 0, v37, s[0:1]
	v_bfe_u32 v35, v37, 16, 1
	v_add3_u32 v35, v37, v35, s30
	v_and_or_b32 v183, v35, s31, v34
	v_bfe_u32 v34, v90, 16, 1
	v_add3_u32 v34, v90, v34, s30
	v_lshrrev_b32_e32 v90, 16, v34
	s_waitcnt lgkmcnt(0)
	v_mfma_f32_16x16x32_bf16 v[34:37], v[46:49], v[154:157], v[38:41]
	v_cmp_le_i32_e64 s[0:1], v165, v152
	v_add_u32_e32 v171, 0x3000, v135
	v_add_u32_e32 v170, 0x3800, v135
	v_bfe_u32 v38, v91, 16, 1
	v_add3_u32 v38, v91, v38, s30
	v_and_or_b32 v184, v38, s31, v90
	v_mfma_f32_16x16x32_bf16 v[38:41], v[46:49], v[174:177], v[42:45]
	v_cndmask_b32_e64 v93, 0, v93, s[0:1]
	ds_read2_b64 v[186:189], v170 offset1:4
	v_add_u32_e32 v153, 32, v120
	v_bfe_u32 v42, v92, 16, 1
	v_add3_u32 v42, v92, v42, s30
	v_lshrrev_b32_e32 v90, 16, v42
	v_mfma_f32_16x16x32_bf16 v[42:45], v[46:49], v[178:181], v[82:85]
	v_cmp_le_i32_e64 s[0:1], v153, v140
	v_add_u32_e32 v159, 35, v120
	v_add_u32_e32 v158, 51, v120
	v_bfe_u32 v82, v93, 16, 1
	v_add3_u32 v82, v93, v82, s30
	v_and_or_b32 v185, v82, s31, v90
	ds_read2_b64 v[82:85], v145 offset1:4
	s_waitcnt lgkmcnt(0)
	v_mfma_f32_16x16x32_bf16 v[50:53], v[82:85], v[154:157], v[50:53]
	v_mfma_f32_16x16x32_bf16 v[54:57], v[82:85], v[174:177], v[54:57]
	v_mfma_f32_16x16x32_bf16 v[58:61], v[82:85], v[178:181], v[58:61]
	v_mfma_f32_16x16x32_bf16 v[62:65], v[82:85], v[182:185], v[62:65]
	ds_read2_b64 v[82:85], v171 offset1:4
	v_mfma_f32_16x16x32_bf16 v[66:69], v[22:25], v[14:17], 0
	v_mfma_f32_16x16x32_bf16 v[70:73], v[22:25], v[10:13], 0
	v_mfma_f32_16x16x32_bf16 v[74:77], v[22:25], v[6:9], 0
	v_mfma_f32_16x16x32_bf16 v[78:81], v[22:25], v[2:5], 0
	v_mfma_f32_16x16x32_bf16 v[22:25], v[18:21], v[14:17], 0
	v_mfma_f32_16x16x32_bf16 v[26:29], v[18:21], v[10:13], 0
	s_waitcnt lgkmcnt(0)
	v_mfma_f32_16x16x32_bf16 v[66:69], v[82:85], v[154:157], v[66:69]
	v_mfma_f32_16x16x32_bf16 v[70:73], v[82:85], v[174:177], v[70:73]
	v_mfma_f32_16x16x32_bf16 v[74:77], v[82:85], v[178:181], v[74:77]
	v_mfma_f32_16x16x32_bf16 v[78:81], v[82:85], v[182:185], v[78:81]
	v_mfma_f32_16x16x32_bf16 v[82:85], v[186:189], v[154:157], v[22:25]
	v_add_u32_e32 v155, 33, v120
	v_add_u32_e32 v154, 49, v120
	v_add_u32_e32 v157, 34, v120
	ds_read_b128 v[22:25], v173
	v_mfma_f32_16x16x32_bf16 v[46:49], v[46:49], v[182:185], v[86:89]
	v_add_u32_e32 v156, 50, v120
	v_mfma_f32_16x16x32_bf16 v[86:89], v[186:189], v[174:177], v[26:29]
	s_nop 2
	ds_read_b128 v[26:29], v143 offset:3072
	v_mfma_f32_16x16x32_bf16 v[30:33], v[18:21], v[6:9], 0
	v_mfma_f32_16x16x32_bf16 v[90:93], v[186:189], v[178:181], v[30:33]
	s_waitcnt lgkmcnt(1)
	v_mfma_f32_16x16x32_bf16 v[30:33], v[22:25], v[14:17], 0
	s_waitcnt lgkmcnt(0)
	v_mfma_f32_16x16x32_bf16 v[14:17], v[26:29], v[14:17], 0
	v_mfma_f32_16x16x32_bf16 v[18:21], v[18:21], v[2:5], 0
	s_nop 4
	v_cndmask_b32_e64 v30, 0, v30, s[0:1]
	v_cmp_le_i32_e64 s[0:1], v167, v140
	v_mfma_f32_16x16x32_bf16 v[18:21], v[186:189], v[182:185], v[18:21]
	s_nop 0
	v_cndmask_b32_e64 v134, 0, v14, s[0:1]
	v_cmp_le_i32_e64 s[0:1], v155, v140
	s_nop 1
	v_cndmask_b32_e64 v14, 0, v31, s[0:1]
	v_cmp_le_i32_e64 s[0:1], v154, v140
	s_nop 1
	v_cndmask_b32_e64 v31, 0, v15, s[0:1]
	v_cmp_le_i32_e64 s[0:1], v157, v140
	s_nop 1
	v_cndmask_b32_e64 v15, 0, v32, s[0:1]
	v_cmp_le_i32_e64 s[0:1], v156, v140
	s_nop 1
	v_cndmask_b32_e64 v32, 0, v16, s[0:1]
	v_cmp_le_i32_e64 s[0:1], v159, v140
	s_nop 1
	v_cndmask_b32_e64 v16, 0, v33, s[0:1]
	v_bfe_u32 v33, v30, 16, 1
	v_add3_u32 v30, v30, v33, s30
	v_bfe_u32 v33, v14, 16, 1
	v_lshrrev_b32_e32 v30, 16, v30
	v_add3_u32 v14, v14, v33, s30
	v_and_or_b32 v14, v14, s31, v30
	v_bfe_u32 v30, v15, 16, 1
	v_add3_u32 v15, v15, v30, s30
	v_bfe_u32 v30, v16, 16, 1
	v_lshrrev_b32_e32 v15, 16, v15
	v_add3_u32 v16, v16, v30, s30
	v_and_or_b32 v15, v16, s31, v15
	v_bfe_u32 v16, v134, 16, 1
	v_add3_u32 v16, v134, v16, s30
	v_bfe_u32 v30, v31, 16, 1
	v_lshrrev_b32_e32 v16, 16, v16
	v_add3_u32 v30, v31, v30, s30
	v_and_or_b32 v16, v30, s31, v16
	v_bfe_u32 v30, v32, 16, 1
	v_add3_u32 v30, v32, v30, s30
	v_lshrrev_b32_e32 v134, 16, v30
	v_mfma_f32_16x16x32_bf16 v[30:33], v[22:25], v[10:13], 0
	v_cmp_le_i32_e64 s[0:1], v158, v140
	v_mfma_f32_16x16x32_bf16 v[10:13], v[26:29], v[10:13], 0
	s_nop 0
	v_cndmask_b32_e64 v17, 0, v17, s[0:1]
	v_cmp_le_i32_e64 s[0:1], v153, v168
	v_bfe_u32 v135, v17, 16, 1
	v_add3_u32 v17, v17, v135, s30
	s_nop 0
	v_cndmask_b32_e64 v30, 0, v30, s[0:1]
	v_cmp_le_i32_e64 s[0:1], v167, v168
	v_and_or_b32 v17, v17, s31, v134
	s_nop 0
	v_cndmask_b32_e64 v10, 0, v10, s[0:1]
	v_cmp_le_i32_e64 s[0:1], v155, v168
	s_nop 1
	v_cndmask_b32_e64 v31, 0, v31, s[0:1]
	v_cmp_le_i32_e64 s[0:1], v154, v168
	s_nop 1
	v_cndmask_b32_e64 v11, 0, v11, s[0:1]
	v_cmp_le_i32_e64 s[0:1], v157, v168
	s_nop 1
	v_cndmask_b32_e64 v32, 0, v32, s[0:1]
	v_cmp_le_i32_e64 s[0:1], v156, v168
	s_nop 1
	v_cndmask_b32_e64 v12, 0, v12, s[0:1]
	v_cmp_le_i32_e64 s[0:1], v159, v168
	s_nop 1
	v_cndmask_b32_e64 v33, 0, v33, s[0:1]
	v_cmp_le_i32_e64 s[0:1], v158, v168
	s_nop 1
	v_cndmask_b32_e64 v137, 0, v13, s[0:1]
	v_bfe_u32 v13, v30, 16, 1
	v_add3_u32 v13, v30, v13, s30
	v_bfe_u32 v30, v31, 16, 1
	v_lshrrev_b32_e32 v13, 16, v13
	v_add3_u32 v30, v31, v30, s30
	v_and_or_b32 v134, v30, s31, v13
	v_bfe_u32 v13, v32, 16, 1
	v_add3_u32 v13, v32, v13, s30
	v_bfe_u32 v30, v33, 16, 1
	v_lshrrev_b32_e32 v13, 16, v13
	v_add3_u32 v30, v33, v30, s30
	v_and_or_b32 v135, v30, s31, v13
	v_bfe_u32 v13, v10, 16, 1
	v_add3_u32 v10, v10, v13, s30
	v_bfe_u32 v13, v11, 16, 1
	v_lshrrev_b32_e32 v10, 16, v10
	v_add3_u32 v11, v11, v13, s30
	v_and_or_b32 v136, v11, s31, v10
	v_bfe_u32 v10, v12, 16, 1
	v_add3_u32 v10, v12, v10, s30
	v_lshrrev_b32_e32 v30, 16, v10
	v_mfma_f32_16x16x32_bf16 v[10:13], v[22:25], v[6:9], 0
	v_cmp_le_i32_e64 s[0:1], v167, v160
	v_bfe_u32 v31, v137, 16, 1
	v_add3_u32 v31, v137, v31, s30
	v_mfma_f32_16x16x32_bf16 v[6:9], v[26:29], v[6:9], 0
	v_and_or_b32 v137, v31, s31, v30
	s_nop 2
	v_cndmask_b32_e64 v10, v10, 0, s[10:11]
	s_nop 2
	v_cndmask_b32_e64 v6, 0, v6, s[0:1]
	v_cmp_le_i32_e64 s[0:1], v155, v160
	s_nop 1
	v_cndmask_b32_e64 v11, 0, v11, s[0:1]
	v_cmp_le_i32_e64 s[0:1], v154, v160
	s_nop 1
	v_cndmask_b32_e64 v7, 0, v7, s[0:1]
	v_cmp_le_i32_e64 s[0:1], v157, v160
	s_nop 1
	v_cndmask_b32_e64 v12, 0, v12, s[0:1]
	v_cmp_le_i32_e64 s[0:1], v156, v160
	s_nop 1
	v_cndmask_b32_e64 v8, 0, v8, s[0:1]
	v_cmp_le_i32_e64 s[0:1], v159, v160
	s_nop 1
	v_cndmask_b32_e64 v13, 0, v13, s[0:1]
	v_cmp_le_i32_e64 s[0:1], v158, v160
	s_nop 1
	v_cndmask_b32_e64 v30, 0, v9, s[0:1]
	v_bfe_u32 v9, v10, 16, 1
	v_add3_u32 v9, v10, v9, s30
	v_bfe_u32 v10, v11, 16, 1
	v_lshrrev_b32_e32 v9, 16, v9
	v_add3_u32 v10, v11, v10, s30
	v_and_or_b32 v174, v10, s31, v9
	v_bfe_u32 v9, v12, 16, 1
	v_add3_u32 v9, v12, v9, s30
	v_bfe_u32 v10, v13, 16, 1
	v_lshrrev_b32_e32 v9, 16, v9
	v_add3_u32 v10, v13, v10, s30
	v_and_or_b32 v175, v10, s31, v9
	v_bfe_u32 v9, v6, 16, 1
	v_add3_u32 v6, v6, v9, s30
	v_bfe_u32 v9, v7, 16, 1
	v_lshrrev_b32_e32 v6, 16, v6
	v_add3_u32 v7, v7, v9, s30
	v_and_or_b32 v176, v7, s31, v6
	v_bfe_u32 v6, v8, 16, 1
	v_add3_u32 v6, v8, v6, s30
	v_lshrrev_b32_e32 v10, 16, v6
	v_mfma_f32_16x16x32_bf16 v[6:9], v[22:25], v[2:5], 0
	v_bfe_u32 v11, v30, 16, 1
	v_cmp_le_i32_e64 s[0:1], v153, v152
	v_add3_u32 v11, v30, v11, s30
	v_mfma_f32_16x16x32_bf16 v[2:5], v[26:29], v[2:5], 0
	v_and_or_b32 v177, v11, s31, v10
	s_nop 2
	v_cndmask_b32_e64 v6, 0, v6, s[0:1]
	v_cmp_le_i32_e64 s[0:1], v155, v152
	s_nop 1
	v_cndmask_b32_e64 v10, v2, 0, s[10:11]
	v_cndmask_b32_e64 v2, 0, v7, s[0:1]
	v_cmp_le_i32_e64 s[0:1], v154, v152
	v_bfe_u32 v7, v6, 16, 1
	v_add3_u32 v6, v6, v7, s30
	v_cndmask_b32_e64 v11, 0, v3, s[0:1]
	v_cmp_le_i32_e64 s[0:1], v157, v152
	v_bfe_u32 v7, v2, 16, 1
	v_lshrrev_b32_e32 v6, 16, v6
	v_cndmask_b32_e64 v3, 0, v8, s[0:1]
	v_cmp_le_i32_e64 s[0:1], v156, v152
	v_add3_u32 v2, v2, v7, s30
	v_bfe_u32 v13, v3, 16, 1
	v_cndmask_b32_e64 v12, 0, v4, s[0:1]
	v_cmp_le_i32_e64 s[0:1], v159, v152
	v_and_or_b32 v2, v2, s31, v6
	v_add3_u32 v3, v3, v13, s30
	v_cndmask_b32_e64 v4, 0, v9, s[0:1]
	ds_read2_b64 v[6:9], v144 offset0:8 offset1:12
	v_bfe_u32 v13, v4, 16, 1
	v_lshrrev_b32_e32 v3, 16, v3
	v_add3_u32 v4, v4, v13, s30
	v_and_or_b32 v3, v4, s31, v3
	v_bfe_u32 v4, v10, 16, 1
	v_add3_u32 v4, v10, v4, s30
	v_bfe_u32 v10, v11, 16, 1
	v_cmp_le_i32_e64 s[0:1], v158, v152
	v_lshrrev_b32_e32 v4, 16, v4
	v_add3_u32 v10, v11, v10, s30
	v_cndmask_b32_e64 v5, 0, v5, s[0:1]
	v_and_or_b32 v4, v10, s31, v4
	v_bfe_u32 v10, v12, 16, 1
	v_add3_u32 v10, v12, v10, s30
	v_bfe_u32 v11, v5, 16, 1
	v_lshrrev_b32_e32 v10, 16, v10
	v_add3_u32 v5, v5, v11, s30
	v_and_or_b32 v5, v5, s31, v10
	s_waitcnt lgkmcnt(0)
	v_mfma_f32_16x16x32_bf16 v[22:25], v[6:9], v[14:17], v[34:37]
	v_mfma_f32_16x16x32_bf16 v[26:29], v[6:9], v[134:137], v[38:41]
	v_mfma_f32_16x16x32_bf16 v[30:33], v[6:9], v[174:177], v[42:45]
	v_mfma_f32_16x16x32_bf16 v[34:37], v[6:9], v[2:5], v[46:49]
	ds_read2_b64 v[6:9], v145 offset0:8 offset1:12
	s_waitcnt lgkmcnt(0)
	v_mfma_f32_16x16x32_bf16 v[38:41], v[6:9], v[14:17], v[50:53]
	ds_read2_b64 v[46:49], v170 offset0:8 offset1:12
	v_mfma_f32_16x16x32_bf16 v[42:45], v[6:9], v[134:137], v[54:57]
	v_mfma_f32_16x16x32_bf16 v[50:53], v[6:9], v[174:177], v[58:61]
	v_mfma_f32_16x16x32_bf16 v[54:57], v[6:9], v[2:5], v[62:65]
	ds_read2_b64 v[6:9], v171 offset0:8 offset1:12
	s_waitcnt lgkmcnt(0)
	v_mfma_f32_16x16x32_bf16 v[58:61], v[6:9], v[14:17], v[66:69]
	v_mfma_f32_16x16x32_bf16 v[62:65], v[6:9], v[134:137], v[70:73]
	v_mfma_f32_16x16x32_bf16 v[10:13], v[6:9], v[174:177], v[74:77]
	v_mfma_f32_16x16x32_bf16 v[6:9], v[6:9], v[2:5], v[78:81]
	v_mfma_f32_16x16x32_bf16 v[66:69], v[46:49], v[14:17], v[82:85]
	v_mfma_f32_16x16x32_bf16 v[70:73], v[46:49], v[134:137], v[86:89]
	v_mfma_f32_16x16x32_bf16 v[14:17], v[46:49], v[174:177], v[90:93]
	v_mfma_f32_16x16x32_bf16 v[2:5], v[46:49], v[2:5], v[18:21]
	s_or_b32 s0, s38, 4
	s_mul_i32 s10, s0, 0x104
	s_ashr_i32 s1, s37, 31
	s_mul_hi_i32 s2, s0, 0x104
	s_add_u32 s0, s10, s37
	s_addc_u32 s1, s2, s1
	s_lshl_b64 s[0:1], s[0:1], 13
	s_add_u32 s0, s23, s0
	s_addc_u32 s1, s24, s1
	v_lshl_add_u64 v[18:19], s[0:1], 0, v[96:97]
	global_load_dword v92, v[18:19], off
	global_load_dword v93, v[18:19], off offset:256
	global_load_dword v96, v[18:19], off offset:512
	global_load_dword v97, v[18:19], off offset:768
	global_load_dword v134, v[18:19], off offset:1024
	global_load_dword v135, v[18:19], off offset:1280
	global_load_dword v136, v[18:19], off offset:1536
	global_load_dword v137, v[18:19], off offset:1792
	global_load_dword v174, v[18:19], off offset:2048
	global_load_dword v175, v[18:19], off offset:2304
	global_load_dword v176, v[18:19], off offset:2560
	global_load_dword v177, v[18:19], off offset:2816
	global_load_dword v178, v[18:19], off offset:3072
	v_lshl_add_u64 v[48:49], s[0:1], 0, v[102:103]
	global_load_dword v102, v[18:19], off offset:3328
	global_load_dword v103, v[18:19], off offset:3584
	v_lshl_add_u64 v[74:75], s[0:1], 0, v[104:105]
	global_load_dword v104, v[18:19], off offset:3840
	v_lshl_add_u64 v[20:21], s[0:1], 0, v[98:99]
	v_lshl_add_u64 v[46:47], s[0:1], 0, v[100:101]
	v_lshl_add_u64 v[78:79], s[0:1], 0, v[108:109]
	global_load_dword v108, v[20:21], off
	global_load_dword v109, v[46:47], off
	v_lshl_add_u64 v[80:81], s[0:1], 0, v[112:113]
	global_load_dword v112, v[48:49], off
	v_lshl_add_u64 v[76:77], s[0:1], 0, v[106:107]
	global_load_dword v75, v[74:75], off
	v_lshl_add_u64 v[90:91], s[0:1], 0, v[132:133]
	v_lshl_add_u64 v[18:19], s[0:1], 0, v[114:115]
	v_lshl_add_u64 v[82:83], s[0:1], 0, v[116:117]
	v_lshl_add_u64 v[20:21], s[0:1], 0, v[118:119]
	v_lshl_add_u64 v[84:85], s[0:1], 0, v[122:123]
	v_lshl_add_u64 v[86:87], s[0:1], 0, v[124:125]
	v_lshl_add_u64 v[46:47], s[0:1], 0, v[126:127]
	v_lshl_add_u64 v[88:89], s[0:1], 0, v[128:129]
	v_lshl_add_u64 v[48:49], s[0:1], 0, v[130:131]
	global_load_dword v76, v[76:77], off
	s_nop 0
	global_load_dword v77, v[78:79], off
	s_nop 0
	global_load_dword v78, v[80:81], off
	global_load_dword v79, v[18:19], off
	s_nop 0
	global_load_dword v80, v[82:83], off
	global_load_dword v81, v[20:21], off
	global_load_dword v113, v[84:85], off
	global_load_dword v114, v[86:87], off
	global_load_dword v115, v[46:47], off
	global_load_dword v116, v[88:89], off
	global_load_dword v117, v[48:49], off
	s_nop 0
	global_load_dword v90, v[90:91], off
	s_add_u32 s0, s10, s35
	s_addc_u32 s1, s2, s36
	s_lshl_b64 s[0:1], s[0:1], 13
	s_add_u32 s0, s25, s0
	s_addc_u32 s1, s26, s1
	v_lshl_add_u64 v[106:107], s[0:1], 0, v[94:95]
	global_load_dwordx4 v[86:89], v[106:107], off offset:16
	global_load_dwordx4 v[98:101], v[106:107], off
	global_load_dwordx4 v[82:85], v[110:111], off
	v_cmp_ge_i32_e64 s[0:1], v161, v140
	v_or_b32_e32 v192, s33, v140
	v_readlane_b32 s36, v239, 33
	v_readlane_b32 s50, v239, 47
	v_readlane_b32 s51, v239, 48
	v_ashrrev_i32_e32 v193, 31, v192
	v_readlane_b32 s37, v239, 34
	v_readlane_b32 s38, v239, 35
	v_readlane_b32 s39, v239, 36
	v_readlane_b32 s40, v239, 37
	v_readlane_b32 s41, v239, 38
	v_readlane_b32 s42, v239, 39
	v_readlane_b32 s43, v239, 40
	v_readlane_b32 s44, v239, 41
	v_readlane_b32 s45, v239, 42
	v_readlane_b32 s46, v239, 43
	v_readlane_b32 s47, v239, 44
	v_readlane_b32 s48, v239, 45
	v_readlane_b32 s49, v239, 46
	s_waitcnt vmcnt(34)
	v_bfe_u32 v18, v92, 16, 1
	s_waitcnt vmcnt(33)
	v_bfe_u32 v19, v93, 16, 1
	s_waitcnt vmcnt(32)
	v_bfe_u32 v20, v96, 16, 1
	s_waitcnt vmcnt(31)
	v_bfe_u32 v21, v97, 16, 1
	s_waitcnt vmcnt(30)
	v_bfe_u32 v46, v134, 16, 1
	s_waitcnt vmcnt(29)
	v_bfe_u32 v47, v135, 16, 1
	v_add3_u32 v18, v92, v18, s30
	v_add3_u32 v20, v96, v20, s30
	v_add3_u32 v46, v134, v46, s30
	s_waitcnt vmcnt(26)
	v_bfe_u32 v74, v174, 16, 1
	v_add3_u32 v19, v93, v19, s30
	v_add3_u32 v21, v97, v21, s30
	v_add3_u32 v47, v135, v47, s30
	v_lshrrev_b32_e32 v18, 16, v18
	v_lshrrev_b32_e32 v20, 16, v20
	v_lshrrev_b32_e32 v46, 16, v46
	v_bfe_u32 v48, v136, 16, 1
	v_add3_u32 v74, v174, v74, s30
	v_and_or_b32 v18, v19, s31, v18
	v_and_or_b32 v19, v21, s31, v20
	v_and_or_b32 v20, v47, s31, v46
	s_waitcnt vmcnt(25)
	v_bfe_u32 v47, v175, 16, 1
	v_bfe_u32 v49, v137, 16, 1
	v_add3_u32 v48, v136, v48, s30
	v_lshrrev_b32_e32 v46, 16, v74
	v_add3_u32 v47, v175, v47, s30
	v_add3_u32 v49, v137, v49, s30
	v_lshrrev_b32_e32 v48, 16, v48
	v_and_or_b32 v46, v47, s31, v46
	s_waitcnt vmcnt(24)
	v_bfe_u32 v47, v176, 16, 1
	v_and_or_b32 v21, v49, s31, v48
	v_add3_u32 v47, v176, v47, s30
	s_waitcnt vmcnt(23)
	v_bfe_u32 v48, v177, 16, 1
	v_lshrrev_b32_e32 v47, 16, v47
	v_add3_u32 v48, v177, v48, s30
	v_and_or_b32 v47, v48, s31, v47
	s_waitcnt vmcnt(22)
	v_bfe_u32 v48, v178, 16, 1
	v_add3_u32 v48, v178, v48, s30
	s_waitcnt vmcnt(21)
	v_bfe_u32 v49, v102, 16, 1
	v_lshrrev_b32_e32 v48, 16, v48
	v_add3_u32 v49, v102, v49, s30
	v_and_or_b32 v48, v49, s31, v48
	s_waitcnt vmcnt(20)
	v_bfe_u32 v49, v103, 16, 1
	v_add3_u32 v49, v103, v49, s30
	s_waitcnt vmcnt(19)
	v_bfe_u32 v74, v104, 16, 1
	v_lshrrev_b32_e32 v49, 16, v49
	v_add3_u32 v74, v104, v74, s30
	v_and_or_b32 v49, v74, s31, v49
	s_waitcnt vmcnt(18)
	v_bfe_u32 v74, v108, 16, 1
	v_add3_u32 v74, v108, v74, s30
	s_waitcnt vmcnt(17)
	v_bfe_u32 v91, v109, 16, 1
	v_lshrrev_b32_e32 v74, 16, v74
	v_add3_u32 v91, v109, v91, s30
	v_and_or_b32 v74, v91, s31, v74
	s_waitcnt vmcnt(16)
	v_bfe_u32 v91, v112, 16, 1
	v_add3_u32 v91, v112, v91, s30
	s_waitcnt vmcnt(15)
	v_bfe_u32 v92, v75, 16, 1
	v_lshrrev_b32_e32 v91, 16, v91
	v_add3_u32 v75, v75, v92, s30
	v_and_or_b32 v75, v75, s31, v91
	s_waitcnt vmcnt(14)
	v_bfe_u32 v91, v76, 16, 1
	v_add3_u32 v76, v76, v91, s30
	s_waitcnt vmcnt(13)
	v_bfe_u32 v91, v77, 16, 1
	v_lshrrev_b32_e32 v76, 16, v76
	v_add3_u32 v77, v77, v91, s30
	v_and_or_b32 v76, v77, s31, v76
	s_waitcnt vmcnt(12)
	v_bfe_u32 v77, v78, 16, 1
	v_add3_u32 v77, v78, v77, s30
	s_waitcnt vmcnt(11)
	v_bfe_u32 v78, v79, 16, 1
	v_lshrrev_b32_e32 v77, 16, v77
	v_add3_u32 v78, v79, v78, s30
	global_load_dwordx4 v[102:105], v[110:111], off offset:256
	v_and_or_b32 v77, v78, s31, v77
	s_waitcnt vmcnt(11)
	v_bfe_u32 v78, v80, 16, 1
	v_add3_u32 v78, v80, v78, s30
	s_waitcnt vmcnt(10)
	v_bfe_u32 v79, v81, 16, 1
	v_lshrrev_b32_e32 v78, 16, v78
	v_add3_u32 v79, v81, v79, s30
	v_and_or_b32 v78, v79, s31, v78
	s_waitcnt vmcnt(9)
	v_bfe_u32 v79, v113, 16, 1
	v_add3_u32 v79, v113, v79, s30
	s_waitcnt vmcnt(8)
	v_bfe_u32 v80, v114, 16, 1
	v_lshrrev_b32_e32 v79, 16, v79
	v_add3_u32 v80, v114, v80, s30
	v_and_or_b32 v79, v80, s31, v79
	s_waitcnt vmcnt(7)
	v_bfe_u32 v80, v115, 16, 1
	v_add3_u32 v80, v115, v80, s30
	s_waitcnt vmcnt(6)
	v_bfe_u32 v81, v116, 16, 1
	v_lshrrev_b32_e32 v80, 16, v80
	v_add3_u32 v81, v116, v81, s30
	v_and_or_b32 v80, v81, s31, v80
	s_waitcnt vmcnt(5)
	v_bfe_u32 v81, v117, 16, 1
	v_add3_u32 v81, v117, v81, s30
	s_waitcnt vmcnt(4)
	v_bfe_u32 v91, v90, 16, 1
	v_lshrrev_b32_e32 v81, 16, v81
	v_add3_u32 v90, v90, v91, s30
	v_and_or_b32 v81, v90, s31, v81
	global_load_dwordx4 v[90:93], v[106:107], off offset:48
	global_load_dwordx4 v[94:97], v[106:107], off offset:32
	s_waitcnt vmcnt(5)
	v_mul_f32_e32 v87, 0x3fb8aa3b, v87
	s_waitcnt vmcnt(4)
	v_mul_f32_e32 v98, 0x3fb8aa3b, v98
	v_exp_f32_e32 v116, v87
	v_mul_f32_e32 v87, 0x3fb8aa3b, v100
	v_exp_f32_e32 v108, v98
	v_mul_f32_e32 v98, 0x3fb8aa3b, v99
	v_exp_f32_e32 v109, v87
	v_mul_f32_e32 v87, 0x3fb8aa3b, v88
	v_mul_f32_e32 v88, 0x3fb8aa3b, v101
	v_exp_f32_e32 v112, v98
	v_exp_f32_e32 v113, v88
	global_load_dwordx4 v[98:101], v[110:111], off offset:16
	s_waitcnt vmcnt(4)
	v_lshlrev_b32_e32 v115, 16, v83
	v_lshlrev_b32_e32 v114, 16, v82
	v_and_b32_e32 v83, 0xffff0000, v83
	v_and_b32_e32 v82, 0xffff0000, v82
	v_pk_mul_f32 v[114:115], v[114:115], s[18:19] op_sel_hi:[1,0]
	v_pk_mul_f32 v[82:83], v[82:83], s[18:19] op_sel_hi:[1,0]
	v_rcp_f32_e32 v118, v112
	v_pk_mul_f32 v[122:123], v[114:115], v[108:109]
	v_pk_mul_f32 v[82:83], v[82:83], v[112:113]
	v_rcp_f32_e32 v119, v113
	global_load_dwordx4 v[112:115], v[110:111], off offset:272
	v_mul_f32_e32 v86, 0x3fb8aa3b, v86
	v_mul_f32_e32 v88, 0x3fb8aa3b, v89
	v_exp_f32_e32 v86, v86
	v_exp_f32_e32 v87, v87
	v_exp_f32_e32 v117, v88
	v_rcp_f32_e32 v88, v108
	v_rcp_f32_e32 v89, v109
	v_lshlrev_b32_e32 v125, 16, v85
	v_lshlrev_b32_e32 v124, 16, v84
	v_and_b32_e32 v85, 0xffff0000, v85
	v_and_b32_e32 v84, 0xffff0000, v84
	v_pk_mul_f32 v[124:125], v[124:125], s[18:19] op_sel_hi:[1,0]
	v_pk_mul_f32 v[84:85], v[84:85], s[18:19] op_sel_hi:[1,0]
	v_pk_mul_f32 v[124:125], v[124:125], v[86:87]
	v_pk_mul_f32 v[84:85], v[84:85], v[116:117]
	s_waitcnt vmcnt(4)
	v_lshlrev_b32_e32 v109, 16, v103
	v_lshlrev_b32_e32 v108, 16, v102
	v_pk_mul_f32 v[88:89], v[88:89], v[108:109]
	v_rcp_f32_e32 v108, v86
	v_rcp_f32_e32 v109, v87
	v_and_b32_e32 v103, 0xffff0000, v103
	v_and_b32_e32 v102, 0xffff0000, v102
	v_pk_mul_f32 v[102:103], v[118:119], v[102:103]
	v_rcp_f32_e32 v118, v116
	v_rcp_f32_e32 v119, v117
	v_lshlrev_b32_e32 v87, 16, v105
	v_lshlrev_b32_e32 v86, 16, v104
	v_bfe_u32 v116, v83, 16, 1
	v_pk_mul_f32 v[86:87], v[108:109], v[86:87]
	v_bfe_u32 v108, v85, 16, 1
	v_add3_u32 v83, v83, v116, s30
	v_bfe_u32 v116, v124, 16, 1
	v_bfe_u32 v109, v84, 16, 1
	v_bfe_u32 v117, v82, 16, 1
	v_add3_u32 v85, v85, v108, s30
	v_bfe_u32 v108, v122, 16, 1
	v_add3_u32 v116, v124, v116, s30
	v_and_b32_e32 v105, 0xffff0000, v105
	v_and_b32_e32 v104, 0xffff0000, v104
	v_add3_u32 v82, v82, v117, s30
	v_add3_u32 v84, v84, v109, s30
	v_bfe_u32 v109, v123, 16, 1
	v_bfe_u32 v117, v125, 16, 1
	v_add3_u32 v108, v122, v108, s30
	v_lshrrev_b32_e32 v116, 16, v116
	v_pk_mul_f32 v[104:105], v[118:119], v[104:105]
	v_add3_u32 v117, v125, v117, s30
	v_add3_u32 v109, v123, v109, s30
	v_lshrrev_b32_e32 v108, 16, v108
	v_and_or_b32 v84, v84, s31, v116
	v_bfe_u32 v116, v103, 16, 1
	v_lshrrev_b32_e32 v109, 16, v109
	v_lshrrev_b32_e32 v117, 16, v117
	v_and_or_b32 v82, v82, s31, v108
	v_bfe_u32 v108, v105, 16, 1
	v_add3_u32 v103, v103, v116, s30
	v_bfe_u32 v116, v86, 16, 1
	v_and_or_b32 v85, v85, s31, v117
	v_and_or_b32 v83, v83, s31, v109
	v_bfe_u32 v109, v104, 16, 1
	v_bfe_u32 v117, v102, 16, 1
	v_add3_u32 v105, v105, v108, s30
	v_bfe_u32 v108, v88, 16, 1
	v_add3_u32 v86, v86, v116, s30
	v_add3_u32 v102, v102, v117, s30
	v_add3_u32 v104, v104, v109, s30
	v_bfe_u32 v109, v89, 16, 1
	v_bfe_u32 v117, v87, 16, 1
	v_add3_u32 v88, v88, v108, s30
	v_lshrrev_b32_e32 v86, 16, v86
	s_waitcnt vmcnt(3)
	v_mul_f32_e32 v91, 0x3fb8aa3b, v91
	v_add3_u32 v87, v87, v117, s30
	v_add3_u32 v89, v89, v109, s30
	v_lshrrev_b32_e32 v108, 16, v88
	v_and_or_b32 v88, v104, s31, v86
	s_waitcnt vmcnt(2)
	v_mul_f32_e32 v94, 0x3fb8aa3b, v94
	v_mul_f32_e32 v95, 0x3fb8aa3b, v95
	v_exp_f32_e32 v104, v91
	v_mul_f32_e32 v91, 0x3fb8aa3b, v96
	v_lshrrev_b32_e32 v109, 16, v89
	v_lshrrev_b32_e32 v87, 16, v87
	v_and_or_b32 v86, v102, s31, v108
	v_exp_f32_e32 v94, v94
	v_exp_f32_e32 v102, v95
	v_exp_f32_e32 v95, v91
	v_mul_f32_e32 v91, 0x3fb8aa3b, v92
	v_mul_f32_e32 v92, 0x3fb8aa3b, v97
	v_and_or_b32 v89, v105, s31, v87
	v_and_or_b32 v87, v103, s31, v109
	v_exp_f32_e32 v103, v92
	v_mul_f32_e32 v90, 0x3fb8aa3b, v90
	global_load_dwordx4 v[116:119], v[106:107], off offset:80
	global_load_dwordx4 v[122:125], v[106:107], off offset:64
	v_exp_f32_e32 v90, v90
	v_exp_f32_e32 v91, v91
	v_mul_f32_e32 v92, 0x3fb8aa3b, v93
	s_waitcnt vmcnt(3)
	v_lshlrev_b32_e32 v109, 16, v99
	v_lshlrev_b32_e32 v108, 16, v98
	v_and_b32_e32 v99, 0xffff0000, v99
	v_and_b32_e32 v98, 0xffff0000, v98
	v_exp_f32_e32 v105, v92
	v_rcp_f32_e32 v92, v94
	v_pk_mul_f32 v[98:99], v[98:99], s[18:19] op_sel_hi:[1,0]
	v_rcp_f32_e32 v93, v95
	v_pk_mul_f32 v[126:127], v[98:99], v[102:103]
	v_lshlrev_b32_e32 v99, 16, v101
	v_lshlrev_b32_e32 v98, 16, v100
	v_pk_mul_f32 v[108:109], v[108:109], s[18:19] op_sel_hi:[1,0]
	v_pk_mul_f32 v[98:99], v[98:99], s[18:19] op_sel_hi:[1,0]
	v_pk_mul_f32 v[108:109], v[108:109], v[94:95]
	s_waitcnt vmcnt(2)
	v_lshlrev_b32_e32 v95, 16, v113
	v_lshlrev_b32_e32 v94, 16, v112
	v_pk_mul_f32 v[128:129], v[98:99], v[90:91]
	v_and_b32_e32 v99, 0xffff0000, v101
	v_and_b32_e32 v98, 0xffff0000, v100
	v_pk_mul_f32 v[94:95], v[92:93], v[94:95]
	v_and_b32_e32 v93, 0xffff0000, v113
	v_and_b32_e32 v92, 0xffff0000, v112
	v_pk_mul_f32 v[112:113], v[98:99], s[18:19] op_sel_hi:[1,0]
	global_load_dwordx4 v[98:101], v[110:111], off offset:32
	v_rcp_f32_e32 v96, v102
	v_rcp_f32_e32 v97, v103
	v_rcp_f32_e32 v102, v104
	v_rcp_f32_e32 v103, v105
	v_pk_mul_f32 v[130:131], v[112:113], v[104:105]
	v_pk_mul_f32 v[96:97], v[96:97], v[92:93]
	v_rcp_f32_e32 v92, v90
	v_rcp_f32_e32 v93, v91
	v_lshlrev_b32_e32 v91, 16, v115
	v_lshlrev_b32_e32 v90, 16, v114
	v_pk_mul_f32 v[104:105], v[92:93], v[90:91]
	v_and_b32_e32 v91, 0xffff0000, v115
	v_and_b32_e32 v90, 0xffff0000, v114
	global_load_dwordx4 v[112:115], v[110:111], off offset:288
	v_pk_mul_f32 v[102:103], v[102:103], v[90:91]
	v_bfe_u32 v90, v131, 16, 1
	v_bfe_u32 v91, v130, 16, 1
	v_bfe_u32 v92, v127, 16, 1
	v_bfe_u32 v93, v126, 16, 1
	v_add3_u32 v126, v126, v93, s30
	v_add3_u32 v127, v127, v92, s30
	v_add3_u32 v91, v130, v91, s30
	v_add3_u32 v90, v131, v90, s30
	v_bfe_u32 v92, v108, 16, 1
	v_bfe_u32 v93, v109, 16, 1
	v_bfe_u32 v130, v128, 16, 1
	v_bfe_u32 v131, v129, 16, 1
	v_add3_u32 v129, v129, v131, s30
	v_add3_u32 v128, v128, v130, s30
	v_add3_u32 v93, v109, v93, s30
	v_add3_u32 v92, v108, v92, s30
	v_lshrrev_b32_e32 v108, 16, v92
	v_lshrrev_b32_e32 v109, 16, v93
	v_lshrrev_b32_e32 v92, 16, v128
	v_lshrrev_b32_e32 v93, 16, v129
	v_and_or_b32 v93, v90, s31, v93
	v_and_or_b32 v92, v91, s31, v92
	v_and_or_b32 v91, v127, s31, v109
	v_and_or_b32 v90, v126, s31, v108
	v_bfe_u32 v108, v103, 16, 1
	v_bfe_u32 v109, v102, 16, 1
	v_bfe_u32 v126, v97, 16, 1
	v_bfe_u32 v127, v96, 16, 1
	v_add3_u32 v127, v96, v127, s30
	v_add3_u32 v126, v97, v126, s30
	v_add3_u32 v96, v102, v109, s30
	v_add3_u32 v97, v103, v108, s30
	v_bfe_u32 v103, v95, 16, 1
	v_bfe_u32 v108, v104, 16, 1
	v_bfe_u32 v109, v105, 16, 1
	v_bfe_u32 v102, v94, 16, 1
	v_add3_u32 v105, v105, v109, s30
	v_add3_u32 v104, v104, v108, s30
	v_add3_u32 v95, v95, v103, s30
	v_add3_u32 v94, v94, v102, s30
	v_lshrrev_b32_e32 v95, 16, v95
	v_lshrrev_b32_e32 v102, 16, v104
	v_lshrrev_b32_e32 v103, 16, v105
	s_waitcnt vmcnt(3)
	v_mul_f32_e32 v116, 0x3fb8aa3b, v116
	v_and_or_b32 v97, v97, s31, v103
	v_and_or_b32 v96, v96, s31, v102
	v_and_or_b32 v95, v126, s31, v95
	global_load_dwordx4 v[102:105], v[106:107], off offset:112
	s_nop 0
	global_load_dwordx4 v[106:109], v[106:107], off offset:96
	v_exp_f32_e32 v126, v116
	s_waitcnt vmcnt(4)
	v_mul_f32_e32 v116, 0x3fb8aa3b, v123
	v_exp_f32_e32 v128, v116
	v_mul_f32_e32 v116, 0x3fb8aa3b, v117
	v_exp_f32_e32 v130, v116
	v_mul_f32_e32 v116, 0x3fb8aa3b, v124
	v_lshrrev_b32_e32 v94, 16, v94
	v_mul_f32_e32 v122, 0x3fb8aa3b, v122
	v_exp_f32_e32 v123, v116
	v_mul_f32_e32 v116, 0x3fb8aa3b, v118
	v_and_or_b32 v94, v127, s31, v94
	v_exp_f32_e32 v122, v122
	v_exp_f32_e32 v127, v116
	v_mul_f32_e32 v116, 0x3fb8aa3b, v125
	v_exp_f32_e32 v129, v116
	v_mul_f32_e32 v116, 0x3fb8aa3b, v119
	v_exp_f32_e32 v131, v116
	global_load_dwordx4 v[116:119], v[110:111], off offset:48
	s_waitcnt vmcnt(4)
	v_lshlrev_b32_e32 v125, 16, v99
	v_lshlrev_b32_e32 v124, 16, v98
	v_pk_mul_f32 v[124:125], v[124:125], s[18:19] op_sel_hi:[1,0]
	v_rcp_f32_e32 v132, v122
	v_pk_mul_f32 v[136:137], v[124:125], v[122:123]
	v_rcp_f32_e32 v133, v123
	global_load_dwordx4 v[122:125], v[110:111], off offset:304
	v_rcp_f32_e32 v134, v128
	v_rcp_f32_e32 v135, v129
	v_and_b32_e32 v99, 0xffff0000, v99
	v_and_b32_e32 v98, 0xffff0000, v98
	v_pk_mul_f32 v[98:99], v[98:99], s[18:19] op_sel_hi:[1,0]
	s_waitcnt vmcnt(4)
	v_lshlrev_b32_e32 v111, 16, v113
	v_pk_mul_f32 v[98:99], v[98:99], v[128:129]
	v_lshlrev_b32_e32 v110, 16, v112
	v_and_b32_e32 v113, 0xffff0000, v113
	v_and_b32_e32 v112, 0xffff0000, v112
	v_rcp_f32_e32 v128, v126
	v_rcp_f32_e32 v129, v127
	v_pk_mul_f32 v[112:113], v[134:135], v[112:113]
	v_lshlrev_b32_e32 v135, 16, v101
	v_lshlrev_b32_e32 v134, 16, v100
	v_and_b32_e32 v101, 0xffff0000, v101
	v_and_b32_e32 v100, 0xffff0000, v100
	v_pk_mul_f32 v[134:135], v[134:135], s[18:19] op_sel_hi:[1,0]
	v_pk_mul_f32 v[100:101], v[100:101], s[18:19] op_sel_hi:[1,0]
	v_pk_mul_f32 v[110:111], v[132:133], v[110:111]
	v_rcp_f32_e32 v132, v130
	v_pk_mul_f32 v[134:135], v[134:135], v[126:127]
	v_pk_mul_f32 v[100:101], v[100:101], v[130:131]
	v_rcp_f32_e32 v133, v131
	v_lshlrev_b32_e32 v127, 16, v115
	v_lshlrev_b32_e32 v126, 16, v114
	v_pk_mul_f32 v[126:127], v[128:129], v[126:127]
	v_bfe_u32 v128, v101, 16, 1
	v_bfe_u32 v130, v99, 16, 1
	v_bfe_u32 v129, v100, 16, 1
	v_bfe_u32 v131, v98, 16, 1
	v_add3_u32 v99, v99, v130, s30
	v_add3_u32 v101, v101, v128, s30
	v_bfe_u32 v128, v136, 16, 1
	v_bfe_u32 v130, v134, 16, 1
	v_and_b32_e32 v115, 0xffff0000, v115
	v_and_b32_e32 v114, 0xffff0000, v114
	v_add3_u32 v98, v98, v131, s30
	v_add3_u32 v100, v100, v129, s30
	v_bfe_u32 v129, v137, 16, 1
	v_bfe_u32 v131, v135, 16, 1
	v_add3_u32 v130, v134, v130, s30
	v_add3_u32 v128, v136, v128, s30
	v_pk_mul_f32 v[114:115], v[132:133], v[114:115]
	v_add3_u32 v131, v135, v131, s30
	v_add3_u32 v129, v137, v129, s30
	v_lshrrev_b32_e32 v128, 16, v128
	v_lshrrev_b32_e32 v130, 16, v130
	v_lshrrev_b32_e32 v129, 16, v129
	v_lshrrev_b32_e32 v131, 16, v131
	v_and_or_b32 v100, v100, s31, v130
	v_and_or_b32 v98, v98, s31, v128
	v_bfe_u32 v128, v115, 16, 1
	v_bfe_u32 v130, v113, 16, 1
	v_and_or_b32 v101, v101, s31, v131
	v_and_or_b32 v99, v99, s31, v129
	v_bfe_u32 v129, v114, 16, 1
	v_bfe_u32 v131, v112, 16, 1
	v_add3_u32 v130, v113, v130, s30
	v_add3_u32 v113, v115, v128, s30
	v_bfe_u32 v128, v126, 16, 1
	v_add3_u32 v131, v112, v131, s30
	v_add3_u32 v112, v114, v129, s30
	v_bfe_u32 v114, v110, 16, 1
	v_bfe_u32 v129, v127, 16, 1
	v_add3_u32 v126, v126, v128, s30
	s_waitcnt vmcnt(3)
	v_mul_f32_e32 v103, 0x3fb8aa3b, v103
	v_bfe_u32 v115, v111, 16, 1
	v_add3_u32 v127, v127, v129, s30
	v_add3_u32 v110, v110, v114, s30
	v_lshrrev_b32_e32 v114, 16, v126
	s_waitcnt vmcnt(2)
	v_mul_f32_e32 v106, 0x3fb8aa3b, v106
	v_mul_f32_e32 v107, 0x3fb8aa3b, v107
	v_exp_f32_e32 v126, v103
	v_mul_f32_e32 v103, 0x3fb8aa3b, v108
	v_add3_u32 v111, v111, v115, s30
	v_lshrrev_b32_e32 v115, 16, v127
	v_and_or_b32 v112, v112, s31, v114
	v_exp_f32_e32 v106, v106
	v_exp_f32_e32 v114, v107
	v_exp_f32_e32 v107, v103
	v_mul_f32_e32 v103, 0x3fb8aa3b, v104
	v_mul_f32_e32 v104, 0x3fb8aa3b, v109
	v_and_or_b32 v113, v113, s31, v115
	v_exp_f32_e32 v115, v104
	v_mul_f32_e32 v104, 0x3fb8aa3b, v105
	v_mul_f32_e32 v102, 0x3fb8aa3b, v102
	v_exp_f32_e32 v127, v104
	v_rcp_f32_e32 v104, v106
	v_rcp_f32_e32 v105, v107
	v_exp_f32_e32 v102, v102
	v_exp_f32_e32 v103, v103
	v_rcp_f32_e32 v108, v114
	s_waitcnt vmcnt(1)
	v_lshlrev_b32_e32 v129, 16, v117
	v_lshlrev_b32_e32 v128, 16, v116
	v_rcp_f32_e32 v109, v115
	v_pk_mul_f32 v[128:129], v[128:129], s[18:19] op_sel_hi:[1,0]
	v_and_b32_e32 v117, 0xffff0000, v117
	v_pk_mul_f32 v[128:129], v[128:129], v[106:107]
	s_waitcnt vmcnt(0)
	v_lshlrev_b32_e32 v107, 16, v123
	v_lshlrev_b32_e32 v106, 16, v122
	v_and_b32_e32 v116, 0xffff0000, v116
	v_pk_mul_f32 v[106:107], v[104:105], v[106:107]
	v_and_b32_e32 v105, 0xffff0000, v123
	v_and_b32_e32 v104, 0xffff0000, v122
	v_pk_mul_f32 v[116:117], v[116:117], s[18:19] op_sel_hi:[1,0]
	v_pk_mul_f32 v[108:109], v[108:109], v[104:105]
	v_rcp_f32_e32 v104, v102
	v_rcp_f32_e32 v105, v103
	v_pk_mul_f32 v[116:117], v[116:117], v[114:115]
	v_rcp_f32_e32 v114, v126
	v_lshlrev_b32_e32 v123, 16, v119
	v_lshlrev_b32_e32 v122, 16, v118
	v_rcp_f32_e32 v115, v127
	v_pk_mul_f32 v[122:123], v[122:123], s[18:19] op_sel_hi:[1,0]
	v_and_b32_e32 v119, 0xffff0000, v119
	v_and_b32_e32 v118, 0xffff0000, v118
	v_pk_mul_f32 v[122:123], v[122:123], v[102:103]
	v_pk_mul_f32 v[118:119], v[118:119], s[18:19] op_sel_hi:[1,0]
	v_lshlrev_b32_e32 v103, 16, v125
	v_lshlrev_b32_e32 v102, 16, v124
	v_pk_mul_f32 v[118:119], v[118:119], v[126:127]
	v_pk_mul_f32 v[126:127], v[104:105], v[102:103]
	v_and_b32_e32 v103, 0xffff0000, v125
	v_and_b32_e32 v102, 0xffff0000, v124
	v_pk_mul_f32 v[114:115], v[114:115], v[102:103]
	v_bfe_u32 v102, v119, 16, 1
	v_bfe_u32 v103, v118, 16, 1
	v_bfe_u32 v104, v117, 16, 1
	v_bfe_u32 v105, v116, 16, 1
	v_add3_u32 v116, v116, v105, s30
	v_add3_u32 v117, v117, v104, s30
	v_add3_u32 v103, v118, v103, s30
	v_add3_u32 v102, v119, v102, s30
	v_bfe_u32 v104, v128, 16, 1
	v_bfe_u32 v105, v129, 16, 1
	v_bfe_u32 v118, v122, 16, 1
	v_bfe_u32 v119, v123, 16, 1
	v_add3_u32 v119, v123, v119, s30
	v_add3_u32 v118, v122, v118, s30
	v_add3_u32 v105, v129, v105, s30
	v_add3_u32 v104, v128, v104, s30
	v_lshrrev_b32_e32 v122, 16, v104
	v_lshrrev_b32_e32 v123, 16, v105
	v_lshrrev_b32_e32 v104, 16, v118
	v_lshrrev_b32_e32 v105, 16, v119
	v_and_or_b32 v105, v102, s31, v105
	v_and_or_b32 v104, v103, s31, v104
	v_and_or_b32 v103, v117, s31, v123
	v_and_or_b32 v102, v116, s31, v122
	v_bfe_u32 v116, v115, 16, 1
	v_bfe_u32 v117, v114, 16, 1
	v_bfe_u32 v118, v109, 16, 1
	v_bfe_u32 v119, v108, 16, 1
	v_add3_u32 v119, v108, v119, s30
	v_add3_u32 v118, v109, v118, s30
	v_add3_u32 v108, v114, v117, s30
	v_add3_u32 v109, v115, v116, s30
	v_bfe_u32 v114, v106, 16, 1
	v_bfe_u32 v115, v107, 16, 1
	v_bfe_u32 v116, v126, 16, 1
	v_bfe_u32 v117, v127, 16, 1
	v_add3_u32 v117, v127, v117, s30
	v_add3_u32 v116, v126, v116, s30
	v_add3_u32 v107, v107, v115, s30
	v_add3_u32 v106, v106, v114, s30
	v_lshrrev_b32_e32 v110, 16, v110
	v_lshrrev_b32_e32 v111, 16, v111
	v_lshrrev_b32_e32 v106, 16, v106
	v_lshrrev_b32_e32 v107, 16, v107
	v_lshrrev_b32_e32 v114, 16, v116
	v_lshrrev_b32_e32 v115, 16, v117
	s_waitcnt lgkmcnt(0)
	ds_write_b128 v142, v[82:85]
	ds_write_b128 v142, v[90:93] offset:16
	ds_write_b128 v142, v[98:101] offset:32
	ds_write_b128 v142, v[102:105] offset:48
	ds_write_b128 v142, v[18:21] offset:4096
	ds_write_b128 v142, v[46:49] offset:4112
	ds_write_b128 v142, v[74:77] offset:4128
	ds_write_b128 v142, v[78:81] offset:4144
	v_and_or_b32 v111, v130, s31, v111
	v_and_or_b32 v110, v131, s31, v110
	v_and_or_b32 v109, v109, s31, v115
	v_and_or_b32 v108, v108, s31, v114
	v_and_or_b32 v107, v118, s31, v107
	v_and_or_b32 v106, v119, s31, v106
	s_waitcnt lgkmcnt(0)
	ds_read_b128 v[134:137], v172
	ds_read_b128 v[98:101], v172 offset:1024
	ds_read_b128 v[46:49], v172 offset:2048
	ds_read_b128 v[18:21], v172 offset:3072
	s_waitcnt lgkmcnt(0)
	ds_write_b128 v142, v[86:89]
	ds_write_b128 v142, v[94:97] offset:16
	ds_write_b128 v142, v[110:113] offset:32
	ds_write_b128 v142, v[106:109] offset:48
	s_waitcnt lgkmcnt(0)
	ds_read_b128 v[78:81], v172 offset:4096
	ds_read_b128 v[82:85], v172
	s_waitcnt lgkmcnt(1)
	v_mfma_f32_16x16x32_bf16 v[110:113], v[78:81], v[98:101], v[26:29]
	s_nop 2
	ds_read_b128 v[26:29], v172 offset:5120
	ds_read_b128 v[94:97], v172 offset:6144
	ds_read_b128 v[90:93], v172 offset:7168
	ds_read_b128 v[86:89], v143 offset:1024
	v_mfma_f32_16x16x32_bf16 v[74:77], v[78:81], v[46:49], v[30:33]
	s_waitcnt lgkmcnt(3)
	v_mfma_f32_16x16x32_bf16 v[30:33], v[26:29], v[134:137], v[38:41]
	s_waitcnt lgkmcnt(0)
	v_mfma_f32_16x16x32_bf16 v[38:41], v[86:89], v[134:137], 0
	v_mfma_f32_16x16x32_bf16 v[122:125], v[78:81], v[134:137], v[22:25]
	v_mfma_f32_16x16x32_bf16 v[22:25], v[78:81], v[18:21], v[34:37]
	s_nop 5
	v_cndmask_b32_e64 v38, 0, v38, s[0:1]
	v_cmp_ge_i32_e64 s[0:1], v169, v140
	v_mfma_f32_16x16x32_bf16 v[34:37], v[82:85], v[134:137], 0
	v_mfma_f32_16x16x32_bf16 v[114:117], v[26:29], v[98:101], v[42:45]
	v_mfma_f32_16x16x32_bf16 v[102:105], v[90:93], v[98:101], v[70:73]
	s_nop 5
	v_cndmask_b32_e64 v34, v34, 0, vcc
	v_cndmask_b32_e64 v35, 0, v35, s[0:1]
	v_cmp_ge_i32_e64 s[0:1], v162, v140
	v_bfe_u32 v42, v34, 16, 1
	v_add3_u32 v34, v34, v42, s30
	v_cndmask_b32_e64 v39, 0, v39, s[0:1]
	v_cmp_ge_i32_e64 s[0:1], v164, v140
	v_bfe_u32 v42, v35, 16, 1
	v_lshrrev_b32_e32 v34, 16, v34
	v_cndmask_b32_e64 v36, 0, v36, s[0:1]
	v_cmp_ge_i32_e64 s[0:1], v163, v140
	v_add3_u32 v35, v35, v42, s30
	v_and_or_b32 v70, v35, s31, v34
	v_cndmask_b32_e64 v40, 0, v40, s[0:1]
	v_cmp_ge_i32_e64 s[0:1], v166, v140
	v_bfe_u32 v34, v36, 16, 1
	v_add3_u32 v34, v36, v34, s30
	v_cndmask_b32_e64 v37, 0, v37, s[0:1]
	v_bfe_u32 v35, v37, 16, 1
	v_lshrrev_b32_e32 v34, 16, v34
	v_add3_u32 v35, v37, v35, s30
	v_and_or_b32 v71, v35, s31, v34
	v_bfe_u32 v34, v38, 16, 1
	v_add3_u32 v34, v38, v34, s30
	v_bfe_u32 v35, v39, 16, 1
	v_cmp_ge_i32_e64 s[0:1], v165, v140
	v_lshrrev_b32_e32 v34, 16, v34
	v_add3_u32 v35, v39, v35, s30
	v_cndmask_b32_e64 v41, 0, v41, s[0:1]
	v_and_or_b32 v72, v35, s31, v34
	v_bfe_u32 v34, v40, 16, 1
	v_add3_u32 v34, v40, v34, s30
	v_bfe_u32 v39, v41, 16, 1
	v_lshrrev_b32_e32 v38, 16, v34
	v_add3_u32 v39, v41, v39, s30
	v_mfma_f32_16x16x32_bf16 v[78:81], v[26:29], v[46:49], v[50:53]
	v_and_or_b32 v73, v39, s31, v38
	v_cmp_ge_i32_e64 s[0:1], v169, v168
	v_mfma_f32_16x16x32_bf16 v[50:53], v[94:97], v[134:137], v[58:61]
	v_mfma_f32_16x16x32_bf16 v[106:109], v[94:97], v[98:101], v[62:65]
	s_nop 1
	ds_read2_b64 v[58:61], v144 offset1:4
	v_mfma_f32_16x16x32_bf16 v[34:37], v[82:85], v[98:101], 0
	ds_read2_b64 v[62:65], v145 offset1:4
	v_mfma_f32_16x16x32_bf16 v[38:41], v[86:89], v[98:101], 0
	v_mfma_f32_16x16x32_bf16 v[26:29], v[26:29], v[18:21], v[54:57]
	s_nop 4
	v_cndmask_b32_e64 v34, v34, 0, s[8:9]
	s_nop 0
	v_cndmask_b32_e64 v142, v38, 0, vcc
	v_cndmask_b32_e64 v38, 0, v35, s[0:1]
	v_mfma_f32_16x16x32_bf16 v[54:57], v[90:93], v[134:137], v[66:69]
	v_cmp_ge_i32_e64 s[0:1], v162, v168
	v_bfe_u32 v35, v34, 16, 1
	v_add3_u32 v34, v34, v35, s30
	ds_read2_b64 v[66:69], v171 offset1:4
	v_cndmask_b32_e64 v174, 0, v39, s[0:1]
	v_cmp_ge_i32_e64 s[0:1], v164, v168
	v_lshrrev_b32_e32 v39, 16, v34
	s_waitcnt lgkmcnt(0)
	v_mfma_f32_16x16x32_bf16 v[126:129], v[66:69], v[70:73], v[50:53]
	v_cndmask_b32_e64 v42, 0, v36, s[0:1]
	v_cmp_ge_i32_e64 s[0:1], v163, v168
	v_bfe_u32 v188, v174, 16, 1
	s_add_u32 s8, s27, s20
	v_cndmask_b32_e64 v172, 0, v40, s[0:1]
	v_cmp_ge_i32_e64 s[0:1], v166, v168
	v_bfe_u32 v40, v38, 16, 1
	v_add3_u32 v38, v38, v40, s30
	v_cndmask_b32_e64 v119, 0, v37, s[0:1]
	v_cmp_ge_i32_e64 s[0:1], v165, v168
	v_mfma_f32_16x16x32_bf16 v[34:37], v[58:61], v[70:73], v[122:125]
	v_and_or_b32 v118, v38, s31, v39
	v_cndmask_b32_e64 v175, 0, v41, s[0:1]
	ds_read2_b64 v[38:41], v170 offset1:4
	v_mfma_f32_16x16x32_bf16 v[122:125], v[62:65], v[70:73], v[30:33]
	v_bfe_u32 v51, v119, 16, 1
	v_add3_u32 v51, v119, v51, s30
	v_cmp_ge_i32_e64 s[0:1], v153, v140
	v_bfe_u32 v30, v42, 16, 1
	v_add3_u32 v30, v42, v30, s30
	ds_read_b128 v[42:45], v173
	v_lshrrev_b32_e32 v50, 16, v30
	ds_read_b128 v[30:33], v143 offset:3072
	s_waitcnt lgkmcnt(2)
	v_mfma_f32_16x16x32_bf16 v[130:133], v[38:41], v[70:73], v[54:57]
	v_and_or_b32 v119, v51, s31, v50
	s_addc_u32 s9, s28, 0
	s_nop 0
	v_bfe_u32 v54, v142, 16, 1
	s_waitcnt lgkmcnt(1)
	v_mfma_f32_16x16x32_bf16 v[50:53], v[42:45], v[134:137], 0
	v_add3_u32 v54, v142, v54, s30
	v_lshrrev_b32_e32 v173, 16, v54
	s_waitcnt lgkmcnt(0)
	v_mfma_f32_16x16x32_bf16 v[54:57], v[30:33], v[134:137], 0
	s_nop 3
	v_cndmask_b32_e64 v50, 0, v50, s[0:1]
	v_cmp_ge_i32_e64 s[0:1], v167, v140
	v_lshlrev_b64 v[136:137], 1, v[120:121]
	v_lshl_add_u64 v[134:135], v[120:121], 2, s[50:51]
	global_load_dwordx4 v[180:183], v[134:135], off offset:256
	v_cndmask_b32_e64 v54, 0, v54, s[0:1]
	v_cmp_ge_i32_e64 s[0:1], v155, v140
	v_bfe_u32 v121, v172, 16, 1
	v_add3_u32 v121, v172, v121, s30
	v_cndmask_b32_e64 v51, 0, v51, s[0:1]
	v_cmp_ge_i32_e64 s[0:1], v154, v140
	v_bfe_u32 v70, v51, 16, 1
	v_add3_u32 v51, v51, v70, s30
	v_cndmask_b32_e64 v55, 0, v55, s[0:1]
	v_cmp_ge_i32_e64 s[0:1], v157, v140
	v_bfe_u32 v70, v50, 16, 1
	v_add3_u32 v50, v50, v70, s30
	v_cndmask_b32_e64 v52, 0, v52, s[0:1]
	v_cmp_ge_i32_e64 s[0:1], v156, v140
	v_lshrrev_b32_e32 v50, 16, v50
	v_and_or_b32 v176, v51, s31, v50
	v_cndmask_b32_e64 v56, 0, v56, s[0:1]
	v_cmp_ge_i32_e64 s[0:1], v159, v140
	v_bfe_u32 v51, v52, 16, 1
	v_add3_u32 v51, v52, v51, s30
	v_cndmask_b32_e64 v53, 0, v53, s[0:1]
	v_bfe_u32 v50, v53, 16, 1
	v_cmp_ge_i32_e64 s[0:1], v158, v140
	v_add3_u32 v50, v53, v50, s30
	v_lshrrev_b32_e32 v51, 16, v51
	v_cndmask_b32_e64 v57, 0, v57, s[0:1]
	v_and_or_b32 v177, v50, s31, v51
	v_mad_i64_i32 v[50:51], s[0:1], v192, s29, v[138:139]
	v_lshl_add_u64 v[50:51], v[50:51], 0, s[20:21]
	v_lshl_add_u64 v[142:143], v[50:51], 0, v[136:137]
	global_load_dwordx2 v[194:195], v[142:143], off offset:1024
	s_mov_b32 s100, 0x16400
	s_mov_b32 s101, 0
	global_load_dwordx4 v[230:233], v[134:135], off offset:256
	global_load_dwordx4 v[234:237], v[134:135], off offset:320
	global_load_dwordx4 v[240:243], v[134:135], off offset:384
	global_load_dwordx4 v[244:247], v[134:135], off offset:448
	global_load_dwordx2 v[196:197], v[142:143], off offset:1056
	global_load_dwordx2 v[198:199], v[142:143], off offset:1088
	global_load_dwordx2 v[200:201], v[142:143], off offset:1120
	v_lshl_add_u64 v[226:227], v[142:143], 0, s[100:101]
	global_load_dwordx2 v[202:203], v[226:227], off offset:1024
	global_load_dwordx2 v[204:205], v[226:227], off offset:1056
	global_load_dwordx2 v[206:207], v[226:227], off offset:1088
	global_load_dwordx2 v[208:209], v[226:227], off offset:1120
	v_lshl_add_u64 v[226:227], v[226:227], 0, s[100:101]
	global_load_dwordx2 v[210:211], v[226:227], off offset:1024
	global_load_dwordx2 v[212:213], v[226:227], off offset:1056
	global_load_dwordx2 v[214:215], v[226:227], off offset:1088
	global_load_dwordx2 v[216:217], v[226:227], off offset:1120
	v_lshl_add_u64 v[226:227], v[226:227], 0, s[100:101]
	global_load_dwordx2 v[218:219], v[226:227], off offset:1024
	global_load_dwordx2 v[220:221], v[226:227], off offset:1056
	global_load_dwordx2 v[222:223], v[226:227], off offset:1088
	global_load_dwordx2 v[224:225], v[226:227], off offset:1120
	v_bfe_u32 v51, v54, 16, 1
	ds_read2_b64 v[70:73], v144 offset0:8 offset1:12
	v_bfe_u32 v50, v55, 16, 1
	v_add3_u32 v51, v54, v51, s30
	v_add3_u32 v50, v55, v50, s30
	v_lshrrev_b32_e32 v51, 16, v51
	v_and_or_b32 v178, v50, s31, v51
	v_bfe_u32 v50, v57, 16, 1
	v_bfe_u32 v51, v56, 16, 1
	v_add3_u32 v50, v57, v50, s30
	v_add3_u32 v51, v56, v51, s30
	ds_read2_b64 v[54:57], v145 offset0:8 offset1:12
	v_lshrrev_b32_e32 v51, 16, v51
	v_and_or_b32 v179, v50, s31, v51
	ds_read2_b64 v[50:53], v171 offset0:8 offset1:12
	v_lshrrev_b32_e32 v121, 16, v121
	s_waitcnt lgkmcnt(2)
	v_mfma_f32_16x16x32_bf16 v[184:187], v[70:73], v[176:179], v[34:37]
	v_cmp_lt_i32_e64 s[0:1], v148, v149
	s_nop 1
	v_add3_u32 v34, v174, v188, s30
	v_and_or_b32 v120, v34, s31, v173
	ds_read2_b64 v[34:37], v170 offset0:8 offset1:12
	s_waitcnt lgkmcnt(2)
	v_mfma_f32_16x16x32_bf16 v[188:191], v[54:57], v[176:179], v[122:125]
	v_mul_f32_e32 v140, v185, v185
	v_fmac_f32_e32 v140, v184, v184
	v_fmac_f32_e32 v140, v186, v186
	s_waitcnt lgkmcnt(1)
	v_mfma_f32_16x16x32_bf16 v[126:129], v[50:53], v[176:179], v[126:129]
	v_fmac_f32_e32 v140, v187, v187
	s_nop 1
	v_fmac_f32_e32 v140, v188, v188
	v_bfe_u32 v122, v175, 16, 1
	v_fmac_f32_e32 v140, v189, v189
	v_add3_u32 v122, v175, v122, s30
	v_fmac_f32_e32 v140, v190, v190
	v_and_or_b32 v121, v122, s31, v121
	s_waitcnt lgkmcnt(0)
	v_mfma_f32_16x16x32_bf16 v[122:125], v[34:37], v[176:179], v[130:133]
	v_fmac_f32_e32 v140, v191, v191
	v_mov_b32_e32 v178, v184
	v_pk_mul_f32 v[132:133], v[126:127], v[126:127]
	v_cndmask_b32_e64 v130, v147, v148, s[0:1]
	v_add_f32_e32 v132, v140, v132
	v_lshlrev_b32_e32 v170, 2, v130
	v_pk_mul_f32 v[130:131], v[128:129], v[128:129]
	v_add_f32_e32 v132, v133, v132
	v_add_f32_e32 v130, v130, v132
	v_add_f32_e32 v140, v131, v130
	v_pk_mul_f32 v[132:133], v[122:123], v[122:123]
	v_pk_mul_f32 v[130:131], v[124:125], v[124:125]
	v_add_f32_e32 v132, v140, v132
	v_add_f32_e32 v132, v133, v132
	v_add_f32_e32 v130, v130, v132
	v_add_f32_e32 v140, v131, v130
	ds_bpermute_b32 v144, v170, v140
	v_cmp_lt_i32_e64 s[0:1], v150, v149
	v_mfma_f32_16x16x32_bf16 v[130:133], v[58:61], v[118:121], v[110:113]
	v_mov_b32_e32 v179, v186
	v_mov_b32_e32 v186, v185
	s_waitcnt lgkmcnt(0)
	v_add_f32_e32 v140, v140, v144
	v_cndmask_b32_e64 v110, v147, v150, s[0:1]
	v_lshlrev_b32_e32 v171, 2, v110
	ds_bpermute_b32 v144, v171, v140
	v_mfma_f32_16x16x32_bf16 v[110:113], v[62:65], v[118:121], v[114:117]
	s_waitcnt lgkmcnt(0)
	s_nop 1
	v_add_f32_e32 v114, v140, v144
	v_fmamk_f32 v114, v114, 0x3c800000, v146
	v_mul_f32_e32 v115, 0x4b800000, v114
	v_cmp_gt_f32_e64 s[0:1], s34, v114
	v_mfma_f32_16x16x32_bf16 v[10:13], v[94:97], v[46:49], v[10:13]
	s_nop 0
	v_cndmask_b32_e64 v114, v114, v115, s[0:1]
	v_rsq_f32_e32 v140, v114
	v_mfma_f32_16x16x32_bf16 v[114:117], v[66:69], v[118:121], v[106:109]
	s_nop 2
	v_mul_f32_e32 v106, 0x45800000, v140
	s_waitcnt vmcnt(19)
	v_lshlrev_b32_e32 v108, 16, v194
	v_mul_f32_e32 v144, 0xbfb8aa3b, v108
	v_exp_f32_e32 v145, v144
	v_and_b32_e32 v144, 0xffff0000, v194
	v_mul_f32_e32 v172, 0xbfb8aa3b, v144
	v_exp_f32_e32 v173, v172
	v_lshlrev_b32_e32 v109, 16, v195
	v_add_f32_e32 v145, 1.0, v145
	v_rcp_f32_e32 v172, v145
	v_add_f32_e32 v173, 1.0, v173
	v_rcp_f32_e32 v174, v173
	v_mul_f32_e32 v173, 0xbfb8aa3b, v109
	v_exp_f32_e32 v173, v173
	v_and_b32_e32 v145, 0xffff0000, v195
	v_mul_f32_e32 v175, 0xbfb8aa3b, v145
	v_exp_f32_e32 v175, v175
	v_add_f32_e32 v173, 1.0, v173
	v_rcp_f32_e32 v173, v173
	v_cndmask_b32_e64 v140, v140, v106, s[0:1]
	v_lshlrev_b64 v[106:107], 11, v[192:193]
	v_pk_mul_f32 v[178:179], v[178:179], v[140:141] op_sel_hi:[1,0]
	v_pk_mul_f32 v[108:109], v[172:173], v[108:109]
	v_add_f32_e32 v172, 1.0, v175
	v_rcp_f32_e32 v175, v172
	v_mov_b32_e32 v192, v180
	v_mov_b32_e32 v193, v182
	v_pk_mul_f32 v[178:179], v[192:193], v[178:179]
	v_pk_mul_f32 v[172:173], v[186:187], v[140:141] op_sel_hi:[1,0]
	v_mov_b32_e32 v182, v181
	v_pk_mul_f32 v[108:109], v[108:109], v[178:179]
	v_pk_mul_f32 v[172:173], v[182:183], v[172:173]
	v_pk_mul_f32 v[144:145], v[174:175], v[144:145]
	v_lshl_add_u64 v[106:107], s[8:9], 0, v[106:107]
	v_pk_mul_f32 v[144:145], v[144:145], v[172:173]
	v_and_b32_sdwa v172, v109, v151 dst_sel:DWORD dst_unused:UNUSED_PAD src0_sel:WORD_1 src1_sel:DWORD
	v_and_b32_sdwa v173, v108, v151 dst_sel:DWORD dst_unused:UNUSED_PAD src0_sel:WORD_1 src1_sel:DWORD
	v_add3_u32 v108, v108, v173, s30
	v_add3_u32 v109, v109, v172, s30
	v_and_b32_sdwa v172, v145, v151 dst_sel:DWORD dst_unused:UNUSED_PAD src0_sel:WORD_1 src1_sel:DWORD
	v_and_b32_sdwa v173, v144, v151 dst_sel:DWORD dst_unused:UNUSED_PAD src0_sel:WORD_1 src1_sel:DWORD
	v_add3_u32 v145, v145, v172, s30
	v_add3_u32 v144, v144, v173, s30
	v_and_b32_e32 v145, 0xffff0000, v145
	v_and_b32_e32 v144, 0xffff0000, v144
	v_or_b32_sdwa v109, v145, v109 dst_sel:DWORD dst_unused:UNUSED_PAD src0_sel:DWORD src1_sel:WORD_1
	v_or_b32_sdwa v108, v144, v108 dst_sel:DWORD dst_unused:UNUSED_PAD src0_sel:DWORD src1_sel:WORD_1
	v_lshl_add_u64 v[144:145], v[106:107], 0, v[136:137]
	global_store_dwordx2 v[144:145], v[108:109], off
	v_mfma_f32_16x16x32_bf16 v[106:109], v[38:41], v[118:121], v[102:105]
	s_waitcnt vmcnt(15)
	v_lshlrev_b32_e32 v119, 16, v196
	v_and_b32_e32 v179, 0xffff0000, v196
	v_mul_f32_e32 v118, v188, v140
	v_mul_f32_e32 v102, 0xbfb8aa3b, v119
	v_exp_f32_e32 v120, v102
	v_lshlrev_b32_e32 v181, 16, v197
	v_and_b32_e32 v177, 0xffff0000, v197
	v_mul_f32_e32 v178, v189, v140
	v_add_f32_e32 v120, 1.0, v120
	v_rcp_f32_e32 v121, v120
	v_mul_f32_e32 v176, v191, v140
	v_mul_f32_e32 v180, v190, v140
	v_mfma_f32_16x16x32_bf16 v[102:105], v[42:45], v[98:101], 0
	v_cmp_ge_i32_e64 s[0:1], v153, v168
	v_mov_b32_e32 v120, v234
	v_mul_f32_e32 v172, 0xbfb8aa3b, v179
	v_exp_f32_e32 v172, v172
	v_pk_mul_f32 v[118:119], v[120:121], v[118:119]
	v_mov_b32_e32 v120, v235
	v_pk_mul_f32 v[118:119], v[118:119], v[118:119] op_sel:[0,1] op_sel_hi:[1,0]
	v_mfma_f32_16x16x32_bf16 v[98:101], v[30:33], v[98:101], 0
	v_add_f32_e32 v119, 1.0, v172
	v_rcp_f32_e32 v121, v119
	v_mul_f32_e32 v119, 0xbfb8aa3b, v181
	v_exp_f32_e32 v119, v119
	v_mov_b32_e32 v172, v236
	v_pk_mul_f32 v[120:121], v[120:121], v[178:179]
	v_mov_b32_e32 v178, v237
	v_add_f32_e32 v119, 1.0, v119
	v_rcp_f32_e32 v173, v119
	v_mul_f32_e32 v119, 0xbfb8aa3b, v177
	v_exp_f32_e32 v119, v119
	v_pk_mul_f32 v[120:121], v[120:121], v[120:121] op_sel:[0,1] op_sel_hi:[1,0]
	v_pk_mul_f32 v[172:173], v[172:173], v[180:181]
	v_cndmask_b32_e64 v102, 0, v102, s[0:1]
	v_add_f32_e32 v119, 1.0, v119
	v_rcp_f32_e32 v179, v119
	v_bfe_u32 v119, v118, 16, 1
	v_add3_u32 v118, v118, v119, s30
	v_bfe_u32 v119, v120, 16, 1
	v_pk_mul_f32 v[174:175], v[178:179], v[176:177]
	v_pk_mul_f32 v[172:173], v[172:173], v[172:173] op_sel:[0,1] op_sel_hi:[1,0]
	v_lshrrev_b32_e32 v118, 16, v118
	v_add3_u32 v119, v120, v119, s30
	v_pk_mul_f32 v[174:175], v[174:175], v[174:175] op_sel:[0,1] op_sel_hi:[1,0]
	v_and_or_b32 v118, v119, s31, v118
	v_bfe_u32 v119, v172, 16, 1
	v_add3_u32 v119, v172, v119, s30
	v_bfe_u32 v120, v174, 16, 1
	v_lshrrev_b32_e32 v119, 16, v119
	v_add3_u32 v120, v174, v120, s30
	v_and_or_b32 v119, v120, s31, v119
	global_store_dwordx2 v[144:145], v[118:119], off offset:32
	v_cmp_ge_i32_e64 s[0:1], v167, v168
	v_mfma_f32_16x16x32_bf16 v[6:9], v[94:97], v[18:21], v[6:9]
	v_cndmask_b32_e64 v118, 0, v98, s[0:1]
	v_cmp_ge_i32_e64 s[0:1], v155, v168
	v_mfma_f32_16x16x32_bf16 v[14:17], v[90:93], v[46:49], v[14:17]
	s_nop 0
	v_cndmask_b32_e64 v98, 0, v103, s[0:1]
	v_cmp_ge_i32_e64 s[0:1], v154, v168
	v_mfma_f32_16x16x32_bf16 v[2:5], v[90:93], v[18:21], v[2:5]
	s_nop 0
	v_cndmask_b32_e64 v103, 0, v99, s[0:1]
	v_cmp_ge_i32_e64 s[0:1], v157, v168
	s_nop 1
	v_cndmask_b32_e64 v99, 0, v104, s[0:1]
	v_cmp_ge_i32_e64 s[0:1], v156, v168
	s_nop 1
	v_cndmask_b32_e64 v104, 0, v100, s[0:1]
	v_cmp_ge_i32_e64 s[0:1], v159, v168
	s_nop 1
	v_cndmask_b32_e64 v100, 0, v105, s[0:1]
	v_bfe_u32 v105, v98, 16, 1
	v_add3_u32 v98, v98, v105, s30
	v_bfe_u32 v105, v102, 16, 1
	v_add3_u32 v102, v102, v105, s30
	v_lshrrev_b32_e32 v102, 16, v102
	v_and_or_b32 v98, v98, s31, v102
	v_bfe_u32 v102, v100, 16, 1
	v_add3_u32 v100, v100, v102, s30
	v_bfe_u32 v102, v99, 16, 1
	v_add3_u32 v99, v99, v102, s30
	v_lshrrev_b32_e32 v99, 16, v99
	v_bfe_u32 v102, v118, 16, 1
	v_cmp_ge_i32_e64 s[0:1], v158, v168
	v_and_or_b32 v99, v100, s31, v99
	v_bfe_u32 v100, v103, 16, 1
	v_add3_u32 v102, v118, v102, s30
	v_cndmask_b32_e64 v101, 0, v101, s[0:1]
	v_add3_u32 v100, v103, v100, s30
	v_lshrrev_b32_e32 v102, 16, v102
	v_and_or_b32 v100, v100, s31, v102
	v_bfe_u32 v102, v101, 16, 1
	v_add3_u32 v101, v101, v102, s30
	v_bfe_u32 v102, v104, 16, 1
	v_add3_u32 v102, v104, v102, s30
	v_lshrrev_b32_e32 v102, 16, v102
	v_and_or_b32 v101, v101, s31, v102
	v_mul_f32_e32 v102, v126, v140
	s_waitcnt vmcnt(15)
	v_lshlrev_b32_e32 v103, 16, v198
	v_mul_f32_e32 v104, 0xbfb8aa3b, v103
	v_exp_f32_e32 v104, v104
	v_mfma_f32_16x16x32_bf16 v[118:121], v[70:73], v[98:101], v[130:133]
	v_add_f32_e32 v104, 1.0, v104
	v_rcp_f32_e32 v105, v104
	s_nop 0
	v_and_b32_e32 v131, 0xffff0000, v198
	v_mul_f32_e32 v126, 0xbfb8aa3b, v131
	v_exp_f32_e32 v126, v126
	v_mul_f32_e32 v130, v127, v140
	v_lshlrev_b32_e32 v127, 16, v199
	v_mov_b32_e32 v104, v240
	v_pk_mul_f32 v[102:103], v[104:105], v[102:103]
	v_mov_b32_e32 v104, v241
	v_pk_mul_f32 v[102:103], v[102:103], v[102:103] op_sel:[0,1] op_sel_hi:[1,0]
	v_and_b32_e32 v133, 0xffff0000, v199
	v_add_f32_e32 v103, 1.0, v126
	v_rcp_f32_e32 v105, v103
	v_mul_f32_e32 v103, 0xbfb8aa3b, v127
	v_exp_f32_e32 v103, v103
	v_mul_f32_e32 v126, v128, v140
	v_pk_mul_f32 v[104:105], v[104:105], v[130:131]
	v_mov_b32_e32 v130, v242
	v_add_f32_e32 v103, 1.0, v103
	v_rcp_f32_e32 v131, v103
	v_mul_f32_e32 v103, 0xbfb8aa3b, v133
	v_exp_f32_e32 v103, v103
	v_pk_mul_f32 v[104:105], v[104:105], v[104:105] op_sel:[0,1] op_sel_hi:[1,0]
	v_pk_mul_f32 v[126:127], v[130:131], v[126:127]
	v_mul_f32_e32 v132, v129, v140
	v_add_f32_e32 v103, 1.0, v103
	v_rcp_f32_e32 v131, v103
	v_bfe_u32 v103, v102, 16, 1
	v_mov_b32_e32 v130, v243
	v_add3_u32 v102, v102, v103, s30
	v_bfe_u32 v103, v104, 16, 1
	v_pk_mul_f32 v[126:127], v[126:127], v[126:127] op_sel:[0,1] op_sel_hi:[1,0]
	v_pk_mul_f32 v[128:129], v[130:131], v[132:133]
	v_lshrrev_b32_e32 v102, 16, v102
	v_add3_u32 v103, v104, v103, s30
	v_pk_mul_f32 v[128:129], v[128:129], v[128:129] op_sel:[0,1] op_sel_hi:[1,0]
	v_and_or_b32 v102, v103, s31, v102
	v_bfe_u32 v103, v126, 16, 1
	v_add3_u32 v103, v126, v103, s30
	v_bfe_u32 v104, v128, 16, 1
	v_lshrrev_b32_e32 v103, 16, v103
	v_add3_u32 v104, v128, v104, s30
	v_and_or_b32 v103, v104, s31, v103
	global_store_dwordx2 v[144:145], v[102:103], off offset:64
	s_waitcnt vmcnt(15)
	v_lshlrev_b32_e32 v131, 16, v200
	v_mul_f32_e32 v102, 0xbfb8aa3b, v131
	v_exp_f32_e32 v130, v102
	v_mfma_f32_16x16x32_bf16 v[102:105], v[50:53], v[98:101], v[114:117]
	s_nop 2
	v_add_f32_e32 v115, 1.0, v130
	v_rcp_f32_e32 v115, v115
	v_and_b32_e32 v117, 0xffff0000, v200
	v_mul_f32_e32 v116, 0xbfb8aa3b, v117
	v_exp_f32_e32 v116, v116
	v_mul_f32_e32 v114, v122, v140
	v_mul_f32_e32 v122, v123, v140
	v_mfma_f32_16x16x32_bf16 v[110:113], v[54:57], v[98:101], v[110:113]
	v_mov_b32_e32 v130, v244
	v_pk_mul_f32 v[114:115], v[114:115], v[130:131]
	v_lshlrev_b32_e32 v131, 16, v201
	v_pk_mul_f32 v[114:115], v[114:115], v[114:115] op_sel:[0,1] op_sel_hi:[1,0]
	v_mov_b32_e32 v130, v246
	v_add_f32_e32 v115, 1.0, v116
	v_rcp_f32_e32 v123, v115
	v_mul_f32_e32 v115, 0xbfb8aa3b, v131
	v_exp_f32_e32 v115, v115
	v_mov_b32_e32 v116, v245
	v_and_b32_e32 v127, 0xffff0000, v201
	v_pk_mul_f32 v[116:117], v[122:123], v[116:117]
	v_add_f32_e32 v115, 1.0, v115
	v_rcp_f32_e32 v123, v115
	v_mul_f32_e32 v115, 0xbfb8aa3b, v127
	v_exp_f32_e32 v115, v115
	v_mul_f32_e32 v122, v124, v140
	v_pk_mul_f32 v[122:123], v[122:123], v[130:131]
	v_pk_mul_f32 v[116:117], v[116:117], v[116:117] op_sel:[0,1] op_sel_hi:[1,0]
	v_add_f32_e32 v115, 1.0, v115
	v_rcp_f32_e32 v131, v115
	v_bfe_u32 v115, v114, 16, 1
	v_mul_f32_e32 v130, v125, v140
	v_mov_b32_e32 v126, v247
	v_add3_u32 v114, v114, v115, s30
	v_bfe_u32 v115, v116, 16, 1
	v_pk_mul_f32 v[124:125], v[130:131], v[126:127]
	v_lshrrev_b32_e32 v114, 16, v114
	v_add3_u32 v115, v116, v115, s30
	v_or_b32_e32 v126, s33, v168
	v_and_or_b32 v116, v115, s31, v114
	v_mad_i64_i32 v[114:115], s[0:1], v126, s29, v[138:139]
	v_lshl_add_u64 v[114:115], v[114:115], 0, s[20:21]
	v_lshl_add_u64 v[114:115], v[114:115], 0, v[136:137]
	v_pk_mul_f32 v[122:123], v[122:123], v[122:123] op_sel:[0,1] op_sel_hi:[1,0]
	v_pk_mul_f32 v[124:125], v[124:125], v[124:125] op_sel:[0,1] op_sel_hi:[1,0]
	v_bfe_u32 v117, v122, 16, 1
	v_add3_u32 v117, v122, v117, s30
	v_bfe_u32 v122, v124, 16, 1
	v_lshrrev_b32_e32 v117, 16, v117
	v_add3_u32 v122, v124, v122, s30
	v_and_or_b32 v117, v122, s31, v117
	global_store_dwordx2 v[144:145], v[116:117], off offset:96
	v_mul_f32_e32 v116, v119, v119
	v_fmac_f32_e32 v116, v118, v118
	v_fmac_f32_e32 v116, v120, v120
	v_fmac_f32_e32 v116, v121, v121
	v_fmac_f32_e32 v116, v110, v110
	v_fmac_f32_e32 v116, v111, v111
	v_fmac_f32_e32 v116, v112, v112
	v_mfma_f32_16x16x32_bf16 v[98:101], v[34:37], v[98:101], v[106:109]
	v_fmac_f32_e32 v116, v113, v113
	v_ashrrev_i32_e32 v127, 31, v126
	s_nop 0
	v_pk_mul_f32 v[108:109], v[102:103], v[102:103]
	v_pk_mul_f32 v[106:107], v[104:105], v[104:105]
	v_add_f32_e32 v108, v116, v108
	v_add_f32_e32 v108, v109, v108
	v_add_f32_e32 v106, v106, v108
	v_add_f32_e32 v116, v107, v106
	v_pk_mul_f32 v[108:109], v[98:99], v[98:99]
	v_pk_mul_f32 v[106:107], v[100:101], v[100:101]
	v_add_f32_e32 v108, v116, v108
	v_add_f32_e32 v108, v109, v108
	v_add_f32_e32 v106, v106, v108
	v_add_f32_e32 v106, v107, v106
	ds_bpermute_b32 v107, v170, v106
	s_waitcnt lgkmcnt(0)
	v_add_f32_e32 v106, v106, v107
	ds_bpermute_b32 v107, v171, v106
	s_waitcnt lgkmcnt(0)
	v_add_f32_e32 v94, v106, v107
	v_fmamk_f32 v94, v94, 0x3c800000, v146
	v_mul_f32_e32 v95, 0x4b800000, v94
	v_cmp_gt_f32_e64 s[0:1], s34, v94
	s_waitcnt vmcnt(15)
	v_lshlrev_b32_e32 v96, 16, v202
	v_cndmask_b32_e64 v94, v94, v95, s[0:1]
	v_rsq_f32_e32 v94, v94
	v_mul_f32_e32 v106, 0xbfb8aa3b, v96
	v_exp_f32_e32 v107, v106
	v_and_b32_e32 v106, 0xffff0000, v202
	v_mul_f32_e32 v95, 0x45800000, v94
	v_cndmask_b32_e64 v130, v94, v95, s[0:1]
	v_mul_f32_e32 v108, 0xbfb8aa3b, v106
	v_mul_f32_e32 v97, v118, v130
	v_exp_f32_e32 v118, v108
	v_add_f32_e32 v107, 1.0, v107
	v_rcp_f32_e32 v108, v107
	v_mov_b32_e32 v109, v230
	v_add_f32_e32 v107, 1.0, v118
	v_rcp_f32_e32 v122, v107
	v_pk_mul_f32 v[96:97], v[108:109], v[96:97]
	v_mul_f32_e32 v107, v119, v130
	v_pk_mul_f32 v[96:97], v[96:97], v[96:97] op_sel:[0,1] op_sel_hi:[1,0]
	v_mov_b32_e32 v123, v231
	v_pk_mul_f32 v[106:107], v[122:123], v[106:107]
	v_lshlrev_b32_e32 v108, 16, v203
	v_pk_mul_f32 v[106:107], v[106:107], v[106:107] op_sel:[0,1] op_sel_hi:[1,0]
	v_mul_f32_e32 v97, 0xbfb8aa3b, v108
	v_and_b32_e32 v118, 0xffff0000, v203
	v_exp_f32_e32 v97, v97
	v_mul_f32_e32 v107, 0xbfb8aa3b, v118
	v_exp_f32_e32 v107, v107
	v_mov_b32_e32 v123, v232
	v_add_f32_e32 v97, 1.0, v97
	v_rcp_f32_e32 v122, v97
	v_add_f32_e32 v97, 1.0, v107
	v_rcp_f32_e32 v124, v97
	v_mul_f32_e32 v109, v120, v130
	v_bfe_u32 v97, v96, 16, 1
	v_pk_mul_f32 v[108:109], v[122:123], v[108:109]
	v_mul_f32_e32 v119, v121, v130
	v_add3_u32 v96, v96, v97, s30
	v_bfe_u32 v97, v106, 16, 1
	v_pk_mul_f32 v[108:109], v[108:109], v[108:109] op_sel:[0,1] op_sel_hi:[1,0]
	v_mov_b32_e32 v125, v233
	v_pk_mul_f32 v[118:119], v[124:125], v[118:119]
	v_lshrrev_b32_e32 v96, 16, v96
	v_add3_u32 v97, v106, v97, s30
	v_pk_mul_f32 v[118:119], v[118:119], v[118:119] op_sel:[0,1] op_sel_hi:[1,0]
	v_and_or_b32 v96, v97, s31, v96
	v_bfe_u32 v97, v108, 16, 1
	v_lshlrev_b64 v[94:95], 11, v[126:127]
	v_add3_u32 v97, v108, v97, s30
	v_bfe_u32 v106, v118, 16, 1
	v_lshl_add_u64 v[94:95], s[8:9], 0, v[94:95]
	v_lshrrev_b32_e32 v97, 16, v97
	v_add3_u32 v106, v118, v106, s30
	v_and_or_b32 v97, v106, s31, v97
	v_lshl_add_u64 v[94:95], v[94:95], 0, v[136:137]
	global_store_dwordx2 v[94:95], v[96:97], off
	s_waitcnt vmcnt(15)
	v_lshlrev_b32_e32 v97, 16, v204
	v_mul_f32_e32 v90, 0xbfb8aa3b, v97
	v_exp_f32_e32 v118, v90
	v_mul_f32_e32 v96, v110, v130
	v_and_b32_e32 v121, 0xffff0000, v204
	v_mul_f32_e32 v120, v111, v130
	v_add_f32_e32 v110, 1.0, v118
	v_rcp_f32_e32 v119, v110
	v_mul_f32_e32 v116, v113, v130
	v_mfma_f32_16x16x32_bf16 v[90:93], v[82:85], v[46:49], 0
	v_cmp_ge_i32_e64 s[0:1], v161, v160
	v_mov_b32_e32 v118, v234
	v_mul_f32_e32 v106, 0xbfb8aa3b, v121
	v_exp_f32_e32 v106, v106
	v_pk_mul_f32 v[96:97], v[118:119], v[96:97]
	v_lshlrev_b32_e32 v119, 16, v205
	v_pk_mul_f32 v[96:97], v[96:97], v[96:97] op_sel:[0,1] op_sel_hi:[1,0]
	v_mov_b32_e32 v110, v235
	v_add_f32_e32 v97, 1.0, v106
	v_rcp_f32_e32 v111, v97
	v_mul_f32_e32 v97, 0xbfb8aa3b, v119
	v_exp_f32_e32 v97, v97
	v_and_b32_e32 v117, 0xffff0000, v205
	v_pk_mul_f32 v[106:107], v[110:111], v[120:121]
	v_mul_f32_e32 v118, v112, v130
	v_add_f32_e32 v97, 1.0, v97
	v_rcp_f32_e32 v111, v97
	v_mul_f32_e32 v97, 0xbfb8aa3b, v117
	v_exp_f32_e32 v97, v97
	v_mov_b32_e32 v110, v236
	v_pk_mul_f32 v[110:111], v[110:111], v[118:119]
	v_mov_b32_e32 v118, v237
	v_add_f32_e32 v97, 1.0, v97
	v_rcp_f32_e32 v119, v97
	v_pk_mul_f32 v[106:107], v[106:107], v[106:107] op_sel:[0,1] op_sel_hi:[1,0]
	v_bfe_u32 v97, v96, 16, 1
	v_add3_u32 v96, v96, v97, s30
	v_pk_mul_f32 v[108:109], v[118:119], v[116:117]
	v_bfe_u32 v97, v106, 16, 1
	v_pk_mul_f32 v[110:111], v[110:111], v[110:111] op_sel:[0,1] op_sel_hi:[1,0]
	v_lshrrev_b32_e32 v96, 16, v96
	v_add3_u32 v97, v106, v97, s30
	v_pk_mul_f32 v[108:109], v[108:109], v[108:109] op_sel:[0,1] op_sel_hi:[1,0]
	v_and_or_b32 v96, v97, s31, v96
	v_bfe_u32 v97, v110, 16, 1
	v_add3_u32 v97, v110, v97, s30
	v_bfe_u32 v106, v108, 16, 1
	v_lshrrev_b32_e32 v97, 16, v97
	v_add3_u32 v106, v108, v106, s30
	v_and_or_b32 v97, v106, s31, v97
	global_store_dwordx2 v[94:95], v[96:97], off offset:32
	v_mfma_f32_16x16x32_bf16 v[110:113], v[86:89], v[46:49], 0
	v_cndmask_b32_e64 v90, v90, 0, s[6:7]
	v_bfe_u32 v97, v90, 16, 1
	v_add3_u32 v90, v90, v97, s30
	v_lshrrev_b32_e32 v90, 16, v90
	v_mfma_f32_16x16x32_bf16 v[86:89], v[86:89], v[18:21], 0
	s_nop 2
	v_cndmask_b32_e64 v96, 0, v110, s[0:1]
	v_cmp_ge_i32_e64 s[0:1], v169, v160
	v_mfma_f32_16x16x32_bf16 v[82:85], v[82:85], v[18:21], 0
	s_nop 0
	v_cndmask_b32_e64 v91, 0, v91, s[0:1]
	v_cmp_ge_i32_e64 s[0:1], v162, v160
	v_bfe_u32 v97, v91, 16, 1
	v_add3_u32 v91, v91, v97, s30
	v_cndmask_b32_e64 v118, 0, v111, s[0:1]
	v_cmp_ge_i32_e64 s[0:1], v164, v160
	v_and_or_b32 v90, v91, s31, v90
	s_nop 0
	v_cndmask_b32_e64 v92, 0, v92, s[0:1]
	v_cmp_ge_i32_e64 s[0:1], v163, v160
	v_bfe_u32 v91, v92, 16, 1
	v_add3_u32 v91, v92, v91, s30
	v_cndmask_b32_e64 v119, 0, v112, s[0:1]
	v_cmp_ge_i32_e64 s[0:1], v166, v160
	v_lshrrev_b32_e32 v91, 16, v91
	v_mul_f32_e32 v112, v103, v130
	v_cndmask_b32_e64 v93, 0, v93, s[0:1]
	v_bfe_u32 v92, v93, 16, 1
	v_add3_u32 v92, v93, v92, s30
	v_and_or_b32 v91, v92, s31, v91
	v_bfe_u32 v92, v96, 16, 1
	v_add3_u32 v92, v96, v92, s30
	v_cmp_ge_i32_e64 s[0:1], v165, v160
	v_lshrrev_b32_e32 v114, 16, v92
	v_mul_f32_e32 v92, v102, v130
	v_cndmask_b32_e64 v120, 0, v113, s[0:1]
	v_cmp_ge_i32_e64 s[0:1], v161, v152
	v_bfe_u32 v115, v118, 16, 1
	s_waitcnt vmcnt(15)
	v_lshlrev_b32_e32 v93, 16, v206
	v_mul_f32_e32 v110, 0xbfb8aa3b, v93
	v_exp_f32_e32 v110, v110
	v_and_b32_e32 v113, 0xffff0000, v206
	v_add_f32_e32 v102, 1.0, v110
	v_rcp_f32_e32 v111, v102
	v_mul_f32_e32 v102, 0xbfb8aa3b, v113
	v_exp_f32_e32 v102, v102
	v_mov_b32_e32 v110, v240
	v_pk_mul_f32 v[92:93], v[110:111], v[92:93]
	v_lshlrev_b32_e32 v111, 16, v207
	v_pk_mul_f32 v[92:93], v[92:93], v[92:93] op_sel:[0,1] op_sel_hi:[1,0]
	v_mul_f32_e32 v110, v104, v130
	v_add_f32_e32 v93, 1.0, v102
	v_rcp_f32_e32 v103, v93
	v_mul_f32_e32 v93, 0xbfb8aa3b, v111
	v_exp_f32_e32 v93, v93
	v_mov_b32_e32 v102, v241
	v_pk_mul_f32 v[102:103], v[102:103], v[112:113]
	v_and_b32_e32 v113, 0xffff0000, v207
	v_add_f32_e32 v93, 1.0, v93
	v_rcp_f32_e32 v107, v93
	v_mul_f32_e32 v93, 0xbfb8aa3b, v113
	v_exp_f32_e32 v93, v93
	v_mov_b32_e32 v106, v242
	v_pk_mul_f32 v[106:107], v[106:107], v[110:111]
	v_pk_mul_f32 v[102:103], v[102:103], v[102:103] op_sel:[0,1] op_sel_hi:[1,0]
	v_add_f32_e32 v93, 1.0, v93
	v_rcp_f32_e32 v111, v93
	v_bfe_u32 v93, v92, 16, 1
	v_mul_f32_e32 v112, v105, v130
	v_mov_b32_e32 v110, v243
	v_add3_u32 v92, v92, v93, s30
	v_bfe_u32 v93, v102, 16, 1
	v_pk_mul_f32 v[106:107], v[106:107], v[106:107] op_sel:[0,1] op_sel_hi:[1,0]
	v_pk_mul_f32 v[104:105], v[110:111], v[112:113]
	v_lshrrev_b32_e32 v92, 16, v92
	v_add3_u32 v93, v102, v93, s30
	v_pk_mul_f32 v[104:105], v[104:105], v[104:105] op_sel:[0,1] op_sel_hi:[1,0]
	v_and_or_b32 v92, v93, s31, v92
	v_bfe_u32 v93, v106, 16, 1
	v_add3_u32 v93, v106, v93, s30
	v_bfe_u32 v102, v104, 16, 1
	v_lshrrev_b32_e32 v93, 16, v93
	v_add3_u32 v102, v104, v102, s30
	v_and_or_b32 v93, v102, s31, v93
	global_store_dwordx2 v[94:95], v[92:93], off offset:64
	v_bfe_u32 v93, v119, 16, 1
	v_cndmask_b32_e64 v111, 0, v86, s[0:1]
	v_cmp_ge_i32_e64 s[0:1], v169, v152
	v_add3_u32 v93, v119, v93, s30
	v_bfe_u32 v106, v120, 16, 1
	v_cndmask_b32_e64 v86, 0, v83, s[0:1]
	v_cmp_ge_i32_e64 s[0:1], v162, v152
	v_add3_u32 v92, v118, v115, s30
	v_lshrrev_b32_e32 v93, 16, v93
	v_add3_u32 v106, v120, v106, s30
	v_cndmask_b32_e64 v112, 0, v87, s[0:1]
	v_cmp_ge_i32_e64 s[0:1], v164, v152
	v_and_or_b32 v92, v92, s31, v114
	v_and_or_b32 v93, v106, s31, v93
	v_cndmask_b32_e64 v110, v82, 0, s[4:5]
	v_cndmask_b32_e64 v113, 0, v84, s[0:1]
	v_cmp_ge_i32_e64 s[0:1], v163, v152
	v_mfma_f32_16x16x32_bf16 v[106:109], v[58:61], v[90:93], v[74:77]
	s_nop 0
	v_cndmask_b32_e64 v114, 0, v88, s[0:1]
	v_cmp_ge_i32_e64 s[0:1], v166, v152
	v_bfe_u32 v74, v110, 16, 1
	v_bfe_u32 v76, v86, 16, 1
	v_cndmask_b32_e64 v75, 0, v85, s[0:1]
	v_add3_u32 v74, v110, v74, s30
	v_add3_u32 v76, v86, v76, s30
	v_mfma_f32_16x16x32_bf16 v[84:87], v[38:41], v[90:93], v[14:17]
	v_lshrrev_b32_e32 v74, 16, v74
	v_and_or_b32 v74, v76, s31, v74
	v_cmp_ge_i32_e64 s[0:1], v165, v152
	v_bfe_u32 v14, v113, 16, 1
	v_add3_u32 v14, v113, v14, s30
	v_lshrrev_b32_e32 v76, 16, v14
	v_mfma_f32_16x16x32_bf16 v[14:17], v[42:45], v[46:49], 0
	v_cndmask_b32_e64 v115, 0, v89, s[0:1]
	v_cmp_ge_i32_e64 s[0:1], v167, v160
	v_bfe_u32 v77, v75, 16, 1
	v_mfma_f32_16x16x32_bf16 v[46:49], v[30:33], v[46:49], 0
	v_add3_u32 v75, v75, v77, s30
	s_nop 2
	v_cndmask_b32_e64 v14, v14, 0, vcc
	s_waitcnt vmcnt(15)
	v_lshlrev_b32_e32 v77, 16, v209
	v_mfma_f32_16x16x32_bf16 v[80:83], v[62:65], v[90:93], v[78:81]
	v_and_or_b32 v75, v75, s31, v76
	v_mov_b32_e32 v76, v246
	v_mfma_f32_16x16x32_bf16 v[10:13], v[66:69], v[90:93], v[10:13]
	v_cndmask_b32_e64 v92, 0, v46, s[0:1]
	v_cmp_ge_i32_e64 s[0:1], v155, v160
	v_and_b32_e32 v79, 0xffff0000, v209
	v_mov_b32_e32 v78, v247
	v_cndmask_b32_e64 v15, 0, v15, s[0:1]
	v_bfe_u32 v46, v15, 16, 1
	v_cmp_ge_i32_e64 s[0:1], v154, v160
	v_add3_u32 v15, v15, v46, s30
	v_bfe_u32 v46, v14, 16, 1
	v_cndmask_b32_e64 v93, 0, v47, s[0:1]
	v_cmp_ge_i32_e64 s[0:1], v157, v160
	v_add3_u32 v14, v14, v46, s30
	v_lshrrev_b32_e32 v14, 16, v14
	v_cndmask_b32_e64 v16, 0, v16, s[0:1]
	v_cmp_ge_i32_e64 s[0:1], v156, v160
	v_and_or_b32 v46, v15, s31, v14
	v_bfe_u32 v15, v16, 16, 1
	v_cndmask_b32_e64 v110, 0, v48, s[0:1]
	v_cmp_ge_i32_e64 s[0:1], v159, v160
	v_add3_u32 v15, v16, v15, s30
	v_lshrrev_b32_e32 v16, 16, v15
	v_cndmask_b32_e64 v17, 0, v17, s[0:1]
	v_bfe_u32 v14, v17, 16, 1
	v_lshlrev_b32_e32 v15, 16, v208
	v_add3_u32 v14, v17, v14, s30
	v_mul_f32_e32 v17, 0xbfb8aa3b, v15
	v_exp_f32_e32 v17, v17
	v_cmp_ge_i32_e64 s[0:1], v158, v160
	v_and_or_b32 v47, v14, s31, v16
	v_mul_f32_e32 v16, v98, v130
	v_add_f32_e32 v14, 1.0, v17
	v_cndmask_b32_e64 v113, 0, v49, s[0:1]
	v_rcp_f32_e32 v17, v14
	v_and_b32_e32 v49, 0xffff0000, v208
	v_mul_f32_e32 v48, 0xbfb8aa3b, v49
	v_exp_f32_e32 v48, v48
	v_mov_b32_e32 v14, v244
	v_pk_mul_f32 v[14:15], v[16:17], v[14:15]
	v_mul_f32_e32 v16, v99, v130
	v_pk_mul_f32 v[14:15], v[14:15], v[14:15] op_sel:[0,1] op_sel_hi:[1,0]
	v_or_b32_e32 v96, s33, v160
	v_add_f32_e32 v15, 1.0, v48
	v_rcp_f32_e32 v17, v15
	v_mul_f32_e32 v15, 0xbfb8aa3b, v77
	v_exp_f32_e32 v15, v15
	v_mov_b32_e32 v48, v245
	v_pk_mul_f32 v[16:17], v[16:17], v[48:49]
	v_mul_f32_e32 v48, v100, v130
	v_add_f32_e32 v15, 1.0, v15
	v_rcp_f32_e32 v49, v15
	v_mul_f32_e32 v15, 0xbfb8aa3b, v79
	v_exp_f32_e32 v15, v15
	v_pk_mul_f32 v[16:17], v[16:17], v[16:17] op_sel:[0,1] op_sel_hi:[1,0]
	v_pk_mul_f32 v[48:49], v[48:49], v[76:77]
	v_mul_f32_e32 v76, v101, v130
	v_add_f32_e32 v15, 1.0, v15
	v_rcp_f32_e32 v77, v15
	v_bfe_u32 v15, v14, 16, 1
	v_add3_u32 v14, v14, v15, s30
	v_bfe_u32 v15, v16, 16, 1
	v_add3_u32 v15, v16, v15, s30
	v_mad_i64_i32 v[16:17], s[0:1], v96, s29, v[138:139]
	v_lshl_add_u64 v[16:17], v[16:17], 0, s[20:21]
	v_pk_mul_f32 v[76:77], v[76:77], v[78:79]
	v_lshl_add_u64 v[78:79], v[16:17], 0, v[136:137]
	v_pk_mul_f32 v[48:49], v[48:49], v[48:49] op_sel:[0,1] op_sel_hi:[1,0]
	v_lshrrev_b32_e32 v14, 16, v14
	v_pk_mul_f32 v[76:77], v[76:77], v[76:77] op_sel:[0,1] op_sel_hi:[1,0]
	v_and_or_b32 v14, v15, s31, v14
	v_bfe_u32 v15, v48, 16, 1
	v_add3_u32 v15, v48, v15, s30
	v_bfe_u32 v16, v76, 16, 1
	v_lshrrev_b32_e32 v15, 16, v15
	v_add3_u32 v16, v76, v16, s30
	v_and_or_b32 v15, v16, s31, v15
	global_store_dwordx2 v[94:95], v[14:15], off offset:96
	v_bfe_u32 v15, v92, 16, 1
	v_bfe_u32 v116, v93, 16, 1
	v_add3_u32 v15, v92, v15, s30
	v_add3_u32 v14, v93, v116, s30
	v_lshrrev_b32_e32 v15, 16, v15
	v_and_or_b32 v48, v14, s31, v15
	v_bfe_u32 v15, v110, 16, 1
	v_bfe_u32 v14, v113, 16, 1
	v_add3_u32 v15, v110, v15, s30
	v_add3_u32 v14, v113, v14, s30
	v_lshrrev_b32_e32 v15, 16, v15
	v_and_or_b32 v49, v14, s31, v15
	v_bfe_u32 v14, v111, 16, 1
	v_add3_u32 v14, v111, v14, s30
	v_mfma_f32_16x16x32_bf16 v[92:95], v[70:73], v[46:49], v[106:109]
	v_bfe_u32 v15, v112, 16, 1
	v_lshrrev_b32_e32 v14, 16, v14
	v_add3_u32 v15, v112, v15, s30
	v_and_or_b32 v76, v15, s31, v14
	v_mfma_f32_16x16x32_bf16 v[14:17], v[50:53], v[46:49], v[10:13]
	v_ashrrev_i32_e32 v97, 31, v96
	s_nop 1
	v_bfe_u32 v10, v114, 16, 1
	v_add3_u32 v10, v114, v10, s30
	v_mfma_f32_16x16x32_bf16 v[80:83], v[54:57], v[46:49], v[80:83]
	v_lshrrev_b32_e32 v77, 16, v10
	v_mfma_f32_16x16x32_bf16 v[10:13], v[34:37], v[46:49], v[84:87]
	v_mul_f32_e64 v48, v14, v14
	v_mul_f32_e64 v49, v15, v15
	v_pk_mul_f32 v[46:47], v[16:17], v[16:17]
	v_mul_f32_e32 v84, v93, v93
	v_fmac_f32_e32 v84, v92, v92
	v_fmac_f32_e32 v84, v94, v94
	v_fmac_f32_e32 v84, v95, v95
	v_fmac_f32_e32 v84, v80, v80
	v_fmac_f32_e32 v84, v81, v81
	v_fmac_f32_e32 v84, v82, v82
	v_fmac_f32_e32 v84, v83, v83
	v_add_f32_e32 v48, v84, v48
	v_add_f32_e32 v48, v49, v48
	v_add_f32_e32 v46, v46, v48
	v_add_f32_e32 v84, v47, v46
	v_pk_mul_f32 v[48:49], v[10:11], v[10:11]
	v_pk_mul_f32 v[46:47], v[12:13], v[12:13]
	v_add_f32_e32 v48, v84, v48
	v_add_f32_e32 v48, v49, v48
	v_add_f32_e32 v46, v46, v48
	v_add_f32_e32 v84, v47, v46
	ds_bpermute_b32 v85, v170, v84
	v_bfe_u32 v46, v115, 16, 1
	v_add3_u32 v46, v115, v46, s30
	v_and_or_b32 v77, v46, s31, v77
	s_nop 1
	v_mfma_f32_16x16x32_bf16 v[46:49], v[58:61], v[74:77], v[22:25]
	s_waitcnt lgkmcnt(0)
	v_add_f32_e32 v58, v84, v85
	ds_bpermute_b32 v59, v171, v58
	v_mov_b32_e32 v61, v230
	v_mfma_f32_16x16x32_bf16 v[22:25], v[62:65], v[74:77], v[26:29]
	s_waitcnt lgkmcnt(0)
	s_nop 0
	v_add_f32_e32 v26, v58, v59
	v_fmamk_f32 v26, v26, 0x3c800000, v146
	v_mul_f32_e32 v27, 0x4b800000, v26
	v_cmp_gt_f32_e64 s[0:1], s34, v26
	s_nop 1
	v_cndmask_b32_e64 v26, v26, v27, s[0:1]
	v_rsq_f32_e32 v58, v26
	v_mfma_f32_16x16x32_bf16 v[26:29], v[66:69], v[74:77], v[6:9]
	v_mov_b32_e32 v67, v232
	s_nop 1
	v_mul_f32_e32 v6, 0x45800000, v58
	s_waitcnt vmcnt(15)
	v_lshlrev_b32_e32 v8, 16, v210
	v_cndmask_b32_e64 v68, v58, v6, s[0:1]
	v_mul_f32_e32 v58, 0xbfb8aa3b, v8
	v_exp_f32_e32 v59, v58
	v_and_b32_e32 v58, 0xffff0000, v210
	v_mul_f32_e32 v60, 0xbfb8aa3b, v58
	v_exp_f32_e32 v62, v60
	v_add_f32_e32 v59, 1.0, v59
	v_rcp_f32_e32 v60, v59
	v_mul_f32_e32 v9, v92, v68
	v_add_f32_e32 v59, 1.0, v62
	v_rcp_f32_e32 v88, v59
	v_pk_mul_f32 v[8:9], v[60:61], v[8:9]
	v_mul_f32_e32 v59, v93, v68
	v_pk_mul_f32 v[8:9], v[8:9], v[8:9] op_sel:[0,1] op_sel_hi:[1,0]
	v_mov_b32_e32 v89, v231
	v_pk_mul_f32 v[58:59], v[88:89], v[58:59]
	v_lshlrev_b32_e32 v60, 16, v211
	v_pk_mul_f32 v[58:59], v[58:59], v[58:59] op_sel:[0,1] op_sel_hi:[1,0]
	v_mul_f32_e32 v9, 0xbfb8aa3b, v60
	v_and_b32_e32 v62, 0xffff0000, v211
	v_exp_f32_e32 v9, v9
	v_mul_f32_e32 v59, 0xbfb8aa3b, v62
	v_exp_f32_e32 v59, v59
	v_mul_f32_e32 v61, v94, v68
	v_add_f32_e32 v9, 1.0, v9
	v_rcp_f32_e32 v66, v9
	v_add_f32_e32 v9, 1.0, v59
	v_rcp_f32_e32 v90, v9
	v_bfe_u32 v9, v8, 16, 1
	v_pk_mul_f32 v[60:61], v[66:67], v[60:61]
	v_mul_f32_e32 v63, v95, v68
	v_add3_u32 v8, v8, v9, s30
	v_bfe_u32 v9, v58, 16, 1
	v_pk_mul_f32 v[60:61], v[60:61], v[60:61] op_sel:[0,1] op_sel_hi:[1,0]
	v_mov_b32_e32 v91, v233
	v_pk_mul_f32 v[62:63], v[90:91], v[62:63]
	v_lshrrev_b32_e32 v8, 16, v8
	v_add3_u32 v9, v58, v9, s30
	v_pk_mul_f32 v[62:63], v[62:63], v[62:63] op_sel:[0,1] op_sel_hi:[1,0]
	v_and_or_b32 v8, v9, s31, v8
	v_bfe_u32 v9, v60, 16, 1
	v_lshlrev_b64 v[6:7], 11, v[96:97]
	v_add3_u32 v9, v60, v9, s30
	v_bfe_u32 v58, v62, 16, 1
	v_lshl_add_u64 v[6:7], s[8:9], 0, v[6:7]
	v_lshrrev_b32_e32 v9, 16, v9
	v_add3_u32 v58, v62, v58, s30
	v_and_or_b32 v9, v58, s31, v9
	v_lshl_add_u64 v[58:59], v[6:7], 0, v[136:137]
	global_store_dwordx2 v[58:59], v[8:9], off
	v_mfma_f32_16x16x32_bf16 v[6:9], v[38:41], v[74:77], v[2:5]
	v_mul_f32_e32 v38, v80, v68
	v_cmp_ge_i32_e64 s[0:1], v153, v152
	s_waitcnt vmcnt(15)
	v_lshlrev_b32_e32 v39, 16, v212
	v_mul_f32_e32 v2, 0xbfb8aa3b, v39
	v_exp_f32_e32 v40, v2
	v_mfma_f32_16x16x32_bf16 v[2:5], v[42:45], v[18:21], 0
	v_and_b32_e32 v43, 0xffff0000, v212
	v_mul_f32_e32 v42, 0xbfb8aa3b, v43
	v_add_f32_e32 v40, 1.0, v40
	v_rcp_f32_e32 v41, v40
	v_exp_f32_e32 v44, v42
	v_lshlrev_b32_e32 v45, 16, v213
	v_mul_f32_e32 v42, v81, v68
	v_mfma_f32_16x16x32_bf16 v[18:21], v[30:33], v[18:21], 0
	v_cndmask_b32_e64 v2, 0, v2, s[0:1]
	v_bfe_u32 v30, v2, 16, 1
	v_add3_u32 v2, v2, v30, s30
	v_lshrrev_b32_e32 v2, 16, v2
	v_mov_b32_e32 v40, v234
	v_pk_mul_f32 v[38:39], v[40:41], v[38:39]
	v_mov_b32_e32 v40, v235
	v_pk_mul_f32 v[38:39], v[38:39], v[38:39] op_sel:[0,1] op_sel_hi:[1,0]
	v_and_b32_e32 v61, 0xffff0000, v213
	v_add_f32_e32 v39, 1.0, v44
	v_rcp_f32_e32 v41, v39
	v_mul_f32_e32 v39, 0xbfb8aa3b, v45
	v_exp_f32_e32 v39, v39
	v_mul_f32_e32 v44, v82, v68
	v_pk_mul_f32 v[40:41], v[40:41], v[42:43]
	v_mov_b32_e32 v42, v236
	v_add_f32_e32 v39, 1.0, v39
	v_rcp_f32_e32 v43, v39
	v_mul_f32_e32 v39, 0xbfb8aa3b, v61
	v_exp_f32_e32 v39, v39
	v_mul_f32_e32 v60, v83, v68
	v_pk_mul_f32 v[42:43], v[42:43], v[44:45]
	v_mov_b32_e32 v44, v237
	v_add_f32_e32 v39, 1.0, v39
	v_rcp_f32_e32 v45, v39
	v_pk_mul_f32 v[40:41], v[40:41], v[40:41] op_sel:[0,1] op_sel_hi:[1,0]
	v_bfe_u32 v39, v38, 16, 1
	v_add3_u32 v38, v38, v39, s30
	v_pk_mul_f32 v[44:45], v[44:45], v[60:61]
	v_bfe_u32 v39, v40, 16, 1
	v_pk_mul_f32 v[42:43], v[42:43], v[42:43] op_sel:[0,1] op_sel_hi:[1,0]
	v_lshrrev_b32_e32 v38, 16, v38
	v_add3_u32 v39, v40, v39, s30
	v_pk_mul_f32 v[44:45], v[44:45], v[44:45] op_sel:[0,1] op_sel_hi:[1,0]
	v_and_or_b32 v38, v39, s31, v38
	v_bfe_u32 v39, v42, 16, 1
	v_add3_u32 v39, v42, v39, s30
	v_bfe_u32 v40, v44, 16, 1
	v_lshrrev_b32_e32 v39, 16, v39
	v_add3_u32 v40, v44, v40, s30
	v_and_or_b32 v39, v40, s31, v39
	global_store_dwordx2 v[58:59], v[38:39], off offset:32
	v_cndmask_b32_e64 v18, v18, 0, vcc
	v_cmp_ge_i32_e32 vcc, v155, v152
	v_mul_f32_e32 v44, v15, v68
	v_cndmask_b32_e32 v3, 0, v3, vcc
	v_cmp_ge_i32_e32 vcc, v154, v152
	v_bfe_u32 v30, v3, 16, 1
	v_add3_u32 v3, v3, v30, s30
	v_cndmask_b32_e32 v19, 0, v19, vcc
	v_cmp_ge_i32_e32 vcc, v157, v152
	v_and_or_b32 v30, v3, s31, v2
	s_waitcnt vmcnt(15)
	v_and_b32_e32 v45, 0xffff0000, v214
	v_cndmask_b32_e32 v4, 0, v4, vcc
	v_cmp_ge_i32_e32 vcc, v156, v152
	v_bfe_u32 v2, v4, 16, 1
	v_add3_u32 v2, v4, v2, s30
	v_cndmask_b32_e32 v20, 0, v20, vcc
	v_cmp_ge_i32_e32 vcc, v159, v152
	v_lshrrev_b32_e32 v2, 16, v2
	v_lshlrev_b32_e32 v15, 16, v215
	v_cndmask_b32_e32 v5, 0, v5, vcc
	v_bfe_u32 v3, v5, 16, 1
	v_add3_u32 v3, v5, v3, s30
	v_and_or_b32 v31, v3, s31, v2
	v_bfe_u32 v2, v18, 16, 1
	v_cmp_ge_i32_e32 vcc, v158, v152
	v_add3_u32 v2, v18, v2, s30
	v_bfe_u32 v3, v19, 16, 1
	v_cndmask_b32_e32 v21, 0, v21, vcc
	v_lshrrev_b32_e32 v2, 16, v2
	v_add3_u32 v3, v19, v3, s30
	v_and_or_b32 v32, v3, s31, v2
	v_bfe_u32 v3, v21, 16, 1
	v_add3_u32 v4, v21, v3, s30
	v_lshlrev_b32_e32 v3, 16, v214
	v_mul_f32_e32 v5, 0xbfb8aa3b, v3
	v_exp_f32_e32 v5, v5
	v_bfe_u32 v2, v20, 16, 1
	v_add3_u32 v2, v20, v2, s30
	v_lshrrev_b32_e32 v2, 16, v2
	v_and_or_b32 v33, v4, s31, v2
	v_add_f32_e32 v4, 1.0, v5
	v_rcp_f32_e32 v5, v4
	v_mul_f32_e32 v2, v14, v68
	v_mul_f32_e32 v14, 0xbfb8aa3b, v45
	v_exp_f32_e32 v14, v14
	v_mov_b32_e32 v4, v240
	v_pk_mul_f32 v[2:3], v[4:5], v[2:3]
	v_mov_b32_e32 v4, v241
	v_pk_mul_f32 v[2:3], v[2:3], v[2:3] op_sel:[0,1] op_sel_hi:[1,0]
	v_mov_b32_e32 v38, v242
	v_add_f32_e32 v3, 1.0, v14
	v_rcp_f32_e32 v5, v3
	v_mul_f32_e32 v3, 0xbfb8aa3b, v15
	v_exp_f32_e32 v3, v3
	v_mul_f32_e32 v14, v16, v68
	v_pk_mul_f32 v[4:5], v[4:5], v[44:45]
	v_and_b32_e32 v45, 0xffff0000, v215
	v_add_f32_e32 v3, 1.0, v3
	v_rcp_f32_e32 v39, v3
	v_mul_f32_e32 v3, 0xbfb8aa3b, v45
	v_exp_f32_e32 v3, v3
	v_pk_mul_f32 v[4:5], v[4:5], v[4:5] op_sel:[0,1] op_sel_hi:[1,0]
	v_pk_mul_f32 v[14:15], v[38:39], v[14:15]
	v_mul_f32_e32 v44, v17, v68
	v_add_f32_e32 v3, 1.0, v3
	v_rcp_f32_e32 v39, v3
	v_bfe_u32 v3, v2, 16, 1
	v_mov_b32_e32 v38, v243
	v_add3_u32 v2, v2, v3, s30
	v_bfe_u32 v3, v4, 16, 1
	v_pk_mul_f32 v[14:15], v[14:15], v[14:15] op_sel:[0,1] op_sel_hi:[1,0]
	v_pk_mul_f32 v[16:17], v[38:39], v[44:45]
	v_lshrrev_b32_e32 v2, 16, v2
	v_add3_u32 v3, v4, v3, s30
	v_pk_mul_f32 v[16:17], v[16:17], v[16:17] op_sel:[0,1] op_sel_hi:[1,0]
	v_and_or_b32 v2, v3, s31, v2
	v_bfe_u32 v3, v14, 16, 1
	v_add3_u32 v3, v14, v3, s30
	v_bfe_u32 v4, v16, 16, 1
	v_lshrrev_b32_e32 v3, 16, v3
	v_add3_u32 v4, v16, v4, s30
	v_and_or_b32 v3, v4, s31, v3
	global_store_dwordx2 v[58:59], v[2:3], off offset:64
	v_mfma_f32_16x16x32_bf16 v[14:17], v[54:57], v[30:33], v[22:25]
	s_nop 1
	s_waitcnt vmcnt(15)
	v_lshlrev_b32_e32 v23, 16, v216
	v_mul_f32_e32 v2, 0xbfb8aa3b, v23
	v_exp_f32_e32 v22, v2
	v_mfma_f32_16x16x32_bf16 v[2:5], v[50:53], v[30:33], v[26:29]
	v_mul_f32_e32 v24, v10, v68
	v_add_f32_e32 v10, 1.0, v22
	s_nop 0
	v_and_b32_e32 v27, 0xffff0000, v216
	v_rcp_f32_e32 v25, v10
	v_mul_f32_e32 v10, 0xbfb8aa3b, v27
	v_exp_f32_e32 v26, v10
	v_mul_f32_e32 v10, v11, v68
	v_and_b32_e32 v29, 0xffff0000, v217
	v_mfma_f32_16x16x32_bf16 v[18:21], v[70:73], v[30:33], v[46:49]
	v_add_f32_e32 v11, 1.0, v26
	v_rcp_f32_e32 v11, v11
	v_mov_b32_e32 v22, v244
	v_pk_mul_f32 v[22:23], v[24:25], v[22:23]
	v_lshlrev_b32_e32 v25, 16, v217
	v_pk_mul_f32 v[22:23], v[22:23], v[22:23] op_sel:[0,1] op_sel_hi:[1,0]
	v_mov_b32_e32 v26, v245
	v_mul_f32_e32 v23, 0xbfb8aa3b, v25
	v_exp_f32_e32 v23, v23
	v_pk_mul_f32 v[10:11], v[10:11], v[26:27]
	v_mul_f32_e32 v26, v12, v68
	v_pk_mul_f32 v[10:11], v[10:11], v[10:11] op_sel:[0,1] op_sel_hi:[1,0]
	v_mov_b32_e32 v24, v246
	v_add_f32_e32 v11, 1.0, v23
	v_rcp_f32_e32 v27, v11
	v_mul_f32_e32 v11, 0xbfb8aa3b, v29
	v_exp_f32_e32 v11, v11
	v_mov_b32_e32 v28, v247
	v_pk_mul_f32 v[24:25], v[26:27], v[24:25]
	v_mul_f32_e32 v26, v13, v68
	v_add_f32_e32 v11, 1.0, v11
	v_rcp_f32_e32 v27, v11
	v_bfe_u32 v11, v22, 16, 1
	v_add3_u32 v11, v22, v11, s30
	v_lshrrev_b32_e32 v11, 16, v11
	v_pk_mul_f32 v[12:13], v[26:27], v[28:29]
	v_or_b32_e32 v26, s33, v152
	v_pk_mul_f32 v[12:13], v[12:13], v[12:13] op_sel:[0,1] op_sel_hi:[1,0]
	v_pk_mul_f32 v[24:25], v[24:25], v[24:25] op_sel:[0,1] op_sel_hi:[1,0]
	v_bfe_u32 v13, v10, 16, 1
	v_add3_u32 v10, v10, v13, s30
	v_and_or_b32 v22, v10, s31, v11
	v_mad_i64_i32 v[10:11], s[0:1], v26, s29, v[138:139]
	v_lshl_add_u64 v[10:11], v[10:11], 0, s[20:21]
	v_lshl_add_u64 v[10:11], v[10:11], 0, v[136:137]
	v_bfe_u32 v13, v24, 16, 1
	v_add3_u32 v13, v24, v13, s30
	v_bfe_u32 v23, v12, 16, 1
	v_lshrrev_b32_e32 v13, 16, v13
	v_add3_u32 v12, v12, v23, s30
	v_and_or_b32 v23, v12, s31, v13
	global_store_dwordx2 v[58:59], v[22:23], off offset:96
	v_mul_f32_e32 v27, v19, v19
	v_fmac_f32_e32 v27, v18, v18
	v_fmac_f32_e32 v27, v20, v20
	v_fmac_f32_e32 v27, v21, v21
	v_fmac_f32_e32 v27, v14, v14
	v_fmac_f32_e32 v27, v15, v15
	v_fmac_f32_e32 v27, v16, v16
	v_mfma_f32_16x16x32_bf16 v[6:9], v[34:37], v[30:33], v[6:9]
	v_fmac_f32_e32 v27, v17, v17
	v_pk_mul_f32 v[30:31], v[2:3], v[2:3]
	v_pk_mul_f32 v[12:13], v[4:5], v[4:5]
	v_add_f32_e32 v27, v27, v30
	v_add_f32_e32 v27, v31, v27
	v_add_f32_e32 v12, v12, v27
	v_add_f32_e32 v27, v13, v12
	s_nop 0
	v_pk_mul_f32 v[30:31], v[6:7], v[6:7]
	v_pk_mul_f32 v[12:13], v[8:9], v[8:9]
	v_add_f32_e32 v27, v27, v30
	v_add_f32_e32 v27, v31, v27
	v_add_f32_e32 v12, v12, v27
	v_add_f32_e32 v12, v13, v12
	ds_bpermute_b32 v13, v170, v12
	v_ashrrev_i32_e32 v27, 31, v26
	s_waitcnt lgkmcnt(0)
	v_add_f32_e32 v12, v12, v13
	ds_bpermute_b32 v13, v171, v12
	s_waitcnt lgkmcnt(0)
	v_add_f32_e32 v12, v12, v13
	v_fmamk_f32 v12, v12, 0x3c800000, v146
	v_mul_f32_e32 v13, 0x4b800000, v12
	v_cmp_gt_f32_e32 vcc, s34, v12
	v_mov_b32_e32 v33, v230
	v_cndmask_b32_e32 v12, v12, v13, vcc
	v_rsq_f32_e32 v12, v12
	s_nop 0
	v_mul_f32_e32 v13, 0x45800000, v12
	v_cndmask_b32_e32 v34, v12, v13, vcc
	v_lshlrev_b64 v[12:13], 11, v[26:27]
	s_waitcnt vmcnt(15)
	v_lshlrev_b32_e32 v26, 16, v218
	v_mul_f32_e32 v27, v18, v34
	v_mul_f32_e32 v18, 0xbfb8aa3b, v26
	v_exp_f32_e32 v32, v18
	v_and_b32_e32 v18, 0xffff0000, v218
	v_mul_f32_e32 v28, 0xbfb8aa3b, v18
	v_exp_f32_e32 v28, v28
	v_add_f32_e32 v32, 1.0, v32
	v_rcp_f32_e32 v32, v32
	v_mul_f32_e32 v19, v19, v34
	v_add_f32_e32 v22, 1.0, v28
	v_rcp_f32_e32 v22, v22
	v_pk_mul_f32 v[26:27], v[32:33], v[26:27]
	v_mul_f32_e32 v21, v21, v34
	v_pk_mul_f32 v[26:27], v[26:27], v[26:27] op_sel:[0,1] op_sel_hi:[1,0]
	v_mov_b32_e32 v23, v231
	v_pk_mul_f32 v[18:19], v[22:23], v[18:19]
	v_lshlrev_b32_e32 v22, 16, v219
	v_pk_mul_f32 v[18:19], v[18:19], v[18:19] op_sel:[0,1] op_sel_hi:[1,0]
	v_mul_f32_e32 v23, v20, v34
	v_mul_f32_e32 v19, 0xbfb8aa3b, v22
	v_and_b32_e32 v20, 0xffff0000, v219
	v_exp_f32_e32 v19, v19
	v_mul_f32_e32 v27, 0xbfb8aa3b, v20
	v_exp_f32_e32 v27, v27
	v_mov_b32_e32 v29, v232
	v_add_f32_e32 v19, 1.0, v19
	v_rcp_f32_e32 v28, v19
	v_add_f32_e32 v19, 1.0, v27
	v_rcp_f32_e32 v24, v19
	v_bfe_u32 v19, v26, 16, 1
	v_pk_mul_f32 v[22:23], v[28:29], v[22:23]
	v_add3_u32 v19, v26, v19, s30
	v_mov_b32_e32 v25, v233
	v_pk_mul_f32 v[20:21], v[24:25], v[20:21]
	v_pk_mul_f32 v[22:23], v[22:23], v[22:23] op_sel:[0,1] op_sel_hi:[1,0]
	v_pk_mul_f32 v[20:21], v[20:21], v[20:21] op_sel:[0,1] op_sel_hi:[1,0]
	v_lshrrev_b32_e32 v19, 16, v19
	v_bfe_u32 v21, v18, 16, 1
	v_add3_u32 v18, v18, v21, s30
	v_and_or_b32 v18, v18, s31, v19
	v_bfe_u32 v19, v22, 16, 1
	v_add3_u32 v19, v22, v19, s30
	v_bfe_u32 v21, v20, 16, 1
	v_lshl_add_u64 v[12:13], s[8:9], 0, v[12:13]
	v_lshrrev_b32_e32 v19, 16, v19
	v_add3_u32 v20, v20, v21, s30
	v_and_or_b32 v19, v20, s31, v19
	v_lshl_add_u64 v[12:13], v[12:13], 0, v[136:137]
	global_store_dwordx2 v[12:13], v[18:19], off
	s_waitcnt vmcnt(15)
	v_lshlrev_b32_e32 v23, 16, v220
	v_mul_f32_e32 v22, 0xbfb8aa3b, v23
	v_exp_f32_e32 v24, v22
	v_mul_f32_e32 v22, v14, v34
	v_and_b32_e32 v27, 0xffff0000, v220
	v_mul_f32_e32 v26, v15, v34
	v_add_f32_e32 v14, 1.0, v24
	v_rcp_f32_e32 v25, v14
	v_mul_f32_e32 v14, 0xbfb8aa3b, v27
	v_exp_f32_e32 v14, v14
	v_mov_b32_e32 v24, v234
	v_add_f32_e32 v14, 1.0, v14
	v_pk_mul_f32 v[22:23], v[24:25], v[22:23]
	v_rcp_f32_e32 v15, v14
	v_lshlrev_b32_e32 v25, 16, v221
	v_mul_f32_e32 v14, 0xbfb8aa3b, v25
	v_exp_f32_e32 v18, v14
	v_mov_b32_e32 v14, v235
	v_pk_mul_f32 v[14:15], v[14:15], v[26:27]
	v_and_b32_e32 v27, 0xffff0000, v221
	v_pk_mul_f32 v[14:15], v[14:15], v[14:15] op_sel:[0,1] op_sel_hi:[1,0]
	v_mul_f32_e32 v24, v16, v34
	v_add_f32_e32 v15, 1.0, v18
	v_rcp_f32_e32 v19, v15
	v_mul_f32_e32 v15, 0xbfb8aa3b, v27
	v_exp_f32_e32 v15, v15
	v_mov_b32_e32 v18, v236
	v_pk_mul_f32 v[18:19], v[18:19], v[24:25]
	v_mov_b32_e32 v24, v237
	v_add_f32_e32 v15, 1.0, v15
	v_rcp_f32_e32 v25, v15
	v_mul_f32_e32 v26, v17, v34
	v_pk_mul_f32 v[22:23], v[22:23], v[22:23] op_sel:[0,1] op_sel_hi:[1,0]
	v_pk_mul_f32 v[16:17], v[24:25], v[26:27]
	v_bfe_u32 v15, v22, 16, 1
	v_pk_mul_f32 v[16:17], v[16:17], v[16:17] op_sel:[0,1] op_sel_hi:[1,0]
	v_add3_u32 v15, v22, v15, s30
	v_bfe_u32 v17, v14, 16, 1
	v_pk_mul_f32 v[18:19], v[18:19], v[18:19] op_sel:[0,1] op_sel_hi:[1,0]
	v_lshrrev_b32_e32 v15, 16, v15
	v_add3_u32 v14, v14, v17, s30
	v_and_or_b32 v14, v14, s31, v15
	v_bfe_u32 v15, v18, 16, 1
	v_add3_u32 v15, v18, v15, s30
	v_bfe_u32 v17, v16, 16, 1
	v_lshrrev_b32_e32 v15, 16, v15
	v_add3_u32 v16, v16, v17, s30
	v_and_or_b32 v15, v16, s31, v15
	global_store_dwordx2 v[12:13], v[14:15], off offset:32
	s_nop 0
	v_mul_f32_e32 v24, v3, v34
	s_waitcnt vmcnt(15)
	v_lshlrev_b32_e32 v11, 16, v222
	v_mul_f32_e32 v10, 0xbfb8aa3b, v11
	v_exp_f32_e32 v22, v10
	v_mul_f32_e32 v10, v2, v34
	v_and_b32_e32 v25, 0xffff0000, v222
	v_mul_f32_e32 v20, v5, v34
	v_add_f32_e32 v2, 1.0, v22
	v_rcp_f32_e32 v23, v2
	v_mul_f32_e32 v2, 0xbfb8aa3b, v25
	v_exp_f32_e32 v2, v2
	v_mov_b32_e32 v22, v240
	v_add_f32_e32 v2, 1.0, v2
	v_pk_mul_f32 v[10:11], v[22:23], v[10:11]
	v_rcp_f32_e32 v3, v2
	v_lshlrev_b32_e32 v23, 16, v223
	v_pk_mul_f32 v[10:11], v[10:11], v[10:11] op_sel:[0,1] op_sel_hi:[1,0]
	v_mul_f32_e32 v2, 0xbfb8aa3b, v23
	v_exp_f32_e32 v11, v2
	v_mov_b32_e32 v2, v241
	v_pk_mul_f32 v[2:3], v[2:3], v[24:25]
	v_and_b32_e32 v21, 0xffff0000, v223
	v_pk_mul_f32 v[2:3], v[2:3], v[2:3] op_sel:[0,1] op_sel_hi:[1,0]
	v_mul_f32_e32 v22, v4, v34
	v_add_f32_e32 v3, 1.0, v11
	v_rcp_f32_e32 v15, v3
	v_mul_f32_e32 v3, 0xbfb8aa3b, v21
	v_exp_f32_e32 v3, v3
	v_mov_b32_e32 v14, v242
	v_pk_mul_f32 v[14:15], v[14:15], v[22:23]
	v_mov_b32_e32 v22, v243
	v_add_f32_e32 v3, 1.0, v3
	v_rcp_f32_e32 v23, v3
	v_bfe_u32 v3, v10, 16, 1
	v_add3_u32 v3, v10, v3, s30
	v_pk_mul_f32 v[14:15], v[14:15], v[14:15] op_sel:[0,1] op_sel_hi:[1,0]
	v_pk_mul_f32 v[4:5], v[22:23], v[20:21]
	v_lshrrev_b32_e32 v3, 16, v3
	v_pk_mul_f32 v[4:5], v[4:5], v[4:5] op_sel:[0,1] op_sel_hi:[1,0]
	s_waitcnt vmcnt(14)
	v_lshlrev_b32_e32 v11, 16, v224
	v_bfe_u32 v5, v2, 16, 1
	v_add3_u32 v2, v2, v5, s30
	v_and_or_b32 v2, v2, s31, v3
	v_bfe_u32 v3, v14, 16, 1
	v_add3_u32 v3, v14, v3, s30
	v_bfe_u32 v5, v4, 16, 1
	v_lshrrev_b32_e32 v3, 16, v3
	v_add3_u32 v4, v4, v5, s30
	v_and_or_b32 v3, v4, s31, v3
	global_store_dwordx2 v[12:13], v[2:3], off offset:64
	v_mul_f32_e32 v10, 0xbfb8aa3b, v11
	v_exp_f32_e32 v10, v10
	v_and_b32_e32 v17, 0xffff0000, v224
	v_mul_f32_e32 v14, v6, v34
	v_add_f32_e32 v6, 1.0, v10
	v_rcp_f32_e32 v15, v6
	v_mul_f32_e32 v6, v7, v34
	v_mov_b32_e32 v10, v244
	v_mul_f32_e32 v2, 0xbfb8aa3b, v17
	v_exp_f32_e32 v2, v2
	v_pk_mul_f32 v[10:11], v[14:15], v[10:11]
	v_lshlrev_b32_e32 v15, 16, v225
	v_pk_mul_f32 v[10:11], v[10:11], v[10:11] op_sel:[0,1] op_sel_hi:[1,0]
	v_add_f32_e32 v2, 1.0, v2
	v_rcp_f32_e32 v7, v2
	v_mul_f32_e32 v2, 0xbfb8aa3b, v15
	v_exp_f32_e32 v11, v2
	v_mov_b32_e32 v16, v245
	v_pk_mul_f32 v[2:3], v[6:7], v[16:17]
	v_and_b32_e32 v17, 0xffff0000, v225
	v_pk_mul_f32 v[2:3], v[2:3], v[2:3] op_sel:[0,1] op_sel_hi:[1,0]
	v_mul_f32_e32 v6, v8, v34
	v_add_f32_e32 v3, 1.0, v11
	v_rcp_f32_e32 v7, v3
	v_mul_f32_e32 v3, 0xbfb8aa3b, v17
	v_exp_f32_e32 v3, v3
	v_mov_b32_e32 v14, v246
	v_pk_mul_f32 v[6:7], v[6:7], v[14:15]
	v_mul_f32_e32 v14, v9, v34
	v_add_f32_e32 v3, 1.0, v3
	v_rcp_f32_e32 v15, v3
	v_mov_b32_e32 v16, v247
	v_bfe_u32 v3, v10, 16, 1
	v_add3_u32 v3, v10, v3, s30
	v_pk_mul_f32 v[4:5], v[14:15], v[16:17]
	v_pk_mul_f32 v[6:7], v[6:7], v[6:7] op_sel:[0,1] op_sel_hi:[1,0]
	v_pk_mul_f32 v[4:5], v[4:5], v[4:5] op_sel:[0,1] op_sel_hi:[1,0]
	v_lshrrev_b32_e32 v3, 16, v3
	v_bfe_u32 v5, v2, 16, 1
	v_add3_u32 v2, v2, v5, s30
	v_and_or_b32 v2, v2, s31, v3
	v_bfe_u32 v3, v6, 16, 1
	v_add3_u32 v3, v6, v3, s30
	v_bfe_u32 v5, v4, 16, 1
	v_lshrrev_b32_e32 v3, 16, v3
	v_add3_u32 v4, v4, v5, s30
	v_and_or_b32 v3, v4, s31, v3
	global_store_dwordx2 v[12:13], v[2:3], off offset:96
	s_waitcnt lgkmcnt(0)
